# adds: loop-head ds_reads hoisted above SALU preamble; LDS-DMA loads use SGPR-base addressing where address not reused
# speedup vs baseline: 1.0059x; 1.0044x over previous
; #define PG8_STAGE(bufoff, gbase, voff) do { _Pragma("unroll") for (int _i = 0; _i < 2; ++_i) \
;         __builtin_amdgcn_global_load_lds((const unsigned*)((const char*)(gbase) + (voff)[_i]), (LAS unsigned*)(lds + (bufoff) + ldsw + _i * 8192), 16, 0, 0); } while (0)
; #define PG8_LDA(dst, b, h) do { _Pragma("unroll") for (int m = 0; m < 4; ++m) _Pragma("unroll") for (int k = 0; k < 2; ++k) dst[m][k] = *(const LAS bf16x8*)(lds + PG8_SA(b, h) + aoff + m * 2048 + k * 1024); } while (0)
; #define PG8_LDB(dst, b, h) do { _Pragma("unroll") for (int n = 0; n < 2; ++n) _Pragma("unroll") for (int k = 0; k < 2; ++k) dst[n][k] = *(const LAS bf16x8*)(lds + PG8_SB(b, h) + boff + n * 2048 + k * 1024); } while (0)
; #define PG8_MMA(ai, bj, At, Bt) do { __builtin_amdgcn_s_setprio(1); _Pragma("unroll") for (int m = 0; m < 4; ++m) _Pragma("unroll") for (int n = 0; n < 2; ++n) _Pragma("unroll") for (int k = 0; k < 2; ++k) \
;         acc[ai][bj][m][n] = __builtin_amdgcn_mfma_f32_16x16x32_bf16(Bt[n][k], At[m][k], acc[ai][bj][m][n], 0, 0, 0); __builtin_amdgcn_s_setprio(0); } while (0)
; #define PG8_WAIT_V(n) asm volatile("s_waitcnt vmcnt(" #n ")" ::: "memory")
; #define PG8_WAIT_L(n) asm volatile("s_waitcnt lgkmcnt(" #n ")" ::: "memory")
; #define PG8_BAR __builtin_amdgcn_s_barrier()
; #define PG8_SCHED __builtin_amdgcn_sched_barrier(0)
; template <class Epi>
; __device__ __forceinline__ void gemm_phase(LAS unsigned char* lds, const Gemm g, const TileOrder& S, const Epi& E) {
;     ...
;             const bool last = (t == nt - 2);
;             const char* a1 = cA + (size_t)(t + 1) * kstepA;
;             const char* a2 = last ? nA : cA + (size_t)(t + 2) * kstepA; const char* b2 = last ? nB : cB + (size_t)(t + 2) * kstep;
;             const char* a3 = a2 + kstepA; const char* b3 = b2 + kstep;
;             PG8_LDB(B0, 0, 0); PG8_LDB(B1, 0, 1); PG8_SCHED; PG8_LDA(At, 0, 0); PG8_STAGE(PG8_SA(1, 1), a1 + hstepA, voffA);
;             PG8_WAIT_V(8); PG8_WAIT_L(0); PG8_BAR; PG8_MMA(0, 0, At, B0); PG8_MMA(0, 1, At, B1); PG8_BAR; PG8_SCHED;
;             PG8_LDA(At, 0, 1); PG8_STAGE(PG8_SB(0, 0), b2, voffB); PG8_STAGE(PG8_SB(0, 1), b2 + hstepB, voffB); PG8_STAGE(PG8_SA(0, 0), a2, voffA);
;             PG8_WAIT_V(8); PG8_WAIT_L(0); PG8_BAR; PG8_MMA(1, 0, At, B0); PG8_MMA(1, 1, At, B1); PG8_BAR; PG8_SCHED;
.LBB0_51:
	s_mov_b32 s6, 0x10000
	v_add_u32_e32 v0, s6, v186
	s_mov_b32 s12, 0x14000
	ds_read_b128 v[130:133], v0
	ds_read_b128 v[134:137], v0 offset:1024
	ds_read_b128 v[138:141], v0 offset:2048
	ds_read_b128 v[142:145], v0 offset:3072
	v_add_u32_e32 v0, s12, v186
	ds_read_b128 v[154:157], v0
	ds_read_b128 v[158:161], v0 offset:1024
	ds_read_b128 v[162:165], v0 offset:2048
	ds_read_b128 v[166:169], v0 offset:3072
	ds_read_b128 v[170:173], v187
	ds_read_b128 v[174:177], v187 offset:1024
	ds_read_b128 v[178:181], v187 offset:2048
	ds_read_b128 v[188:191], v187 offset:3072
	ds_read_b128 v[192:195], v187 offset:4096
	ds_read_b128 v[196:199], v187 offset:5120
	ds_read_b128 v[200:203], v187 offset:6144
	ds_read_b128 v[204:207], v187 offset:7168
	s_add_u32 s2, s28, 0xfff80080
	s_addc_u32 s3, s29, -1
	s_cmp_eq_u32 s72, 28
	s_cselect_b32 s31, s49, s3
	s_cselect_b32 s30, s68, s2
	s_cselect_b32 s3, s47, s71
	s_cselect_b32 s2, s69, s70
	s_waitcnt lgkmcnt(0)
	s_add_i32 m0, s56, 0xc000
	s_nop 0
	global_load_lds_dwordx4 v150, s[28:29]
	s_add_i32 m0, s56, 0xe000
	s_nop 0
	global_load_lds_dwordx4 v152, s[28:29]
	s_waitcnt vmcnt(8)
	s_waitcnt lgkmcnt(0)
	s_barrier
	s_setprio 1
	s_waitcnt lgkmcnt(0)
	v_mfma_f32_16x16x32_bf16 v[126:129], v[130:133], v[170:173], v[126:129]
	v_mfma_f32_16x16x32_bf16 v[118:121], v[138:141], v[170:173], v[118:121]
	v_mfma_f32_16x16x32_bf16 v[110:113], v[130:133], v[178:181], v[110:113]
	v_mfma_f32_16x16x32_bf16 v[102:105], v[138:141], v[178:181], v[102:105]
	v_mfma_f32_16x16x32_bf16 v[94:97], v[130:133], v[192:195], v[94:97]
	v_mfma_f32_16x16x32_bf16 v[86:89], v[138:141], v[192:195], v[86:89]
	v_mfma_f32_16x16x32_bf16 v[78:81], v[130:133], v[200:203], v[78:81]
	v_mfma_f32_16x16x32_bf16 v[70:73], v[138:141], v[200:203], v[70:73]
	v_mfma_f32_16x16x32_bf16 v[126:129], v[134:137], v[174:177], v[126:129]
	v_mfma_f32_16x16x32_bf16 v[118:121], v[142:145], v[174:177], v[118:121]
	v_mfma_f32_16x16x32_bf16 v[110:113], v[134:137], v[188:191], v[110:113]
	v_mfma_f32_16x16x32_bf16 v[102:105], v[142:145], v[188:191], v[102:105]
	v_mfma_f32_16x16x32_bf16 v[94:97], v[134:137], v[196:199], v[94:97]
	v_mfma_f32_16x16x32_bf16 v[86:89], v[142:145], v[196:199], v[86:89]
	v_mfma_f32_16x16x32_bf16 v[78:81], v[134:137], v[204:207], v[78:81]
	v_mfma_f32_16x16x32_bf16 v[70:73], v[142:145], v[204:207], v[70:73]
	s_setprio 0
	s_setprio 1
	v_mfma_f32_16x16x32_bf16 v[122:125], v[154:157], v[170:173], v[122:125]
	v_mfma_f32_16x16x32_bf16 v[114:117], v[162:165], v[170:173], v[114:117]
	v_mfma_f32_16x16x32_bf16 v[106:109], v[154:157], v[178:181], v[106:109]
	v_mfma_f32_16x16x32_bf16 v[98:101], v[162:165], v[178:181], v[98:101]
	v_mfma_f32_16x16x32_bf16 v[90:93], v[154:157], v[192:195], v[90:93]
	v_mfma_f32_16x16x32_bf16 v[82:85], v[162:165], v[192:195], v[82:85]
	v_mfma_f32_16x16x32_bf16 v[74:77], v[154:157], v[200:203], v[74:77]
	v_mfma_f32_16x16x32_bf16 v[66:69], v[162:165], v[200:203], v[66:69]
	v_mfma_f32_16x16x32_bf16 v[122:125], v[158:161], v[174:177], v[122:125]
	v_mfma_f32_16x16x32_bf16 v[114:117], v[166:169], v[174:177], v[114:117]
	v_mfma_f32_16x16x32_bf16 v[106:109], v[158:161], v[188:191], v[106:109]
	v_mfma_f32_16x16x32_bf16 v[98:101], v[166:169], v[188:191], v[98:101]
	v_mfma_f32_16x16x32_bf16 v[90:93], v[158:161], v[196:199], v[90:93]
	v_mfma_f32_16x16x32_bf16 v[82:85], v[166:169], v[196:199], v[82:85]
	s_setprio 2
	s_barrier
	v_mfma_f32_16x16x32_bf16 v[74:77], v[158:161], v[204:207], v[74:77]
	v_mfma_f32_16x16x32_bf16 v[66:69], v[166:169], v[204:207], v[66:69]
	s_setprio 0
	s_add_i32 s6, s6, s55
	v_lshl_add_u64 v[182:183], s[2:3], 0, v[148:149]
	s_mov_b32 m0, s6
	ds_read_b128 v[170:173], v187 offset:16384
	ds_read_b128 v[174:177], v187 offset:17408
	ds_read_b128 v[178:181], v187 offset:18432
	ds_read_b128 v[188:191], v187 offset:19456
	ds_read_b128 v[192:195], v187 offset:20480
	ds_read_b128 v[196:199], v187 offset:21504
	ds_read_b128 v[200:203], v187 offset:22528
	ds_read_b128 v[204:207], v187 offset:23552
	global_load_lds_dwordx4 v[182:183], off
	s_add_i32 m0, s6, 0x2000
	s_add_u32 s14, s2, 0x80000
	v_lshl_add_u64 v[208:209], s[2:3], 0, v[146:147]
	s_addc_u32 s15, s3, 0
	s_add_i32 s6, s12, s55
	global_load_lds_dwordx4 v[208:209], off
	s_mov_b32 m0, s6
	v_lshl_add_u64 v[212:213], s[30:31], 0, v[146:147]
	global_load_lds_dwordx4 v148, s[14:15]
	s_add_i32 m0, s6, 0x2000
	s_nop 0
	global_load_lds_dwordx4 v146, s[14:15]
	v_lshl_add_u64 v[210:211], s[30:31], 0, v[148:149]
	s_mov_b32 m0, s56
	s_nop 0
	global_load_lds_dwordx4 v[210:211], off
	s_mov_b32 m0, s57
	s_nop 0
	global_load_lds_dwordx4 v[212:213], off
	s_waitcnt vmcnt(8)
	s_waitcnt lgkmcnt(0)
	s_barrier
; #define PG8_STAGE(bufoff, gbase, voff) do { _Pragma("unroll") for (int _i = 0; _i < 2; ++_i) \
;         __builtin_amdgcn_global_load_lds((const unsigned*)((const char*)(gbase) + (voff)[_i]), (LAS unsigned*)(lds + (bufoff) + ldsw + _i * 8192), 16, 0, 0); } while (0)
; #define PG8_LDA(dst, b, h) do { _Pragma("unroll") for (int m = 0; m < 4; ++m) _Pragma("unroll") for (int k = 0; k < 2; ++k) dst[m][k] = *(const LAS bf16x8*)(lds + PG8_SA(b, h) + aoff + m * 2048 + k * 1024); } while (0)
; #define PG8_LDB(dst, b, h) do { _Pragma("unroll") for (int n = 0; n < 2; ++n) _Pragma("unroll") for (int k = 0; k < 2; ++k) dst[n][k] = *(const LAS bf16x8*)(lds + PG8_SB(b, h) + boff + n * 2048 + k * 1024); } while (0)
; #define PG8_MMA(ai, bj, At, Bt) do { __builtin_amdgcn_s_setprio(1); _Pragma("unroll") for (int m = 0; m < 4; ++m) _Pragma("unroll") for (int n = 0; n < 2; ++n) _Pragma("unroll") for (int k = 0; k < 2; ++k) \
;         acc[ai][bj][m][n] = __builtin_amdgcn_mfma_f32_16x16x32_bf16(Bt[n][k], At[m][k], acc[ai][bj][m][n], 0, 0, 0); __builtin_amdgcn_s_setprio(0); } while (0)
; #define PG8_WAIT_V(n) asm volatile("s_waitcnt vmcnt(" #n ")" ::: "memory")
; #define PG8_WAIT_L(n) asm volatile("s_waitcnt lgkmcnt(" #n ")" ::: "memory")
; #define PG8_BAR __builtin_amdgcn_s_barrier()
; #define PG8_SCHED __builtin_amdgcn_sched_barrier(0)
; template <class Epi>
; __device__ __forceinline__ void gemm_phase(LAS unsigned char* lds, const Gemm g, const TileOrder& S, const Epi& E) {
;     ...
;             PG8_WAIT_V(8); PG8_WAIT_L(0); PG8_BAR; PG8_MMA(1, 0, At, B0); PG8_MMA(1, 1, At, B1); PG8_BAR; PG8_SCHED;
;             PG8_LDB(B0, 1, 0); PG8_LDB(B1, 1, 1); PG8_SCHED; PG8_LDA(At, 1, 0); PG8_STAGE(PG8_SA(0, 1), a2 + hstepA, voffA);
;             PG8_WAIT_V(8); PG8_WAIT_L(0); PG8_BAR; PG8_MMA(0, 0, At, B0); PG8_MMA(0, 1, At, B1); PG8_BAR; PG8_SCHED;
	s_setprio 1
	s_waitcnt lgkmcnt(0)
	v_mfma_f32_16x16x32_bf16 v[62:65], v[130:133], v[170:173], v[62:65]
	v_mfma_f32_16x16x32_bf16 v[54:57], v[138:141], v[170:173], v[54:57]
	v_mfma_f32_16x16x32_bf16 v[46:49], v[130:133], v[178:181], v[46:49]
	v_mfma_f32_16x16x32_bf16 v[38:41], v[138:141], v[178:181], v[38:41]
	v_mfma_f32_16x16x32_bf16 v[30:33], v[130:133], v[192:195], v[30:33]
	v_mfma_f32_16x16x32_bf16 v[22:25], v[138:141], v[192:195], v[22:25]
	v_mfma_f32_16x16x32_bf16 v[14:17], v[130:133], v[200:203], v[14:17]
	v_mfma_f32_16x16x32_bf16 v[6:9], v[138:141], v[200:203], v[6:9]
	v_mfma_f32_16x16x32_bf16 v[62:65], v[134:137], v[174:177], v[62:65]
	v_mfma_f32_16x16x32_bf16 v[54:57], v[142:145], v[174:177], v[54:57]
	v_mfma_f32_16x16x32_bf16 v[46:49], v[134:137], v[188:191], v[46:49]
	v_mfma_f32_16x16x32_bf16 v[38:41], v[142:145], v[188:191], v[38:41]
	v_mfma_f32_16x16x32_bf16 v[30:33], v[134:137], v[196:199], v[30:33]
	v_mfma_f32_16x16x32_bf16 v[22:25], v[142:145], v[196:199], v[22:25]
	v_mfma_f32_16x16x32_bf16 v[14:17], v[134:137], v[204:207], v[14:17]
	v_mfma_f32_16x16x32_bf16 v[6:9], v[142:145], v[204:207], v[6:9]
	s_setprio 0
	s_setprio 1
	v_mfma_f32_16x16x32_bf16 v[58:61], v[154:157], v[170:173], v[58:61]
	v_mfma_f32_16x16x32_bf16 v[50:53], v[162:165], v[170:173], v[50:53]
	v_mfma_f32_16x16x32_bf16 v[42:45], v[154:157], v[178:181], v[42:45]
	v_mfma_f32_16x16x32_bf16 v[34:37], v[162:165], v[178:181], v[34:37]
	v_mfma_f32_16x16x32_bf16 v[26:29], v[154:157], v[192:195], v[26:29]
	v_mfma_f32_16x16x32_bf16 v[18:21], v[162:165], v[192:195], v[18:21]
	v_mfma_f32_16x16x32_bf16 v[10:13], v[154:157], v[200:203], v[10:13]
	v_mfma_f32_16x16x32_bf16 v[2:5], v[162:165], v[200:203], v[2:5]
	v_mfma_f32_16x16x32_bf16 v[58:61], v[158:161], v[174:177], v[58:61]
	v_mfma_f32_16x16x32_bf16 v[50:53], v[166:169], v[174:177], v[50:53]
	v_mfma_f32_16x16x32_bf16 v[42:45], v[158:161], v[188:191], v[42:45]
	v_mfma_f32_16x16x32_bf16 v[34:37], v[166:169], v[188:191], v[34:37]
	v_mfma_f32_16x16x32_bf16 v[26:29], v[158:161], v[196:199], v[26:29]
	v_mfma_f32_16x16x32_bf16 v[18:21], v[166:169], v[196:199], v[18:21]
	s_setprio 2
	s_barrier
	v_mfma_f32_16x16x32_bf16 v[10:13], v[158:161], v[204:207], v[10:13]
	v_mfma_f32_16x16x32_bf16 v[2:5], v[166:169], v[204:207], v[2:5]
	s_setprio 0
	s_add_i32 s6, 0, 0x18000
	v_add_u32_e32 v0, s6, v186
	s_add_i32 s12, 0, 0x1c000
	ds_read_b128 v[130:133], v0
	ds_read_b128 v[134:137], v0 offset:1024
	ds_read_b128 v[138:141], v0 offset:2048
	ds_read_b128 v[142:145], v0 offset:3072
	v_add_u32_e32 v0, s12, v186
	ds_read_b128 v[154:157], v0
	ds_read_b128 v[158:161], v0 offset:1024
	ds_read_b128 v[162:165], v0 offset:2048
	ds_read_b128 v[166:169], v0 offset:3072
	s_add_u32 s14, s30, 0x80000
	s_addc_u32 s15, s31, 0
	s_mov_b32 m0, s58
	ds_read_b128 v[170:173], v187 offset:32768
	ds_read_b128 v[174:177], v187 offset:33792
	ds_read_b128 v[178:181], v187 offset:34816
	ds_read_b128 v[188:191], v187 offset:35840
	ds_read_b128 v[192:195], v187 offset:36864
	ds_read_b128 v[196:199], v187 offset:37888
	ds_read_b128 v[200:203], v187 offset:38912
	ds_read_b128 v[204:207], v187 offset:39936
	global_load_lds_dwordx4 v148, s[14:15]
	s_mov_b32 m0, s59
	s_nop 0
	global_load_lds_dwordx4 v146, s[14:15]
	s_waitcnt vmcnt(8)
	s_waitcnt lgkmcnt(0)
	s_barrier
	s_setprio 1
	s_waitcnt lgkmcnt(0)
	v_mfma_f32_16x16x32_bf16 v[126:129], v[130:133], v[170:173], v[126:129]
	v_mfma_f32_16x16x32_bf16 v[118:121], v[138:141], v[170:173], v[118:121]
	v_mfma_f32_16x16x32_bf16 v[110:113], v[130:133], v[178:181], v[110:113]
	v_mfma_f32_16x16x32_bf16 v[102:105], v[138:141], v[178:181], v[102:105]
	v_mfma_f32_16x16x32_bf16 v[94:97], v[130:133], v[192:195], v[94:97]
	v_mfma_f32_16x16x32_bf16 v[86:89], v[138:141], v[192:195], v[86:89]
	v_mfma_f32_16x16x32_bf16 v[78:81], v[130:133], v[200:203], v[78:81]
	v_mfma_f32_16x16x32_bf16 v[70:73], v[138:141], v[200:203], v[70:73]
	v_mfma_f32_16x16x32_bf16 v[126:129], v[134:137], v[174:177], v[126:129]
	v_mfma_f32_16x16x32_bf16 v[118:121], v[142:145], v[174:177], v[118:121]
	v_mfma_f32_16x16x32_bf16 v[110:113], v[134:137], v[188:191], v[110:113]
	v_mfma_f32_16x16x32_bf16 v[102:105], v[142:145], v[188:191], v[102:105]
	v_mfma_f32_16x16x32_bf16 v[94:97], v[134:137], v[196:199], v[94:97]
	v_mfma_f32_16x16x32_bf16 v[86:89], v[142:145], v[196:199], v[86:89]
	v_mfma_f32_16x16x32_bf16 v[78:81], v[134:137], v[204:207], v[78:81]
	v_mfma_f32_16x16x32_bf16 v[70:73], v[142:145], v[204:207], v[70:73]
	s_setprio 0
	s_setprio 1
	v_mfma_f32_16x16x32_bf16 v[122:125], v[154:157], v[170:173], v[122:125]
	v_mfma_f32_16x16x32_bf16 v[114:117], v[162:165], v[170:173], v[114:117]
	v_mfma_f32_16x16x32_bf16 v[106:109], v[154:157], v[178:181], v[106:109]
	v_mfma_f32_16x16x32_bf16 v[98:101], v[162:165], v[178:181], v[98:101]
	v_mfma_f32_16x16x32_bf16 v[90:93], v[154:157], v[192:195], v[90:93]
	v_mfma_f32_16x16x32_bf16 v[82:85], v[162:165], v[192:195], v[82:85]
	v_mfma_f32_16x16x32_bf16 v[74:77], v[154:157], v[200:203], v[74:77]
	v_mfma_f32_16x16x32_bf16 v[66:69], v[162:165], v[200:203], v[66:69]
	v_mfma_f32_16x16x32_bf16 v[122:125], v[158:161], v[174:177], v[122:125]
	v_mfma_f32_16x16x32_bf16 v[114:117], v[166:169], v[174:177], v[114:117]
	v_mfma_f32_16x16x32_bf16 v[106:109], v[158:161], v[188:191], v[106:109]
	v_mfma_f32_16x16x32_bf16 v[98:101], v[166:169], v[188:191], v[98:101]
	v_mfma_f32_16x16x32_bf16 v[90:93], v[158:161], v[196:199], v[90:93]
	v_mfma_f32_16x16x32_bf16 v[82:85], v[166:169], v[196:199], v[82:85]
	s_setprio 2
	s_barrier
; #define PG8_STAGE(bufoff, gbase, voff) do { _Pragma("unroll") for (int _i = 0; _i < 2; ++_i) \
;         __builtin_amdgcn_global_load_lds((const unsigned*)((const char*)(gbase) + (voff)[_i]), (LAS unsigned*)(lds + (bufoff) + ldsw + _i * 8192), 16, 0, 0); } while (0)
; #define PG8_LDA(dst, b, h) do { _Pragma("unroll") for (int m = 0; m < 4; ++m) _Pragma("unroll") for (int k = 0; k < 2; ++k) dst[m][k] = *(const LAS bf16x8*)(lds + PG8_SA(b, h) + aoff + m * 2048 + k * 1024); } while (0)
; #define PG8_MMA(ai, bj, At, Bt) do { __builtin_amdgcn_s_setprio(1); _Pragma("unroll") for (int m = 0; m < 4; ++m) _Pragma("unroll") for (int n = 0; n < 2; ++n) _Pragma("unroll") for (int k = 0; k < 2; ++k) \
;         acc[ai][bj][m][n] = __builtin_amdgcn_mfma_f32_16x16x32_bf16(Bt[n][k], At[m][k], acc[ai][bj][m][n], 0, 0, 0); __builtin_amdgcn_s_setprio(0); } while (0)
; #define PG8_WAIT_V(n) asm volatile("s_waitcnt vmcnt(" #n ")" ::: "memory")
; #define PG8_WAIT_L(n) asm volatile("s_waitcnt lgkmcnt(" #n ")" ::: "memory")
; #define PG8_BAR __builtin_amdgcn_s_barrier()
; #define PG8_SCHED __builtin_amdgcn_sched_barrier(0)
; template <class Epi>
; __device__ __forceinline__ void gemm_phase(LAS unsigned char* lds, const Gemm g, const TileOrder& S, const Epi& E) {
;     ...
;             PG8_WAIT_V(8); PG8_WAIT_L(0); PG8_BAR; PG8_MMA(0, 0, At, B0); PG8_MMA(0, 1, At, B1); PG8_BAR; PG8_SCHED;
;             PG8_LDA(At, 1, 1); PG8_STAGE(PG8_SB(1, 0), b3, voffB); PG8_STAGE(PG8_SB(1, 1), b3 + hstepB, voffB); PG8_STAGE(PG8_SA(1, 0), a3, voffA);
;             PG8_WAIT_V(8); PG8_WAIT_L(0); PG8_BAR; PG8_MMA(1, 0, At, B0); PG8_MMA(1, 1, At, B1); PG8_BAR; PG8_SCHED;
;         }
;         if (wr == 0) PG8_BAR;
	v_mfma_f32_16x16x32_bf16 v[74:77], v[158:161], v[204:207], v[74:77]
	v_mfma_f32_16x16x32_bf16 v[66:69], v[166:169], v[204:207], v[66:69]
	s_setprio 0
	s_add_i32 s6, s6, s55
	v_lshl_add_u64 v[182:183], v[182:183], 0, s[34:35]
	s_mov_b32 m0, s6
	ds_read_b128 v[170:173], v187 offset:49152
	ds_read_b128 v[174:177], v187 offset:50176
	ds_read_b128 v[178:181], v187 offset:51200
	ds_read_b128 v[188:191], v187 offset:52224
	ds_read_b128 v[192:195], v187 offset:53248
	ds_read_b128 v[196:199], v187 offset:54272
	ds_read_b128 v[200:203], v187 offset:55296
	ds_read_b128 v[204:207], v187 offset:56320
	global_load_lds_dwordx4 v[182:183], off
	s_add_i32 m0, s6, 0x2000
	s_add_u32 s2, s2, 0x80080
	v_lshl_add_u64 v[182:183], v[208:209], 0, s[34:35]
	s_addc_u32 s3, s3, 0
	s_add_i32 s6, s12, s55
	global_load_lds_dwordx4 v[182:183], off
	s_mov_b32 m0, s6
	s_nop 0
	global_load_lds_dwordx4 v148, s[2:3]
	v_lshl_add_u64 v[182:183], s[2:3], 0, v[146:147]
	s_add_i32 m0, s6, 0x2000
	s_nop 0
	global_load_lds_dwordx4 v[182:183], off
	v_lshl_add_u64 v[182:183], v[210:211], 0, s[34:35]
	s_mov_b32 m0, s61
	s_nop 0
	global_load_lds_dwordx4 v[182:183], off
	v_lshl_add_u64 v[182:183], v[212:213], 0, s[34:35]
	s_mov_b32 m0, s62
	s_nop 0
	global_load_lds_dwordx4 v[182:183], off
	s_waitcnt vmcnt(8)
	s_waitcnt lgkmcnt(0)
	s_barrier
	s_setprio 1
	s_waitcnt lgkmcnt(0)
	v_mfma_f32_16x16x32_bf16 v[62:65], v[130:133], v[170:173], v[62:65]
	v_mfma_f32_16x16x32_bf16 v[54:57], v[138:141], v[170:173], v[54:57]
	v_mfma_f32_16x16x32_bf16 v[46:49], v[130:133], v[178:181], v[46:49]
	v_mfma_f32_16x16x32_bf16 v[38:41], v[138:141], v[178:181], v[38:41]
	v_mfma_f32_16x16x32_bf16 v[30:33], v[130:133], v[192:195], v[30:33]
	v_mfma_f32_16x16x32_bf16 v[22:25], v[138:141], v[192:195], v[22:25]
	v_mfma_f32_16x16x32_bf16 v[14:17], v[130:133], v[200:203], v[14:17]
	v_mfma_f32_16x16x32_bf16 v[6:9], v[138:141], v[200:203], v[6:9]
	v_mfma_f32_16x16x32_bf16 v[62:65], v[134:137], v[174:177], v[62:65]
	v_mfma_f32_16x16x32_bf16 v[54:57], v[142:145], v[174:177], v[54:57]
	v_mfma_f32_16x16x32_bf16 v[46:49], v[134:137], v[188:191], v[46:49]
	v_mfma_f32_16x16x32_bf16 v[38:41], v[142:145], v[188:191], v[38:41]
	v_mfma_f32_16x16x32_bf16 v[30:33], v[134:137], v[196:199], v[30:33]
	v_mfma_f32_16x16x32_bf16 v[22:25], v[142:145], v[196:199], v[22:25]
	v_mfma_f32_16x16x32_bf16 v[14:17], v[134:137], v[204:207], v[14:17]
	v_mfma_f32_16x16x32_bf16 v[6:9], v[142:145], v[204:207], v[6:9]
	s_setprio 0
	s_setprio 1
	v_mfma_f32_16x16x32_bf16 v[58:61], v[154:157], v[170:173], v[58:61]
	v_mfma_f32_16x16x32_bf16 v[50:53], v[162:165], v[170:173], v[50:53]
	v_mfma_f32_16x16x32_bf16 v[42:45], v[154:157], v[178:181], v[42:45]
	v_mfma_f32_16x16x32_bf16 v[34:37], v[162:165], v[178:181], v[34:37]
	v_mfma_f32_16x16x32_bf16 v[26:29], v[154:157], v[192:195], v[26:29]
	v_mfma_f32_16x16x32_bf16 v[18:21], v[162:165], v[192:195], v[18:21]
	v_mfma_f32_16x16x32_bf16 v[10:13], v[154:157], v[200:203], v[10:13]
	v_mfma_f32_16x16x32_bf16 v[2:5], v[162:165], v[200:203], v[2:5]
	v_mfma_f32_16x16x32_bf16 v[58:61], v[158:161], v[174:177], v[58:61]
	v_mfma_f32_16x16x32_bf16 v[50:53], v[166:169], v[174:177], v[50:53]
	v_mfma_f32_16x16x32_bf16 v[42:45], v[158:161], v[188:191], v[42:45]
	v_mfma_f32_16x16x32_bf16 v[34:37], v[166:169], v[188:191], v[34:37]
	v_mfma_f32_16x16x32_bf16 v[26:29], v[158:161], v[196:199], v[26:29]
	v_mfma_f32_16x16x32_bf16 v[18:21], v[166:169], v[196:199], v[18:21]
	s_setprio 2
	s_barrier
	v_mfma_f32_16x16x32_bf16 v[10:13], v[158:161], v[204:207], v[10:13]
	v_mfma_f32_16x16x32_bf16 v[2:5], v[166:169], v[204:207], v[2:5]
	s_setprio 0
	s_add_i32 s72, s72, 2
	s_add_u32 s28, s28, 0x100
	s_addc_u32 s29, s29, 0
	s_add_u32 s70, s70, 0x100
	s_addc_u32 s71, s71, 0
	s_cmp_gt_u32 s72, 29
	s_cbranch_scc0 .LBB0_51
	s_and_b64 vcc, exec, s[44:45]
	s_cbranch_vccz .LBB0_54
	s_barrier

; #define PG8_STAGE(bufoff, gbase, voff) do { _Pragma("unroll") for (int _i = 0; _i < 2; ++_i) \
;         __builtin_amdgcn_global_load_lds((const unsigned*)((const char*)(gbase) + (voff)[_i]), (LAS unsigned*)(lds + (bufoff) + ldsw + _i * 8192), 16, 0, 0); } while (0)
; #define PG8_LDA(dst, b, h) do { _Pragma("unroll") for (int m = 0; m < 4; ++m) _Pragma("unroll") for (int k = 0; k < 2; ++k) dst[m][k] = *(const LAS bf16x8*)(lds + PG8_SA(b, h) + aoff + m * 2048 + k * 1024); } while (0)
; #define PG8_LDB(dst, b, h) do { _Pragma("unroll") for (int n = 0; n < 2; ++n) _Pragma("unroll") for (int k = 0; k < 2; ++k) dst[n][k] = *(const LAS bf16x8*)(lds + PG8_SB(b, h) + boff + n * 2048 + k * 1024); } while (0)
; #define PG8_MMA(ai, bj, At, Bt) do { __builtin_amdgcn_s_setprio(1); _Pragma("unroll") for (int m = 0; m < 4; ++m) _Pragma("unroll") for (int n = 0; n < 2; ++n) _Pragma("unroll") for (int k = 0; k < 2; ++k) \
;         acc[ai][bj][m][n] = __builtin_amdgcn_mfma_f32_16x16x32_bf16(Bt[n][k], At[m][k], acc[ai][bj][m][n], 0, 0, 0); __builtin_amdgcn_s_setprio(0); } while (0)
; #define PG8_WAIT_V(n) asm volatile("s_waitcnt vmcnt(" #n ")" ::: "memory")
; #define PG8_WAIT_L(n) asm volatile("s_waitcnt lgkmcnt(" #n ")" ::: "memory")
; #define PG8_BAR __builtin_amdgcn_s_barrier()
; #define PG8_SCHED __builtin_amdgcn_sched_barrier(0)
; template <class Epi>
; __device__ __forceinline__ void gemm_phase(LAS unsigned char* lds, const Gemm g, const TileOrder& S, const Epi& E) {
;     ...
;             const bool last = (t == nt - 2);
;             const char* a1 = cA + (size_t)(t + 1) * kstepA;
;             const char* a2 = last ? nA : cA + (size_t)(t + 2) * kstepA; const char* b2 = last ? nB : cB + (size_t)(t + 2) * kstep;
;             const char* a3 = a2 + kstepA; const char* b3 = b2 + kstep;
;             PG8_LDB(B0, 0, 0); PG8_LDB(B1, 0, 1); PG8_SCHED; PG8_LDA(At, 0, 0); PG8_STAGE(PG8_SA(1, 1), a1 + hstepA, voffA);
;             PG8_WAIT_V(8); PG8_WAIT_L(0); PG8_BAR; PG8_MMA(0, 0, At, B0); PG8_MMA(0, 1, At, B1); PG8_BAR; PG8_SCHED;
;             PG8_LDA(At, 0, 1); PG8_STAGE(PG8_SB(0, 0), b2, voffB); PG8_STAGE(PG8_SB(0, 1), b2 + hstepB, voffB); PG8_STAGE(PG8_SA(0, 0), a2, voffA);
;             PG8_WAIT_V(8); PG8_WAIT_L(0); PG8_BAR; PG8_MMA(1, 0, At, B0); PG8_MMA(1, 1, At, B1); PG8_BAR; PG8_SCHED;
.LBB0_255:
	s_mov_b32 s6, 0x10000
	s_mov_b32 s14, 0x14000
	v_add_u32_e32 v134, s6, v238
	v_add_u32_e32 v158, s14, v238
	ds_read_b128 v[118:121], v134
	ds_read_b128 v[126:129], v134 offset:1024
	ds_read_b128 v[130:133], v134 offset:2048
	ds_read_b128 v[134:137], v134 offset:3072
	ds_read_b128 v[138:141], v158
	ds_read_b128 v[142:145], v158 offset:1024
	ds_read_b128 v[154:157], v158 offset:2048
	ds_read_b128 v[158:161], v158 offset:3072
	ds_read_b128 v[162:165], v239
	ds_read_b128 v[166:169], v239 offset:1024
	ds_read_b128 v[170:173], v239 offset:2048
	ds_read_b128 v[174:177], v239 offset:3072
	ds_read_b128 v[178:181], v239 offset:4096
	ds_read_b128 v[182:185], v239 offset:5120
	ds_read_b128 v[186:189], v239 offset:6144
	ds_read_b128 v[200:203], v239 offset:7168
	s_add_u32 s2, s28, 0x4000
	s_addc_u32 s3, s29, 0
	s_cmp_eq_u32 s68, 28
	s_cselect_b32 s48, s64, s2
	s_cselect_b32 s49, s43, s3
	s_cselect_b32 s30, s65, s66
	s_cselect_b32 s31, s39, s67
	s_add_u32 s2, s48, 0x8000
	s_addc_u32 s3, s49, 0
	s_add_i32 m0, s52, 0xc000
	s_nop 0
	global_load_lds_dwordx4 v196, s[28:29]
	s_add_i32 m0, s52, 0xe000
	s_nop 0
	global_load_lds_dwordx4 v198, s[28:29]
	s_waitcnt vmcnt(8)
	s_waitcnt lgkmcnt(0)
	s_barrier
	s_setprio 1
	s_waitcnt lgkmcnt(0)
	v_mfma_f32_16x16x32_bf16 v[150:153], v[118:121], v[162:165], v[150:153]
	v_mfma_f32_16x16x32_bf16 v[146:149], v[130:133], v[162:165], v[146:149]
	v_mfma_f32_16x16x32_bf16 v[110:113], v[118:121], v[170:173], v[110:113]
	v_mfma_f32_16x16x32_bf16 v[106:109], v[130:133], v[170:173], v[106:109]
	v_mfma_f32_16x16x32_bf16 v[94:97], v[118:121], v[178:181], v[94:97]
	v_mfma_f32_16x16x32_bf16 v[90:93], v[130:133], v[178:181], v[90:93]
	v_mfma_f32_16x16x32_bf16 v[78:81], v[118:121], v[186:189], v[78:81]
	v_mfma_f32_16x16x32_bf16 v[74:77], v[130:133], v[186:189], v[74:77]
	v_mfma_f32_16x16x32_bf16 v[150:153], v[126:129], v[166:169], v[150:153]
	v_mfma_f32_16x16x32_bf16 v[146:149], v[134:137], v[166:169], v[146:149]
	v_mfma_f32_16x16x32_bf16 v[110:113], v[126:129], v[174:177], v[110:113]
	v_mfma_f32_16x16x32_bf16 v[106:109], v[134:137], v[174:177], v[106:109]
	v_mfma_f32_16x16x32_bf16 v[94:97], v[126:129], v[182:185], v[94:97]
	v_mfma_f32_16x16x32_bf16 v[90:93], v[134:137], v[182:185], v[90:93]
	v_mfma_f32_16x16x32_bf16 v[78:81], v[126:129], v[200:203], v[78:81]
	v_mfma_f32_16x16x32_bf16 v[74:77], v[134:137], v[200:203], v[74:77]
	s_setprio 0
	s_setprio 1
	v_mfma_f32_16x16x32_bf16 v[122:125], v[138:141], v[162:165], v[122:125]
	v_mfma_f32_16x16x32_bf16 v[114:117], v[154:157], v[162:165], v[114:117]
	v_mfma_f32_16x16x32_bf16 v[102:105], v[138:141], v[170:173], v[102:105]
	v_mfma_f32_16x16x32_bf16 v[98:101], v[154:157], v[170:173], v[98:101]
	v_mfma_f32_16x16x32_bf16 v[86:89], v[138:141], v[178:181], v[86:89]
	v_mfma_f32_16x16x32_bf16 v[82:85], v[154:157], v[178:181], v[82:85]
	v_mfma_f32_16x16x32_bf16 v[70:73], v[138:141], v[186:189], v[70:73]
	v_mfma_f32_16x16x32_bf16 v[66:69], v[154:157], v[186:189], v[66:69]
	v_mfma_f32_16x16x32_bf16 v[122:125], v[142:145], v[166:169], v[122:125]
	v_mfma_f32_16x16x32_bf16 v[114:117], v[158:161], v[166:169], v[114:117]
	v_mfma_f32_16x16x32_bf16 v[102:105], v[142:145], v[174:177], v[102:105]
	v_mfma_f32_16x16x32_bf16 v[98:101], v[158:161], v[174:177], v[98:101]
	v_mfma_f32_16x16x32_bf16 v[86:89], v[142:145], v[182:185], v[86:89]
	v_mfma_f32_16x16x32_bf16 v[82:85], v[158:161], v[182:185], v[82:85]
	s_setprio 2
	s_barrier
	v_mfma_f32_16x16x32_bf16 v[70:73], v[142:145], v[200:203], v[70:73]
	v_mfma_f32_16x16x32_bf16 v[66:69], v[158:161], v[200:203], v[66:69]
	s_setprio 0
	s_add_i32 s6, s6, s51
	v_lshl_add_u64 v[204:205], s[30:31], 0, v[0:1]
	s_mov_b32 m0, s6
	ds_read_b128 v[162:165], v239 offset:16384
	ds_read_b128 v[166:169], v239 offset:17408
	ds_read_b128 v[170:173], v239 offset:18432
	ds_read_b128 v[174:177], v239 offset:19456
	ds_read_b128 v[178:181], v239 offset:20480
	ds_read_b128 v[182:185], v239 offset:21504
	ds_read_b128 v[186:189], v239 offset:22528
	ds_read_b128 v[200:203], v239 offset:23552
	global_load_lds_dwordx4 v[204:205], off
	s_add_i32 m0, s6, 0x2000
	s_add_u32 s12, s30, 0x80000
	v_lshl_add_u64 v[206:207], s[30:31], 0, v[190:191]
	s_addc_u32 s13, s31, 0
	s_add_i32 s6, s14, s51
	global_load_lds_dwordx4 v[206:207], off
	s_mov_b32 m0, s6
	s_nop 0
	global_load_lds_dwordx4 v0, s[12:13]
	s_add_i32 m0, s6, 0x2000
	s_nop 0
	global_load_lds_dwordx4 v190, s[12:13]
	s_mov_b32 m0, s52
	s_nop 0
	global_load_lds_dwordx4 v194, s[48:49]
	s_mov_b32 m0, s53
	s_nop 0
	global_load_lds_dwordx4 v192, s[48:49]
	s_waitcnt vmcnt(8)
	s_waitcnt lgkmcnt(0)
	s_barrier
; #define PG8_STAGE(bufoff, gbase, voff) do { _Pragma("unroll") for (int _i = 0; _i < 2; ++_i) \
;         __builtin_amdgcn_global_load_lds((const unsigned*)((const char*)(gbase) + (voff)[_i]), (LAS unsigned*)(lds + (bufoff) + ldsw + _i * 8192), 16, 0, 0); } while (0)
; #define PG8_LDA(dst, b, h) do { _Pragma("unroll") for (int m = 0; m < 4; ++m) _Pragma("unroll") for (int k = 0; k < 2; ++k) dst[m][k] = *(const LAS bf16x8*)(lds + PG8_SA(b, h) + aoff + m * 2048 + k * 1024); } while (0)
; #define PG8_LDB(dst, b, h) do { _Pragma("unroll") for (int n = 0; n < 2; ++n) _Pragma("unroll") for (int k = 0; k < 2; ++k) dst[n][k] = *(const LAS bf16x8*)(lds + PG8_SB(b, h) + boff + n * 2048 + k * 1024); } while (0)
; #define PG8_MMA(ai, bj, At, Bt) do { __builtin_amdgcn_s_setprio(1); _Pragma("unroll") for (int m = 0; m < 4; ++m) _Pragma("unroll") for (int n = 0; n < 2; ++n) _Pragma("unroll") for (int k = 0; k < 2; ++k) \
;         acc[ai][bj][m][n] = __builtin_amdgcn_mfma_f32_16x16x32_bf16(Bt[n][k], At[m][k], acc[ai][bj][m][n], 0, 0, 0); __builtin_amdgcn_s_setprio(0); } while (0)
; #define PG8_WAIT_V(n) asm volatile("s_waitcnt vmcnt(" #n ")" ::: "memory")
; #define PG8_WAIT_L(n) asm volatile("s_waitcnt lgkmcnt(" #n ")" ::: "memory")
; #define PG8_BAR __builtin_amdgcn_s_barrier()
; #define PG8_SCHED __builtin_amdgcn_sched_barrier(0)
; template <class Epi>
; __device__ __forceinline__ void gemm_phase(LAS unsigned char* lds, const Gemm g, const TileOrder& S, const Epi& E) {
;     ...
;             PG8_WAIT_V(8); PG8_WAIT_L(0); PG8_BAR; PG8_MMA(1, 0, At, B0); PG8_MMA(1, 1, At, B1); PG8_BAR; PG8_SCHED;
;             PG8_LDB(B0, 1, 0); PG8_LDB(B1, 1, 1); PG8_SCHED; PG8_LDA(At, 1, 0); PG8_STAGE(PG8_SA(0, 1), a2 + hstepA, voffA);
;             PG8_WAIT_V(8); PG8_WAIT_L(0); PG8_BAR; PG8_MMA(0, 0, At, B0); PG8_MMA(0, 1, At, B1); PG8_BAR; PG8_SCHED;
	s_setprio 1
	s_waitcnt lgkmcnt(0)
	v_mfma_f32_16x16x32_bf16 v[62:65], v[118:121], v[162:165], v[62:65]
	v_mfma_f32_16x16x32_bf16 v[58:61], v[130:133], v[162:165], v[58:61]
	v_mfma_f32_16x16x32_bf16 v[46:49], v[118:121], v[170:173], v[46:49]
	v_mfma_f32_16x16x32_bf16 v[42:45], v[130:133], v[170:173], v[42:45]
	v_mfma_f32_16x16x32_bf16 v[30:33], v[118:121], v[178:181], v[30:33]
	v_mfma_f32_16x16x32_bf16 v[26:29], v[130:133], v[178:181], v[26:29]
	v_mfma_f32_16x16x32_bf16 v[14:17], v[118:121], v[186:189], v[14:17]
	v_mfma_f32_16x16x32_bf16 v[10:13], v[130:133], v[186:189], v[10:13]
	v_mfma_f32_16x16x32_bf16 v[62:65], v[126:129], v[166:169], v[62:65]
	v_mfma_f32_16x16x32_bf16 v[58:61], v[134:137], v[166:169], v[58:61]
	v_mfma_f32_16x16x32_bf16 v[46:49], v[126:129], v[174:177], v[46:49]
	v_mfma_f32_16x16x32_bf16 v[42:45], v[134:137], v[174:177], v[42:45]
	v_mfma_f32_16x16x32_bf16 v[30:33], v[126:129], v[182:185], v[30:33]
	v_mfma_f32_16x16x32_bf16 v[26:29], v[134:137], v[182:185], v[26:29]
	v_mfma_f32_16x16x32_bf16 v[14:17], v[126:129], v[200:203], v[14:17]
	v_mfma_f32_16x16x32_bf16 v[10:13], v[134:137], v[200:203], v[10:13]
	s_setprio 0
	s_setprio 1
	v_mfma_f32_16x16x32_bf16 v[54:57], v[138:141], v[162:165], v[54:57]
	v_mfma_f32_16x16x32_bf16 v[50:53], v[154:157], v[162:165], v[50:53]
	v_mfma_f32_16x16x32_bf16 v[38:41], v[138:141], v[170:173], v[38:41]
	v_mfma_f32_16x16x32_bf16 v[34:37], v[154:157], v[170:173], v[34:37]
	v_mfma_f32_16x16x32_bf16 v[22:25], v[138:141], v[178:181], v[22:25]
	v_mfma_f32_16x16x32_bf16 v[18:21], v[154:157], v[178:181], v[18:21]
	v_mfma_f32_16x16x32_bf16 v[6:9], v[138:141], v[186:189], v[6:9]
	v_mfma_f32_16x16x32_bf16 v[2:5], v[154:157], v[186:189], v[2:5]
	v_mfma_f32_16x16x32_bf16 v[54:57], v[142:145], v[166:169], v[54:57]
	v_mfma_f32_16x16x32_bf16 v[50:53], v[158:161], v[166:169], v[50:53]
	v_mfma_f32_16x16x32_bf16 v[38:41], v[142:145], v[174:177], v[38:41]
	v_mfma_f32_16x16x32_bf16 v[34:37], v[158:161], v[174:177], v[34:37]
	v_mfma_f32_16x16x32_bf16 v[22:25], v[142:145], v[182:185], v[22:25]
	v_mfma_f32_16x16x32_bf16 v[18:21], v[158:161], v[182:185], v[18:21]
	s_setprio 2
	s_barrier
	v_mfma_f32_16x16x32_bf16 v[6:9], v[142:145], v[200:203], v[6:9]
	v_mfma_f32_16x16x32_bf16 v[2:5], v[158:161], v[200:203], v[2:5]
	s_setprio 0
	s_add_i32 s6, 0, 0x18000
	s_add_i32 s14, 0, 0x1c000
	v_add_u32_e32 v134, s6, v238
	v_add_u32_e32 v158, s14, v238
	ds_read_b128 v[118:121], v134
	ds_read_b128 v[126:129], v134 offset:1024
	ds_read_b128 v[130:133], v134 offset:2048
	ds_read_b128 v[134:137], v134 offset:3072
	ds_read_b128 v[138:141], v158
	ds_read_b128 v[142:145], v158 offset:1024
	ds_read_b128 v[154:157], v158 offset:2048
	ds_read_b128 v[158:161], v158 offset:3072
	s_add_u32 s12, s48, 0x4000
	s_addc_u32 s13, s49, 0
	s_mov_b32 m0, s54
	ds_read_b128 v[162:165], v239 offset:32768
	ds_read_b128 v[166:169], v239 offset:33792
	ds_read_b128 v[170:173], v239 offset:34816
	ds_read_b128 v[174:177], v239 offset:35840
	ds_read_b128 v[178:181], v239 offset:36864
	ds_read_b128 v[182:185], v239 offset:37888
	ds_read_b128 v[186:189], v239 offset:38912
	ds_read_b128 v[200:203], v239 offset:39936
	global_load_lds_dwordx4 v194, s[12:13]
	s_mov_b32 m0, s55
	s_nop 0
	global_load_lds_dwordx4 v192, s[12:13]
	s_waitcnt vmcnt(8)
	s_waitcnt lgkmcnt(0)
	s_barrier
	s_setprio 1
	s_waitcnt lgkmcnt(0)
	v_mfma_f32_16x16x32_bf16 v[150:153], v[118:121], v[162:165], v[150:153]
	v_mfma_f32_16x16x32_bf16 v[146:149], v[130:133], v[162:165], v[146:149]
	v_mfma_f32_16x16x32_bf16 v[110:113], v[118:121], v[170:173], v[110:113]
	v_mfma_f32_16x16x32_bf16 v[106:109], v[130:133], v[170:173], v[106:109]
	v_mfma_f32_16x16x32_bf16 v[94:97], v[118:121], v[178:181], v[94:97]
	v_mfma_f32_16x16x32_bf16 v[90:93], v[130:133], v[178:181], v[90:93]
	v_mfma_f32_16x16x32_bf16 v[78:81], v[118:121], v[186:189], v[78:81]
	v_mfma_f32_16x16x32_bf16 v[74:77], v[130:133], v[186:189], v[74:77]
	v_mfma_f32_16x16x32_bf16 v[150:153], v[126:129], v[166:169], v[150:153]
	v_mfma_f32_16x16x32_bf16 v[146:149], v[134:137], v[166:169], v[146:149]
	v_mfma_f32_16x16x32_bf16 v[110:113], v[126:129], v[174:177], v[110:113]
	v_mfma_f32_16x16x32_bf16 v[106:109], v[134:137], v[174:177], v[106:109]
	v_mfma_f32_16x16x32_bf16 v[94:97], v[126:129], v[182:185], v[94:97]
	v_mfma_f32_16x16x32_bf16 v[90:93], v[134:137], v[182:185], v[90:93]
	v_mfma_f32_16x16x32_bf16 v[78:81], v[126:129], v[200:203], v[78:81]
	v_mfma_f32_16x16x32_bf16 v[74:77], v[134:137], v[200:203], v[74:77]
	s_setprio 0
	s_setprio 1
	v_mfma_f32_16x16x32_bf16 v[122:125], v[138:141], v[162:165], v[122:125]
	v_mfma_f32_16x16x32_bf16 v[114:117], v[154:157], v[162:165], v[114:117]
	v_mfma_f32_16x16x32_bf16 v[102:105], v[138:141], v[170:173], v[102:105]
	v_mfma_f32_16x16x32_bf16 v[98:101], v[154:157], v[170:173], v[98:101]
	v_mfma_f32_16x16x32_bf16 v[86:89], v[138:141], v[178:181], v[86:89]
	v_mfma_f32_16x16x32_bf16 v[82:85], v[154:157], v[178:181], v[82:85]
	v_mfma_f32_16x16x32_bf16 v[70:73], v[138:141], v[186:189], v[70:73]
	v_mfma_f32_16x16x32_bf16 v[66:69], v[154:157], v[186:189], v[66:69]
	v_mfma_f32_16x16x32_bf16 v[122:125], v[142:145], v[166:169], v[122:125]
	v_mfma_f32_16x16x32_bf16 v[114:117], v[158:161], v[166:169], v[114:117]
	v_mfma_f32_16x16x32_bf16 v[102:105], v[142:145], v[174:177], v[102:105]
	v_mfma_f32_16x16x32_bf16 v[98:101], v[158:161], v[174:177], v[98:101]
	v_mfma_f32_16x16x32_bf16 v[86:89], v[142:145], v[182:185], v[86:89]
	v_mfma_f32_16x16x32_bf16 v[82:85], v[158:161], v[182:185], v[82:85]
	s_setprio 2
	s_barrier
; #define PG8_STAGE(bufoff, gbase, voff) do { _Pragma("unroll") for (int _i = 0; _i < 2; ++_i) \
;         __builtin_amdgcn_global_load_lds((const unsigned*)((const char*)(gbase) + (voff)[_i]), (LAS unsigned*)(lds + (bufoff) + ldsw + _i * 8192), 16, 0, 0); } while (0)
; #define PG8_LDA(dst, b, h) do { _Pragma("unroll") for (int m = 0; m < 4; ++m) _Pragma("unroll") for (int k = 0; k < 2; ++k) dst[m][k] = *(const LAS bf16x8*)(lds + PG8_SA(b, h) + aoff + m * 2048 + k * 1024); } while (0)
; #define PG8_MMA(ai, bj, At, Bt) do { __builtin_amdgcn_s_setprio(1); _Pragma("unroll") for (int m = 0; m < 4; ++m) _Pragma("unroll") for (int n = 0; n < 2; ++n) _Pragma("unroll") for (int k = 0; k < 2; ++k) \
;         acc[ai][bj][m][n] = __builtin_amdgcn_mfma_f32_16x16x32_bf16(Bt[n][k], At[m][k], acc[ai][bj][m][n], 0, 0, 0); __builtin_amdgcn_s_setprio(0); } while (0)
; #define PG8_WAIT_V(n) asm volatile("s_waitcnt vmcnt(" #n ")" ::: "memory")
; #define PG8_WAIT_L(n) asm volatile("s_waitcnt lgkmcnt(" #n ")" ::: "memory")
; #define PG8_BAR __builtin_amdgcn_s_barrier()
; #define PG8_SCHED __builtin_amdgcn_sched_barrier(0)
; template <class Epi>
; __device__ __forceinline__ void gemm_phase(LAS unsigned char* lds, const Gemm g, const TileOrder& S, const Epi& E) {
;     ...
;             PG8_WAIT_V(8); PG8_WAIT_L(0); PG8_BAR; PG8_MMA(0, 0, At, B0); PG8_MMA(0, 1, At, B1); PG8_BAR; PG8_SCHED;
;             PG8_LDA(At, 1, 1); PG8_STAGE(PG8_SB(1, 0), b3, voffB); PG8_STAGE(PG8_SB(1, 1), b3 + hstepB, voffB); PG8_STAGE(PG8_SA(1, 0), a3, voffA);
;             PG8_WAIT_V(8); PG8_WAIT_L(0); PG8_BAR; PG8_MMA(1, 0, At, B0); PG8_MMA(1, 1, At, B1); PG8_BAR; PG8_SCHED;
;         }
;         if (wr == 0) PG8_BAR;
	v_mfma_f32_16x16x32_bf16 v[70:73], v[142:145], v[200:203], v[70:73]
	v_mfma_f32_16x16x32_bf16 v[66:69], v[158:161], v[200:203], v[66:69]
	s_setprio 0
	s_add_i32 s6, s6, s51
	v_lshl_add_u64 v[204:205], v[204:205], 0, s[34:35]
	s_mov_b32 m0, s6
	ds_read_b128 v[162:165], v239 offset:49152
	ds_read_b128 v[166:169], v239 offset:50176
	ds_read_b128 v[170:173], v239 offset:51200
	ds_read_b128 v[174:177], v239 offset:52224
	ds_read_b128 v[178:181], v239 offset:53248
	ds_read_b128 v[182:185], v239 offset:54272
	ds_read_b128 v[186:189], v239 offset:55296
	ds_read_b128 v[200:203], v239 offset:56320
	global_load_lds_dwordx4 v[204:205], off
	s_add_i32 m0, s6, 0x2000
	s_add_u32 s12, s30, 0x80080
	v_lshl_add_u64 v[204:205], v[206:207], 0, s[34:35]
	s_addc_u32 s13, s31, 0
	s_add_i32 s6, s14, s51
	global_load_lds_dwordx4 v[204:205], off
	s_mov_b32 m0, s6
	s_nop 0
	global_load_lds_dwordx4 v0, s[12:13]
	s_add_i32 m0, s6, 0x2000
	s_nop 0
	global_load_lds_dwordx4 v190, s[12:13]
	s_mov_b32 m0, s60
	s_nop 0
	global_load_lds_dwordx4 v194, s[2:3]
	s_mov_b32 m0, s61
	s_nop 0
	global_load_lds_dwordx4 v192, s[2:3]
	s_waitcnt vmcnt(8)
	s_waitcnt lgkmcnt(0)
	s_barrier
	s_setprio 1
	s_waitcnt lgkmcnt(0)
	v_mfma_f32_16x16x32_bf16 v[62:65], v[118:121], v[162:165], v[62:65]
	v_mfma_f32_16x16x32_bf16 v[58:61], v[130:133], v[162:165], v[58:61]
	v_mfma_f32_16x16x32_bf16 v[46:49], v[118:121], v[170:173], v[46:49]
	v_mfma_f32_16x16x32_bf16 v[42:45], v[130:133], v[170:173], v[42:45]
	v_mfma_f32_16x16x32_bf16 v[30:33], v[118:121], v[178:181], v[30:33]
	v_mfma_f32_16x16x32_bf16 v[26:29], v[130:133], v[178:181], v[26:29]
	v_mfma_f32_16x16x32_bf16 v[14:17], v[118:121], v[186:189], v[14:17]
	v_mfma_f32_16x16x32_bf16 v[10:13], v[130:133], v[186:189], v[10:13]
	v_mfma_f32_16x16x32_bf16 v[62:65], v[126:129], v[166:169], v[62:65]
	v_mfma_f32_16x16x32_bf16 v[58:61], v[134:137], v[166:169], v[58:61]
	v_mfma_f32_16x16x32_bf16 v[46:49], v[126:129], v[174:177], v[46:49]
	v_mfma_f32_16x16x32_bf16 v[42:45], v[134:137], v[174:177], v[42:45]
	v_mfma_f32_16x16x32_bf16 v[30:33], v[126:129], v[182:185], v[30:33]
	v_mfma_f32_16x16x32_bf16 v[26:29], v[134:137], v[182:185], v[26:29]
	v_mfma_f32_16x16x32_bf16 v[14:17], v[126:129], v[200:203], v[14:17]
	v_mfma_f32_16x16x32_bf16 v[10:13], v[134:137], v[200:203], v[10:13]
	s_setprio 0
	s_setprio 1
	v_mfma_f32_16x16x32_bf16 v[54:57], v[138:141], v[162:165], v[54:57]
	v_mfma_f32_16x16x32_bf16 v[50:53], v[154:157], v[162:165], v[50:53]
	v_mfma_f32_16x16x32_bf16 v[38:41], v[138:141], v[170:173], v[38:41]
	v_mfma_f32_16x16x32_bf16 v[34:37], v[154:157], v[170:173], v[34:37]
	v_mfma_f32_16x16x32_bf16 v[22:25], v[138:141], v[178:181], v[22:25]
	v_mfma_f32_16x16x32_bf16 v[18:21], v[154:157], v[178:181], v[18:21]
	v_mfma_f32_16x16x32_bf16 v[6:9], v[138:141], v[186:189], v[6:9]
	v_mfma_f32_16x16x32_bf16 v[2:5], v[154:157], v[186:189], v[2:5]
	v_mfma_f32_16x16x32_bf16 v[54:57], v[142:145], v[166:169], v[54:57]
	v_mfma_f32_16x16x32_bf16 v[50:53], v[158:161], v[166:169], v[50:53]
	v_mfma_f32_16x16x32_bf16 v[38:41], v[142:145], v[174:177], v[38:41]
	v_mfma_f32_16x16x32_bf16 v[34:37], v[158:161], v[174:177], v[34:37]
	v_mfma_f32_16x16x32_bf16 v[22:25], v[142:145], v[182:185], v[22:25]
	v_mfma_f32_16x16x32_bf16 v[18:21], v[158:161], v[182:185], v[18:21]
	s_setprio 2
	s_barrier
	v_mfma_f32_16x16x32_bf16 v[6:9], v[142:145], v[200:203], v[6:9]
	v_mfma_f32_16x16x32_bf16 v[2:5], v[158:161], v[200:203], v[2:5]
	s_setprio 0
	s_add_i32 s68, s68, 2
	s_add_u32 s66, s66, 0x100
	s_addc_u32 s67, s67, 0
	s_add_u32 s28, s28, 0x10000
	s_addc_u32 s29, s29, 0
	s_cmp_gt_u32 s68, 29
	s_cbranch_scc0 .LBB0_255
	s_and_b64 vcc, exec, s[36:37]
	s_cbranch_vccz .LBB0_258
	s_barrier

; #define PG8_STAGE(bufoff, gbase, voff) do { _Pragma("unroll") for (int _i = 0; _i < 2; ++_i) \
;         __builtin_amdgcn_global_load_lds((const unsigned*)((const char*)(gbase) + (voff)[_i]), (LAS unsigned*)(lds + (bufoff) + ldsw + _i * 8192), 16, 0, 0); } while (0)
; #define PG8_LDA(dst, b, h) do { _Pragma("unroll") for (int m = 0; m < 4; ++m) _Pragma("unroll") for (int k = 0; k < 2; ++k) dst[m][k] = *(const LAS bf16x8*)(lds + PG8_SA(b, h) + aoff + m * 2048 + k * 1024); } while (0)
; #define PG8_LDB(dst, b, h) do { _Pragma("unroll") for (int n = 0; n < 2; ++n) _Pragma("unroll") for (int k = 0; k < 2; ++k) dst[n][k] = *(const LAS bf16x8*)(lds + PG8_SB(b, h) + boff + n * 2048 + k * 1024); } while (0)
; #define PG8_MMA(ai, bj, At, Bt) do { __builtin_amdgcn_s_setprio(1); _Pragma("unroll") for (int m = 0; m < 4; ++m) _Pragma("unroll") for (int n = 0; n < 2; ++n) _Pragma("unroll") for (int k = 0; k < 2; ++k) \
;         acc[ai][bj][m][n] = __builtin_amdgcn_mfma_f32_16x16x32_bf16(Bt[n][k], At[m][k], acc[ai][bj][m][n], 0, 0, 0); __builtin_amdgcn_s_setprio(0); } while (0)
; #define PG8_WAIT_V(n) asm volatile("s_waitcnt vmcnt(" #n ")" ::: "memory")
; #define PG8_WAIT_L(n) asm volatile("s_waitcnt lgkmcnt(" #n ")" ::: "memory")
; #define PG8_BAR __builtin_amdgcn_s_barrier()
; #define PG8_SCHED __builtin_amdgcn_sched_barrier(0)
; template <class Epi>
; __device__ __forceinline__ void gemm_phase(LAS unsigned char* lds, const Gemm g, const TileOrder& S, const Epi& E) {
;     ...
;             const bool last = (t == nt - 2);
;             const char* a1 = cA + (size_t)(t + 1) * kstepA;
;             const char* a2 = last ? nA : cA + (size_t)(t + 2) * kstepA; const char* b2 = last ? nB : cB + (size_t)(t + 2) * kstep;
;             const char* a3 = a2 + kstepA; const char* b3 = b2 + kstep;
;             PG8_LDB(B0, 0, 0); PG8_LDB(B1, 0, 1); PG8_SCHED; PG8_LDA(At, 0, 0); PG8_STAGE(PG8_SA(1, 1), a1 + hstepA, voffA);
;             PG8_WAIT_V(8); PG8_WAIT_L(0); PG8_BAR; PG8_MMA(0, 0, At, B0); PG8_MMA(0, 1, At, B1); PG8_BAR; PG8_SCHED;
;             PG8_LDA(At, 0, 1); PG8_STAGE(PG8_SB(0, 0), b2, voffB); PG8_STAGE(PG8_SB(0, 1), b2 + hstepB, voffB); PG8_STAGE(PG8_SA(0, 0), a2, voffA);
.LBB0_457:
	s_mov_b32 s6, 0x10000
	s_mov_b32 s12, 0x14000
	v_add_u32_e32 v156, s6, v142
	v_add_u32_e32 v172, s12, v142
	ds_read_b128 v[144:147], v156
	ds_read_b128 v[148:151], v156 offset:1024
	ds_read_b128 v[152:155], v156 offset:2048
	ds_read_b128 v[156:159], v156 offset:3072
	ds_read_b128 v[160:163], v172
	ds_read_b128 v[164:167], v172 offset:1024
	ds_read_b128 v[168:171], v172 offset:2048
	ds_read_b128 v[172:175], v172 offset:3072
	ds_read_b128 v[176:179], v143
	ds_read_b128 v[180:183], v143 offset:1024
	ds_read_b128 v[184:187], v143 offset:2048
	ds_read_b128 v[188:191], v143 offset:3072
	ds_read_b128 v[192:195], v143 offset:4096
	ds_read_b128 v[196:199], v143 offset:5120
	ds_read_b128 v[200:203], v143 offset:6144
	ds_read_b128 v[204:207], v143 offset:7168
	s_add_u32 s2, s44, 0x100
	s_addc_u32 s3, s45, 0
	s_cmp_eq_u32 s60, 4
	s_cselect_b32 s47, s39, s3
	s_cselect_b32 s46, s38, s2
	s_cselect_b32 s5, s29, s59
	s_cselect_b32 s4, s57, s58
	s_add_i32 m0, s26, 0xc000
	s_nop 0
	global_load_lds_dwordx4 v136, s[44:45]
	s_add_i32 m0, s26, 0xe000
	s_nop 0
	global_load_lds_dwordx4 v138, s[44:45]
	s_waitcnt vmcnt(8)
	s_waitcnt lgkmcnt(0)
	s_barrier
	s_setprio 1
	s_waitcnt lgkmcnt(0)
	v_mfma_f32_16x16x32_bf16 v[126:129], v[144:147], v[176:179], v[126:129]
	v_mfma_f32_16x16x32_bf16 v[122:125], v[152:155], v[176:179], v[122:125]
	v_mfma_f32_16x16x32_bf16 v[118:121], v[144:147], v[184:187], v[118:121]
	v_mfma_f32_16x16x32_bf16 v[114:117], v[152:155], v[184:187], v[114:117]
	v_mfma_f32_16x16x32_bf16 v[106:109], v[144:147], v[192:195], v[106:109]
	v_mfma_f32_16x16x32_bf16 v[98:101], v[152:155], v[192:195], v[98:101]
	v_mfma_f32_16x16x32_bf16 v[90:93], v[144:147], v[200:203], v[90:93]
	v_mfma_f32_16x16x32_bf16 v[82:85], v[152:155], v[200:203], v[82:85]
	v_mfma_f32_16x16x32_bf16 v[126:129], v[148:151], v[180:183], v[126:129]
	v_mfma_f32_16x16x32_bf16 v[122:125], v[156:159], v[180:183], v[122:125]
	v_mfma_f32_16x16x32_bf16 v[118:121], v[148:151], v[188:191], v[118:121]
	v_mfma_f32_16x16x32_bf16 v[114:117], v[156:159], v[188:191], v[114:117]
	v_mfma_f32_16x16x32_bf16 v[106:109], v[148:151], v[196:199], v[106:109]
	v_mfma_f32_16x16x32_bf16 v[98:101], v[156:159], v[196:199], v[98:101]
	v_mfma_f32_16x16x32_bf16 v[90:93], v[148:151], v[204:207], v[90:93]
	v_mfma_f32_16x16x32_bf16 v[82:85], v[156:159], v[204:207], v[82:85]
	s_setprio 0
	s_setprio 1
	v_mfma_f32_16x16x32_bf16 v[110:113], v[160:163], v[176:179], v[110:113]
	v_mfma_f32_16x16x32_bf16 v[102:105], v[168:171], v[176:179], v[102:105]
	v_mfma_f32_16x16x32_bf16 v[94:97], v[160:163], v[184:187], v[94:97]
	v_mfma_f32_16x16x32_bf16 v[86:89], v[168:171], v[184:187], v[86:89]
	v_mfma_f32_16x16x32_bf16 v[78:81], v[160:163], v[192:195], v[78:81]
	v_mfma_f32_16x16x32_bf16 v[74:77], v[168:171], v[192:195], v[74:77]
	v_mfma_f32_16x16x32_bf16 v[70:73], v[160:163], v[200:203], v[70:73]
	v_mfma_f32_16x16x32_bf16 v[66:69], v[168:171], v[200:203], v[66:69]
	v_mfma_f32_16x16x32_bf16 v[110:113], v[164:167], v[180:183], v[110:113]
	v_mfma_f32_16x16x32_bf16 v[102:105], v[172:175], v[180:183], v[102:105]
	v_mfma_f32_16x16x32_bf16 v[94:97], v[164:167], v[188:191], v[94:97]
	v_mfma_f32_16x16x32_bf16 v[86:89], v[172:175], v[188:191], v[86:89]
	v_mfma_f32_16x16x32_bf16 v[78:81], v[164:167], v[196:199], v[78:81]
	v_mfma_f32_16x16x32_bf16 v[74:77], v[172:175], v[196:199], v[74:77]
	s_setprio 2
	s_barrier
	v_mfma_f32_16x16x32_bf16 v[70:73], v[164:167], v[204:207], v[70:73]
	v_mfma_f32_16x16x32_bf16 v[66:69], v[172:175], v[204:207], v[66:69]
	s_setprio 0
	s_add_i32 s6, s6, s25
	v_lshl_add_u64 v[208:209], s[4:5], 0, v[0:1]
	s_mov_b32 m0, s6
	ds_read_b128 v[176:179], v143 offset:16384
	ds_read_b128 v[180:183], v143 offset:17408
	ds_read_b128 v[184:187], v143 offset:18432
	ds_read_b128 v[188:191], v143 offset:19456
	ds_read_b128 v[192:195], v143 offset:20480
	ds_read_b128 v[196:199], v143 offset:21504
	ds_read_b128 v[200:203], v143 offset:22528
	ds_read_b128 v[204:207], v143 offset:23552
	global_load_lds_dwordx4 v[208:209], off
	s_add_i32 m0, s6, 0x2000
	s_add_u32 s14, s4, 0x20000
	v_lshl_add_u64 v[210:211], s[4:5], 0, v[130:131]
	s_addc_u32 s15, s5, 0
	s_add_i32 s6, s12, s25
	global_load_lds_dwordx4 v[210:211], off
	s_mov_b32 m0, s6
	v_lshl_add_u64 v[214:215], s[46:47], 0, v[132:133]
	global_load_lds_dwordx4 v0, s[14:15]
	s_add_i32 m0, s6, 0x2000
	s_nop 0
	global_load_lds_dwordx4 v130, s[14:15]
	v_lshl_add_u64 v[212:213], s[46:47], 0, v[134:135]
	s_mov_b32 m0, s26
	s_nop 0
	global_load_lds_dwordx4 v[212:213], off
	s_mov_b32 m0, s48
	s_nop 0
	global_load_lds_dwordx4 v[214:215], off
	s_waitcnt vmcnt(8)
	s_waitcnt lgkmcnt(0)
	s_barrier
; #define PG8_STAGE(bufoff, gbase, voff) do { _Pragma("unroll") for (int _i = 0; _i < 2; ++_i) \
;         __builtin_amdgcn_global_load_lds((const unsigned*)((const char*)(gbase) + (voff)[_i]), (LAS unsigned*)(lds + (bufoff) + ldsw + _i * 8192), 16, 0, 0); } while (0)
; #define PG8_LDA(dst, b, h) do { _Pragma("unroll") for (int m = 0; m < 4; ++m) _Pragma("unroll") for (int k = 0; k < 2; ++k) dst[m][k] = *(const LAS bf16x8*)(lds + PG8_SA(b, h) + aoff + m * 2048 + k * 1024); } while (0)
; #define PG8_LDB(dst, b, h) do { _Pragma("unroll") for (int n = 0; n < 2; ++n) _Pragma("unroll") for (int k = 0; k < 2; ++k) dst[n][k] = *(const LAS bf16x8*)(lds + PG8_SB(b, h) + boff + n * 2048 + k * 1024); } while (0)
; #define PG8_MMA(ai, bj, At, Bt) do { __builtin_amdgcn_s_setprio(1); _Pragma("unroll") for (int m = 0; m < 4; ++m) _Pragma("unroll") for (int n = 0; n < 2; ++n) _Pragma("unroll") for (int k = 0; k < 2; ++k) \
;         acc[ai][bj][m][n] = __builtin_amdgcn_mfma_f32_16x16x32_bf16(Bt[n][k], At[m][k], acc[ai][bj][m][n], 0, 0, 0); __builtin_amdgcn_s_setprio(0); } while (0)
; #define PG8_WAIT_V(n) asm volatile("s_waitcnt vmcnt(" #n ")" ::: "memory")
; #define PG8_WAIT_L(n) asm volatile("s_waitcnt lgkmcnt(" #n ")" ::: "memory")
; #define PG8_BAR __builtin_amdgcn_s_barrier()
; #define PG8_SCHED __builtin_amdgcn_sched_barrier(0)
; template <class Epi>
; __device__ __forceinline__ void gemm_phase(LAS unsigned char* lds, const Gemm g, const TileOrder& S, const Epi& E) {
;     ...
;             PG8_WAIT_V(8); PG8_WAIT_L(0); PG8_BAR; PG8_MMA(1, 0, At, B0); PG8_MMA(1, 1, At, B1); PG8_BAR; PG8_SCHED;
;             PG8_LDB(B0, 1, 0); PG8_LDB(B1, 1, 1); PG8_SCHED; PG8_LDA(At, 1, 0); PG8_STAGE(PG8_SA(0, 1), a2 + hstepA, voffA);
;             PG8_WAIT_V(8); PG8_WAIT_L(0); PG8_BAR; PG8_MMA(0, 0, At, B0); PG8_MMA(0, 1, At, B1); PG8_BAR; PG8_SCHED;
	s_setprio 1
	s_waitcnt lgkmcnt(0)
	v_mfma_f32_16x16x32_bf16 v[62:65], v[144:147], v[176:179], v[62:65]
	v_mfma_f32_16x16x32_bf16 v[58:61], v[152:155], v[176:179], v[58:61]
	v_mfma_f32_16x16x32_bf16 v[54:57], v[144:147], v[184:187], v[54:57]
	v_mfma_f32_16x16x32_bf16 v[50:53], v[152:155], v[184:187], v[50:53]
	v_mfma_f32_16x16x32_bf16 v[38:41], v[144:147], v[192:195], v[38:41]
	v_mfma_f32_16x16x32_bf16 v[34:37], v[152:155], v[192:195], v[34:37]
	v_mfma_f32_16x16x32_bf16 v[22:25], v[144:147], v[200:203], v[22:25]
	v_mfma_f32_16x16x32_bf16 v[18:21], v[152:155], v[200:203], v[18:21]
	v_mfma_f32_16x16x32_bf16 v[62:65], v[148:151], v[180:183], v[62:65]
	v_mfma_f32_16x16x32_bf16 v[58:61], v[156:159], v[180:183], v[58:61]
	v_mfma_f32_16x16x32_bf16 v[54:57], v[148:151], v[188:191], v[54:57]
	v_mfma_f32_16x16x32_bf16 v[50:53], v[156:159], v[188:191], v[50:53]
	v_mfma_f32_16x16x32_bf16 v[38:41], v[148:151], v[196:199], v[38:41]
	v_mfma_f32_16x16x32_bf16 v[34:37], v[156:159], v[196:199], v[34:37]
	v_mfma_f32_16x16x32_bf16 v[22:25], v[148:151], v[204:207], v[22:25]
	v_mfma_f32_16x16x32_bf16 v[18:21], v[156:159], v[204:207], v[18:21]
	s_setprio 0
	s_setprio 1
	v_mfma_f32_16x16x32_bf16 v[46:49], v[160:163], v[176:179], v[46:49]
	v_mfma_f32_16x16x32_bf16 v[42:45], v[168:171], v[176:179], v[42:45]
	v_mfma_f32_16x16x32_bf16 v[30:33], v[160:163], v[184:187], v[30:33]
	v_mfma_f32_16x16x32_bf16 v[26:29], v[168:171], v[184:187], v[26:29]
	v_mfma_f32_16x16x32_bf16 v[14:17], v[160:163], v[192:195], v[14:17]
	v_mfma_f32_16x16x32_bf16 v[10:13], v[168:171], v[192:195], v[10:13]
	v_mfma_f32_16x16x32_bf16 v[6:9], v[160:163], v[200:203], v[6:9]
	v_mfma_f32_16x16x32_bf16 v[2:5], v[168:171], v[200:203], v[2:5]
	v_mfma_f32_16x16x32_bf16 v[46:49], v[164:167], v[180:183], v[46:49]
	v_mfma_f32_16x16x32_bf16 v[42:45], v[172:175], v[180:183], v[42:45]
	v_mfma_f32_16x16x32_bf16 v[30:33], v[164:167], v[188:191], v[30:33]
	v_mfma_f32_16x16x32_bf16 v[26:29], v[172:175], v[188:191], v[26:29]
	v_mfma_f32_16x16x32_bf16 v[14:17], v[164:167], v[196:199], v[14:17]
	v_mfma_f32_16x16x32_bf16 v[10:13], v[172:175], v[196:199], v[10:13]
	s_setprio 2
	s_barrier
	v_mfma_f32_16x16x32_bf16 v[6:9], v[164:167], v[204:207], v[6:9]
	v_mfma_f32_16x16x32_bf16 v[2:5], v[172:175], v[204:207], v[2:5]
	s_setprio 0
	s_add_i32 s6, 0, 0x18000
	s_add_i32 s12, 0, 0x1c000
	v_add_u32_e32 v156, s6, v142
	v_add_u32_e32 v172, s12, v142
	ds_read_b128 v[144:147], v156
	ds_read_b128 v[148:151], v156 offset:1024
	ds_read_b128 v[152:155], v156 offset:2048
	ds_read_b128 v[156:159], v156 offset:3072
	ds_read_b128 v[160:163], v172
	ds_read_b128 v[164:167], v172 offset:1024
	ds_read_b128 v[168:171], v172 offset:2048
	ds_read_b128 v[172:175], v172 offset:3072
	s_add_u32 s14, s46, 0x30000
	s_addc_u32 s15, s47, 0
	s_mov_b32 m0, s49
	ds_read_b128 v[176:179], v143 offset:32768
	ds_read_b128 v[180:183], v143 offset:33792
	ds_read_b128 v[184:187], v143 offset:34816
	ds_read_b128 v[188:191], v143 offset:35840
	ds_read_b128 v[192:195], v143 offset:36864
	ds_read_b128 v[196:199], v143 offset:37888
	ds_read_b128 v[200:203], v143 offset:38912
	ds_read_b128 v[204:207], v143 offset:39936
	global_load_lds_dwordx4 v134, s[14:15]
	s_mov_b32 m0, s50
	s_nop 0
	global_load_lds_dwordx4 v132, s[14:15]
	s_waitcnt vmcnt(8)
	s_waitcnt lgkmcnt(0)
	s_barrier
	s_setprio 1
	s_waitcnt lgkmcnt(0)
	v_mfma_f32_16x16x32_bf16 v[126:129], v[144:147], v[176:179], v[126:129]
	v_mfma_f32_16x16x32_bf16 v[122:125], v[152:155], v[176:179], v[122:125]
	v_mfma_f32_16x16x32_bf16 v[118:121], v[144:147], v[184:187], v[118:121]
	v_mfma_f32_16x16x32_bf16 v[114:117], v[152:155], v[184:187], v[114:117]
	v_mfma_f32_16x16x32_bf16 v[106:109], v[144:147], v[192:195], v[106:109]
	v_mfma_f32_16x16x32_bf16 v[98:101], v[152:155], v[192:195], v[98:101]
	v_mfma_f32_16x16x32_bf16 v[90:93], v[144:147], v[200:203], v[90:93]
	v_mfma_f32_16x16x32_bf16 v[82:85], v[152:155], v[200:203], v[82:85]
	v_mfma_f32_16x16x32_bf16 v[126:129], v[148:151], v[180:183], v[126:129]
	v_mfma_f32_16x16x32_bf16 v[122:125], v[156:159], v[180:183], v[122:125]
	v_mfma_f32_16x16x32_bf16 v[118:121], v[148:151], v[188:191], v[118:121]
	v_mfma_f32_16x16x32_bf16 v[114:117], v[156:159], v[188:191], v[114:117]
	v_mfma_f32_16x16x32_bf16 v[106:109], v[148:151], v[196:199], v[106:109]
	v_mfma_f32_16x16x32_bf16 v[98:101], v[156:159], v[196:199], v[98:101]
	v_mfma_f32_16x16x32_bf16 v[90:93], v[148:151], v[204:207], v[90:93]
	v_mfma_f32_16x16x32_bf16 v[82:85], v[156:159], v[204:207], v[82:85]
	s_setprio 0
	s_setprio 1
	v_mfma_f32_16x16x32_bf16 v[110:113], v[160:163], v[176:179], v[110:113]
	v_mfma_f32_16x16x32_bf16 v[102:105], v[168:171], v[176:179], v[102:105]
	v_mfma_f32_16x16x32_bf16 v[94:97], v[160:163], v[184:187], v[94:97]
	v_mfma_f32_16x16x32_bf16 v[86:89], v[168:171], v[184:187], v[86:89]
	v_mfma_f32_16x16x32_bf16 v[78:81], v[160:163], v[192:195], v[78:81]
	v_mfma_f32_16x16x32_bf16 v[74:77], v[168:171], v[192:195], v[74:77]
	v_mfma_f32_16x16x32_bf16 v[70:73], v[160:163], v[200:203], v[70:73]
	v_mfma_f32_16x16x32_bf16 v[66:69], v[168:171], v[200:203], v[66:69]
	v_mfma_f32_16x16x32_bf16 v[110:113], v[164:167], v[180:183], v[110:113]
	v_mfma_f32_16x16x32_bf16 v[102:105], v[172:175], v[180:183], v[102:105]
	v_mfma_f32_16x16x32_bf16 v[94:97], v[164:167], v[188:191], v[94:97]
	v_mfma_f32_16x16x32_bf16 v[86:89], v[172:175], v[188:191], v[86:89]
	v_mfma_f32_16x16x32_bf16 v[78:81], v[164:167], v[196:199], v[78:81]
	v_mfma_f32_16x16x32_bf16 v[74:77], v[172:175], v[196:199], v[74:77]
	s_setprio 2
	s_barrier
; #define PG8_STAGE(bufoff, gbase, voff) do { _Pragma("unroll") for (int _i = 0; _i < 2; ++_i) \
;         __builtin_amdgcn_global_load_lds((const unsigned*)((const char*)(gbase) + (voff)[_i]), (LAS unsigned*)(lds + (bufoff) + ldsw + _i * 8192), 16, 0, 0); } while (0)
; #define PG8_LDA(dst, b, h) do { _Pragma("unroll") for (int m = 0; m < 4; ++m) _Pragma("unroll") for (int k = 0; k < 2; ++k) dst[m][k] = *(const LAS bf16x8*)(lds + PG8_SA(b, h) + aoff + m * 2048 + k * 1024); } while (0)
; #define PG8_MMA(ai, bj, At, Bt) do { __builtin_amdgcn_s_setprio(1); _Pragma("unroll") for (int m = 0; m < 4; ++m) _Pragma("unroll") for (int n = 0; n < 2; ++n) _Pragma("unroll") for (int k = 0; k < 2; ++k) \
;         acc[ai][bj][m][n] = __builtin_amdgcn_mfma_f32_16x16x32_bf16(Bt[n][k], At[m][k], acc[ai][bj][m][n], 0, 0, 0); __builtin_amdgcn_s_setprio(0); } while (0)
; #define PG8_WAIT_V(n) asm volatile("s_waitcnt vmcnt(" #n ")" ::: "memory")
; #define PG8_WAIT_L(n) asm volatile("s_waitcnt lgkmcnt(" #n ")" ::: "memory")
; #define PG8_BAR __builtin_amdgcn_s_barrier()
; #define PG8_SCHED __builtin_amdgcn_sched_barrier(0)
; template <class Epi>
; __device__ __forceinline__ void gemm_phase(LAS unsigned char* lds, const Gemm g, const TileOrder& S, const Epi& E) {
;     ...
;             PG8_WAIT_V(8); PG8_WAIT_L(0); PG8_BAR; PG8_MMA(0, 0, At, B0); PG8_MMA(0, 1, At, B1); PG8_BAR; PG8_SCHED;
;             PG8_LDA(At, 1, 1); PG8_STAGE(PG8_SB(1, 0), b3, voffB); PG8_STAGE(PG8_SB(1, 1), b3 + hstepB, voffB); PG8_STAGE(PG8_SA(1, 0), a3, voffA);
;             PG8_WAIT_V(8); PG8_WAIT_L(0); PG8_BAR; PG8_MMA(1, 0, At, B0); PG8_MMA(1, 1, At, B1); PG8_BAR; PG8_SCHED;
;         }
;         if (wr == 0) PG8_BAR;
	v_mfma_f32_16x16x32_bf16 v[70:73], v[164:167], v[204:207], v[70:73]
	v_mfma_f32_16x16x32_bf16 v[66:69], v[172:175], v[204:207], v[66:69]
	s_setprio 0
	s_add_i32 s6, s6, s25
	v_lshl_add_u64 v[208:209], v[208:209], 0, s[34:35]
	s_mov_b32 m0, s6
	ds_read_b128 v[176:179], v143 offset:49152
	ds_read_b128 v[180:183], v143 offset:50176
	ds_read_b128 v[184:187], v143 offset:51200
	ds_read_b128 v[188:191], v143 offset:52224
	ds_read_b128 v[192:195], v143 offset:53248
	ds_read_b128 v[196:199], v143 offset:54272
	ds_read_b128 v[200:203], v143 offset:55296
	ds_read_b128 v[204:207], v143 offset:56320
	global_load_lds_dwordx4 v[208:209], off
	s_add_i32 m0, s6, 0x2000
	s_add_u32 s4, s4, 0x20080
	v_lshl_add_u64 v[208:209], v[210:211], 0, s[34:35]
	s_addc_u32 s5, s5, 0
	s_add_i32 s6, s12, s25
	global_load_lds_dwordx4 v[208:209], off
	s_mov_b32 m0, s6
	s_nop 0
	global_load_lds_dwordx4 v0, s[4:5]
	v_lshl_add_u64 v[208:209], s[4:5], 0, v[130:131]
	s_add_i32 m0, s6, 0x2000
	s_nop 0
	global_load_lds_dwordx4 v[208:209], off
	v_lshl_add_u64 v[208:209], v[212:213], 0, s[34:35]
	s_mov_b32 m0, s51
	s_nop 0
	global_load_lds_dwordx4 v[208:209], off
	v_lshl_add_u64 v[208:209], v[214:215], 0, s[34:35]
	s_mov_b32 m0, s52
	s_nop 0
	global_load_lds_dwordx4 v[208:209], off
	s_waitcnt vmcnt(8)
	s_waitcnt lgkmcnt(0)
	s_barrier
	s_setprio 1
	s_waitcnt lgkmcnt(0)
	v_mfma_f32_16x16x32_bf16 v[62:65], v[144:147], v[176:179], v[62:65]
	v_mfma_f32_16x16x32_bf16 v[58:61], v[152:155], v[176:179], v[58:61]
	v_mfma_f32_16x16x32_bf16 v[54:57], v[144:147], v[184:187], v[54:57]
	v_mfma_f32_16x16x32_bf16 v[50:53], v[152:155], v[184:187], v[50:53]
	v_mfma_f32_16x16x32_bf16 v[38:41], v[144:147], v[192:195], v[38:41]
	v_mfma_f32_16x16x32_bf16 v[34:37], v[152:155], v[192:195], v[34:37]
	v_mfma_f32_16x16x32_bf16 v[22:25], v[144:147], v[200:203], v[22:25]
	v_mfma_f32_16x16x32_bf16 v[18:21], v[152:155], v[200:203], v[18:21]
	v_mfma_f32_16x16x32_bf16 v[62:65], v[148:151], v[180:183], v[62:65]
	v_mfma_f32_16x16x32_bf16 v[58:61], v[156:159], v[180:183], v[58:61]
	v_mfma_f32_16x16x32_bf16 v[54:57], v[148:151], v[188:191], v[54:57]
	v_mfma_f32_16x16x32_bf16 v[50:53], v[156:159], v[188:191], v[50:53]
	v_mfma_f32_16x16x32_bf16 v[38:41], v[148:151], v[196:199], v[38:41]
	v_mfma_f32_16x16x32_bf16 v[34:37], v[156:159], v[196:199], v[34:37]
	v_mfma_f32_16x16x32_bf16 v[22:25], v[148:151], v[204:207], v[22:25]
	v_mfma_f32_16x16x32_bf16 v[18:21], v[156:159], v[204:207], v[18:21]
	s_setprio 0
	s_setprio 1
	v_mfma_f32_16x16x32_bf16 v[46:49], v[160:163], v[176:179], v[46:49]
	v_mfma_f32_16x16x32_bf16 v[42:45], v[168:171], v[176:179], v[42:45]
	v_mfma_f32_16x16x32_bf16 v[30:33], v[160:163], v[184:187], v[30:33]
	v_mfma_f32_16x16x32_bf16 v[26:29], v[168:171], v[184:187], v[26:29]
	v_mfma_f32_16x16x32_bf16 v[14:17], v[160:163], v[192:195], v[14:17]
	v_mfma_f32_16x16x32_bf16 v[10:13], v[168:171], v[192:195], v[10:13]
	v_mfma_f32_16x16x32_bf16 v[6:9], v[160:163], v[200:203], v[6:9]
	v_mfma_f32_16x16x32_bf16 v[2:5], v[168:171], v[200:203], v[2:5]
	v_mfma_f32_16x16x32_bf16 v[46:49], v[164:167], v[180:183], v[46:49]
	v_mfma_f32_16x16x32_bf16 v[42:45], v[172:175], v[180:183], v[42:45]
	v_mfma_f32_16x16x32_bf16 v[30:33], v[164:167], v[188:191], v[30:33]
	v_mfma_f32_16x16x32_bf16 v[26:29], v[172:175], v[188:191], v[26:29]
	v_mfma_f32_16x16x32_bf16 v[14:17], v[164:167], v[196:199], v[14:17]
	v_mfma_f32_16x16x32_bf16 v[10:13], v[172:175], v[196:199], v[10:13]
	s_setprio 2
	s_barrier
	v_mfma_f32_16x16x32_bf16 v[6:9], v[164:167], v[204:207], v[6:9]
	v_mfma_f32_16x16x32_bf16 v[2:5], v[172:175], v[204:207], v[2:5]
	s_setprio 0
	s_add_i32 s60, s60, 2
	s_add_u32 s58, s58, 0x100
	s_addc_u32 s59, s59, 0
	s_cmp_gt_u32 s60, 5
	s_mov_b64 s[44:45], s[2:3]
	s_cbranch_scc0 .LBB0_457
	s_and_b64 vcc, exec, s[36:37]
	s_cbranch_vccz .LBB0_460
	s_barrier

; #define PG8_STAGE(bufoff, gbase, voff) do { _Pragma("unroll") for (int _i = 0; _i < 2; ++_i) \
;         __builtin_amdgcn_global_load_lds((const unsigned*)((const char*)(gbase) + (voff)[_i]), (LAS unsigned*)(lds + (bufoff) + ldsw + _i * 8192), 16, 0, 0); } while (0)
; #define PG8_LDA(dst, b, h) do { _Pragma("unroll") for (int m = 0; m < 4; ++m) _Pragma("unroll") for (int k = 0; k < 2; ++k) dst[m][k] = *(const LAS bf16x8*)(lds + PG8_SA(b, h) + aoff + m * 2048 + k * 1024); } while (0)
; #define PG8_LDB(dst, b, h) do { _Pragma("unroll") for (int n = 0; n < 2; ++n) _Pragma("unroll") for (int k = 0; k < 2; ++k) dst[n][k] = *(const LAS bf16x8*)(lds + PG8_SB(b, h) + boff + n * 2048 + k * 1024); } while (0)
; #define PG8_MMA(ai, bj, At, Bt) do { __builtin_amdgcn_s_setprio(1); _Pragma("unroll") for (int m = 0; m < 4; ++m) _Pragma("unroll") for (int n = 0; n < 2; ++n) _Pragma("unroll") for (int k = 0; k < 2; ++k) \
;         acc[ai][bj][m][n] = __builtin_amdgcn_mfma_f32_16x16x32_bf16(Bt[n][k], At[m][k], acc[ai][bj][m][n], 0, 0, 0); __builtin_amdgcn_s_setprio(0); } while (0)
; #define PG8_WAIT_V(n) asm volatile("s_waitcnt vmcnt(" #n ")" ::: "memory")
; #define PG8_WAIT_L(n) asm volatile("s_waitcnt lgkmcnt(" #n ")" ::: "memory")
; #define PG8_BAR __builtin_amdgcn_s_barrier()
; #define PG8_SCHED __builtin_amdgcn_sched_barrier(0)
; template <class Epi>
; __device__ __forceinline__ void gemm_phase(LAS unsigned char* lds, const Gemm g, const TileOrder& S, const Epi& E) {
;     ...
;             const bool last = (t == nt - 2);
;             const char* a1 = cA + (size_t)(t + 1) * kstepA;
;             const char* a2 = last ? nA : cA + (size_t)(t + 2) * kstepA; const char* b2 = last ? nB : cB + (size_t)(t + 2) * kstep;
;             const char* a3 = a2 + kstepA; const char* b3 = b2 + kstep;
;             PG8_LDB(B0, 0, 0); PG8_LDB(B1, 0, 1); PG8_SCHED; PG8_LDA(At, 0, 0); PG8_STAGE(PG8_SA(1, 1), a1 + hstepA, voffA);
;             PG8_WAIT_V(8); PG8_WAIT_L(0); PG8_BAR; PG8_MMA(0, 0, At, B0); PG8_MMA(0, 1, At, B1); PG8_BAR; PG8_SCHED;
;             PG8_LDA(At, 0, 1); PG8_STAGE(PG8_SB(0, 0), b2, voffB); PG8_STAGE(PG8_SB(0, 1), b2 + hstepB, voffB); PG8_STAGE(PG8_SA(0, 0), a2, voffA);
.LBB0_596:
	s_mov_b32 s6, 0x10000
	s_mov_b32 s12, 0x14000
	v_add_u32_e32 v58, s6, v224
	v_add_u32_e32 v102, s12, v224
	ds_read_b128 v[42:45], v58
	ds_read_b128 v[46:49], v58 offset:1024
	ds_read_b128 v[50:53], v58 offset:2048
	ds_read_b128 v[58:61], v58 offset:3072
	ds_read_b128 v[74:77], v102
	ds_read_b128 v[82:85], v102 offset:1024
	ds_read_b128 v[94:97], v102 offset:2048
	ds_read_b128 v[102:105], v102 offset:3072
	ds_read_b128 v[114:117], v225
	ds_read_b128 v[126:129], v225 offset:1024
	ds_read_b128 v[138:141], v225 offset:2048
	ds_read_b128 v[150:153], v225 offset:3072
	ds_read_b128 v[162:165], v225 offset:4096
	ds_read_b128 v[174:177], v225 offset:5120
	ds_read_b128 v[186:189], v225 offset:6144
	ds_read_b128 v[190:193], v225 offset:7168
	s_add_u32 s2, s28, 0x100
	s_addc_u32 s3, s29, 0
	s_cmp_eq_u32 s62, 8
	s_cselect_b32 s47, s1, s3
	s_cselect_b32 s46, s0, s2
	s_cselect_b32 s31, s45, s61
	s_cselect_b32 s30, s44, s60
	s_add_i32 m0, s26, 0xc000
	s_nop 0
	global_load_lds_dwordx4 v214, s[28:29]
	s_add_i32 m0, s26, 0xe000
	s_nop 0
	global_load_lds_dwordx4 v216, s[28:29]
	s_waitcnt vmcnt(8)
	s_waitcnt lgkmcnt(0)
	s_barrier
	s_setprio 1
	s_waitcnt lgkmcnt(0)
	v_mfma_f32_16x16x32_bf16 v[182:185], v[42:45], v[114:117], v[182:185]
	v_mfma_f32_16x16x32_bf16 v[178:181], v[50:53], v[114:117], v[178:181]
	v_mfma_f32_16x16x32_bf16 v[158:161], v[42:45], v[138:141], v[158:161]
	v_mfma_f32_16x16x32_bf16 v[154:157], v[50:53], v[138:141], v[154:157]
	v_mfma_f32_16x16x32_bf16 v[134:137], v[42:45], v[162:165], v[134:137]
	v_mfma_f32_16x16x32_bf16 v[130:133], v[50:53], v[162:165], v[130:133]
	v_mfma_f32_16x16x32_bf16 v[110:113], v[42:45], v[186:189], v[110:113]
	v_mfma_f32_16x16x32_bf16 v[106:109], v[50:53], v[186:189], v[106:109]
	v_mfma_f32_16x16x32_bf16 v[182:185], v[46:49], v[126:129], v[182:185]
	v_mfma_f32_16x16x32_bf16 v[178:181], v[58:61], v[126:129], v[178:181]
	v_mfma_f32_16x16x32_bf16 v[158:161], v[46:49], v[150:153], v[158:161]
	v_mfma_f32_16x16x32_bf16 v[154:157], v[58:61], v[150:153], v[154:157]
	v_mfma_f32_16x16x32_bf16 v[134:137], v[46:49], v[174:177], v[134:137]
	v_mfma_f32_16x16x32_bf16 v[130:133], v[58:61], v[174:177], v[130:133]
	v_mfma_f32_16x16x32_bf16 v[110:113], v[46:49], v[190:193], v[110:113]
	v_mfma_f32_16x16x32_bf16 v[106:109], v[58:61], v[190:193], v[106:109]
	s_setprio 0
	s_setprio 1
	v_mfma_f32_16x16x32_bf16 v[170:173], v[74:77], v[114:117], v[170:173]
	v_mfma_f32_16x16x32_bf16 v[114:117], v[94:97], v[114:117], v[166:169]
	v_mfma_f32_16x16x32_bf16 v[122:125], v[74:77], v[162:165], v[122:125]
	v_mfma_f32_16x16x32_bf16 v[118:121], v[94:97], v[162:165], v[118:121]
	v_mfma_f32_16x16x32_bf16 v[98:101], v[74:77], v[186:189], v[98:101]
	v_mfma_f32_16x16x32_bf16 v[90:93], v[94:97], v[186:189], v[90:93]
	v_mfma_f32_16x16x32_bf16 v[170:173], v[82:85], v[126:129], v[170:173]
	v_mfma_f32_16x16x32_bf16 v[114:117], v[102:105], v[126:129], v[114:117]
	v_mfma_f32_16x16x32_bf16 v[126:129], v[74:77], v[138:141], v[146:149]
	v_mfma_f32_16x16x32_bf16 v[138:141], v[94:97], v[138:141], v[142:145]
	v_mfma_f32_16x16x32_bf16 v[122:125], v[82:85], v[174:177], v[122:125]
	v_mfma_f32_16x16x32_bf16 v[118:121], v[102:105], v[174:177], v[118:121]
	v_mfma_f32_16x16x32_bf16 v[98:101], v[82:85], v[190:193], v[98:101]
	v_mfma_f32_16x16x32_bf16 v[90:93], v[102:105], v[190:193], v[90:93]
	s_setprio 2
	s_barrier
	v_mfma_f32_16x16x32_bf16 v[126:129], v[82:85], v[150:153], v[126:129]
	v_mfma_f32_16x16x32_bf16 v[138:141], v[102:105], v[150:153], v[138:141]
	s_setprio 0
	s_add_i32 s6, s6, s25
	v_lshl_add_u64 v[198:199], s[30:31], 0, v[0:1]
	s_mov_b32 m0, s6
	ds_read_b128 v[142:145], v225 offset:16384
	ds_read_b128 v[146:149], v225 offset:17408
	ds_read_b128 v[150:153], v225 offset:18432
	ds_read_b128 v[162:165], v225 offset:19456
	ds_read_b128 v[166:169], v225 offset:20480
	ds_read_b128 v[174:177], v225 offset:21504
	ds_read_b128 v[186:189], v225 offset:22528
	ds_read_b128 v[190:193], v225 offset:23552
	global_load_lds_dwordx4 v[198:199], off
	s_add_i32 m0, s6, 0x2000
	s_add_u32 s14, s30, 0x30000
	v_lshl_add_u64 v[200:201], s[30:31], 0, v[208:209]
	s_addc_u32 s15, s31, 0
	s_add_i32 s6, s12, s25
	global_load_lds_dwordx4 v[200:201], off
	s_mov_b32 m0, s6
	v_lshl_add_u64 v[202:203], s[46:47], 0, v[212:213]
	global_load_lds_dwordx4 v0, s[14:15]
	v_lshl_add_u64 v[194:195], s[14:15], 0, v[208:209]
	s_add_i32 m0, s6, 0x2000
	v_lshl_add_u64 v[204:205], s[46:47], 0, v[210:211]
	global_load_lds_dwordx4 v[194:195], off
	s_mov_b32 m0, s26
	s_nop 0
	global_load_lds_dwordx4 v[202:203], off
	s_mov_b32 m0, s48
	s_nop 0
	global_load_lds_dwordx4 v[204:205], off
	s_waitcnt vmcnt(8)
	s_waitcnt lgkmcnt(0)
	s_barrier
; #define PG8_STAGE(bufoff, gbase, voff) do { _Pragma("unroll") for (int _i = 0; _i < 2; ++_i) \
;         __builtin_amdgcn_global_load_lds((const unsigned*)((const char*)(gbase) + (voff)[_i]), (LAS unsigned*)(lds + (bufoff) + ldsw + _i * 8192), 16, 0, 0); } while (0)
; #define PG8_LDA(dst, b, h) do { _Pragma("unroll") for (int m = 0; m < 4; ++m) _Pragma("unroll") for (int k = 0; k < 2; ++k) dst[m][k] = *(const LAS bf16x8*)(lds + PG8_SA(b, h) + aoff + m * 2048 + k * 1024); } while (0)
; #define PG8_LDB(dst, b, h) do { _Pragma("unroll") for (int n = 0; n < 2; ++n) _Pragma("unroll") for (int k = 0; k < 2; ++k) dst[n][k] = *(const LAS bf16x8*)(lds + PG8_SB(b, h) + boff + n * 2048 + k * 1024); } while (0)
; #define PG8_MMA(ai, bj, At, Bt) do { __builtin_amdgcn_s_setprio(1); _Pragma("unroll") for (int m = 0; m < 4; ++m) _Pragma("unroll") for (int n = 0; n < 2; ++n) _Pragma("unroll") for (int k = 0; k < 2; ++k) \
;         acc[ai][bj][m][n] = __builtin_amdgcn_mfma_f32_16x16x32_bf16(Bt[n][k], At[m][k], acc[ai][bj][m][n], 0, 0, 0); __builtin_amdgcn_s_setprio(0); } while (0)
; #define PG8_WAIT_V(n) asm volatile("s_waitcnt vmcnt(" #n ")" ::: "memory")
; #define PG8_WAIT_L(n) asm volatile("s_waitcnt lgkmcnt(" #n ")" ::: "memory")
; #define PG8_BAR __builtin_amdgcn_s_barrier()
; #define PG8_SCHED __builtin_amdgcn_sched_barrier(0)
; template <class Epi>
; __device__ __forceinline__ void gemm_phase(LAS unsigned char* lds, const Gemm g, const TileOrder& S, const Epi& E) {
;     ...
;             PG8_WAIT_V(8); PG8_WAIT_L(0); PG8_BAR; PG8_MMA(1, 0, At, B0); PG8_MMA(1, 1, At, B1); PG8_BAR; PG8_SCHED;
;             PG8_LDB(B0, 1, 0); PG8_LDB(B1, 1, 1); PG8_SCHED; PG8_LDA(At, 1, 0); PG8_STAGE(PG8_SA(0, 1), a2 + hstepA, voffA);
;             PG8_WAIT_V(8); PG8_WAIT_L(0); PG8_BAR; PG8_MMA(0, 0, At, B0); PG8_MMA(0, 1, At, B1); PG8_BAR; PG8_SCHED;
	s_setprio 1
	s_waitcnt lgkmcnt(0)
	v_mfma_f32_16x16x32_bf16 v[86:89], v[42:45], v[142:145], v[86:89]
	v_mfma_f32_16x16x32_bf16 v[78:81], v[50:53], v[142:145], v[78:81]
	v_mfma_f32_16x16x32_bf16 v[62:65], v[42:45], v[150:153], v[62:65]
	v_mfma_f32_16x16x32_bf16 v[54:57], v[50:53], v[150:153], v[54:57]
	v_mfma_f32_16x16x32_bf16 v[30:33], v[42:45], v[166:169], v[30:33]
	v_mfma_f32_16x16x32_bf16 v[26:29], v[50:53], v[166:169], v[26:29]
	v_mfma_f32_16x16x32_bf16 v[14:17], v[42:45], v[186:189], v[14:17]
	v_mfma_f32_16x16x32_bf16 v[10:13], v[50:53], v[186:189], v[10:13]
	v_mfma_f32_16x16x32_bf16 v[86:89], v[46:49], v[146:149], v[86:89]
	v_mfma_f32_16x16x32_bf16 v[78:81], v[58:61], v[146:149], v[78:81]
	v_mfma_f32_16x16x32_bf16 v[62:65], v[46:49], v[162:165], v[62:65]
	v_mfma_f32_16x16x32_bf16 v[54:57], v[58:61], v[162:165], v[54:57]
	v_mfma_f32_16x16x32_bf16 v[30:33], v[46:49], v[174:177], v[30:33]
	v_mfma_f32_16x16x32_bf16 v[26:29], v[58:61], v[174:177], v[26:29]
	v_mfma_f32_16x16x32_bf16 v[14:17], v[46:49], v[190:193], v[14:17]
	v_mfma_f32_16x16x32_bf16 v[10:13], v[58:61], v[190:193], v[10:13]
	s_setprio 0
	s_setprio 1
	v_mfma_f32_16x16x32_bf16 v[38:41], v[74:77], v[150:153], v[38:41]
	v_mfma_f32_16x16x32_bf16 v[34:37], v[94:97], v[150:153], v[34:37]
	v_mfma_f32_16x16x32_bf16 v[22:25], v[74:77], v[166:169], v[22:25]
	v_mfma_f32_16x16x32_bf16 v[18:21], v[94:97], v[166:169], v[18:21]
	v_mfma_f32_16x16x32_bf16 v[6:9], v[74:77], v[186:189], v[6:9]
	v_mfma_f32_16x16x32_bf16 v[2:5], v[94:97], v[186:189], v[2:5]
	v_mfma_f32_16x16x32_bf16 v[42:45], v[74:77], v[142:145], v[70:73]
	v_mfma_f32_16x16x32_bf16 v[46:49], v[94:97], v[142:145], v[66:69]
	v_mfma_f32_16x16x32_bf16 v[38:41], v[82:85], v[162:165], v[38:41]
	v_mfma_f32_16x16x32_bf16 v[34:37], v[102:105], v[162:165], v[34:37]
	v_mfma_f32_16x16x32_bf16 v[22:25], v[82:85], v[174:177], v[22:25]
	v_mfma_f32_16x16x32_bf16 v[18:21], v[102:105], v[174:177], v[18:21]
	v_mfma_f32_16x16x32_bf16 v[6:9], v[82:85], v[190:193], v[6:9]
	v_mfma_f32_16x16x32_bf16 v[2:5], v[102:105], v[190:193], v[2:5]
	s_setprio 2
	s_barrier
	v_mfma_f32_16x16x32_bf16 v[42:45], v[82:85], v[146:149], v[42:45]
	v_mfma_f32_16x16x32_bf16 v[46:49], v[102:105], v[146:149], v[46:49]
	s_setprio 0
	s_add_i32 s6, 0, 0x18000
	s_add_i32 s12, 0, 0x1c000
	v_add_u32_e32 v70, s6, v224
	v_add_u32_e32 v102, s12, v224
	ds_read_b128 v[50:53], v70
	ds_read_b128 v[58:61], v70 offset:1024
	ds_read_b128 v[66:69], v70 offset:2048
	ds_read_b128 v[70:73], v70 offset:3072
	ds_read_b128 v[74:77], v102
	ds_read_b128 v[82:85], v102 offset:1024
	ds_read_b128 v[94:97], v102 offset:2048
	ds_read_b128 v[102:105], v102 offset:3072
	s_add_u32 s14, s46, 0x30000
	s_addc_u32 s15, s47, 0
	s_mov_b32 m0, s49
	ds_read_b128 v[142:145], v225 offset:32768
	ds_read_b128 v[146:149], v225 offset:33792
	ds_read_b128 v[150:153], v225 offset:34816
	ds_read_b128 v[162:165], v225 offset:35840
	ds_read_b128 v[174:177], v225 offset:36864
	ds_read_b128 v[186:189], v225 offset:37888
	ds_read_b128 v[190:193], v225 offset:38912
	ds_read_b128 v[194:197], v225 offset:39936
	global_load_lds_dwordx4 v212, s[14:15]
	s_mov_b32 m0, s50
	s_nop 0
	global_load_lds_dwordx4 v210, s[14:15]
	s_waitcnt vmcnt(8)
	s_waitcnt lgkmcnt(0)
	s_barrier
	s_setprio 1
	s_waitcnt lgkmcnt(0)
	v_mfma_f32_16x16x32_bf16 v[166:169], v[50:53], v[142:145], v[182:185]
	v_mfma_f32_16x16x32_bf16 v[182:185], v[58:61], v[146:149], v[166:169]
	v_mfma_f32_16x16x32_bf16 v[166:169], v[66:69], v[142:145], v[178:181]
	v_mfma_f32_16x16x32_bf16 v[158:161], v[50:53], v[150:153], v[158:161]
	v_mfma_f32_16x16x32_bf16 v[154:157], v[66:69], v[150:153], v[154:157]
	v_mfma_f32_16x16x32_bf16 v[134:137], v[50:53], v[174:177], v[134:137]
	v_mfma_f32_16x16x32_bf16 v[130:133], v[66:69], v[174:177], v[130:133]
	v_mfma_f32_16x16x32_bf16 v[110:113], v[50:53], v[190:193], v[110:113]
	v_mfma_f32_16x16x32_bf16 v[106:109], v[66:69], v[190:193], v[106:109]
	v_mfma_f32_16x16x32_bf16 v[178:181], v[70:73], v[146:149], v[166:169]
	v_mfma_f32_16x16x32_bf16 v[158:161], v[58:61], v[162:165], v[158:161]
	v_mfma_f32_16x16x32_bf16 v[154:157], v[70:73], v[162:165], v[154:157]
	v_mfma_f32_16x16x32_bf16 v[134:137], v[58:61], v[186:189], v[134:137]
	v_mfma_f32_16x16x32_bf16 v[130:133], v[70:73], v[186:189], v[130:133]
	v_mfma_f32_16x16x32_bf16 v[110:113], v[58:61], v[194:197], v[110:113]
	v_mfma_f32_16x16x32_bf16 v[106:109], v[70:73], v[194:197], v[106:109]
	s_setprio 0
	s_setprio 1
	v_mfma_f32_16x16x32_bf16 v[166:169], v[74:77], v[142:145], v[170:173]
	v_mfma_f32_16x16x32_bf16 v[114:117], v[94:97], v[142:145], v[114:117]
	v_mfma_f32_16x16x32_bf16 v[170:173], v[82:85], v[146:149], v[166:169]
	v_mfma_f32_16x16x32_bf16 v[166:169], v[102:105], v[146:149], v[114:117]
	v_mfma_f32_16x16x32_bf16 v[114:117], v[74:77], v[150:153], v[126:129]
	v_mfma_f32_16x16x32_bf16 v[146:149], v[82:85], v[162:165], v[114:117]
	v_mfma_f32_16x16x32_bf16 v[114:117], v[94:97], v[150:153], v[138:141]
	v_mfma_f32_16x16x32_bf16 v[142:145], v[102:105], v[162:165], v[114:117]
	v_mfma_f32_16x16x32_bf16 v[114:117], v[74:77], v[174:177], v[122:125]
	v_mfma_f32_16x16x32_bf16 v[122:125], v[82:85], v[186:189], v[114:117]
	v_mfma_f32_16x16x32_bf16 v[114:117], v[94:97], v[174:177], v[118:121]
	v_mfma_f32_16x16x32_bf16 v[98:101], v[74:77], v[190:193], v[98:101]
	v_mfma_f32_16x16x32_bf16 v[90:93], v[94:97], v[190:193], v[90:93]
	v_mfma_f32_16x16x32_bf16 v[118:121], v[102:105], v[186:189], v[114:117]
	s_setprio 2
	s_barrier
; #define PG8_STAGE(bufoff, gbase, voff) do { _Pragma("unroll") for (int _i = 0; _i < 2; ++_i) \
;         __builtin_amdgcn_global_load_lds((const unsigned*)((const char*)(gbase) + (voff)[_i]), (LAS unsigned*)(lds + (bufoff) + ldsw + _i * 8192), 16, 0, 0); } while (0)
; #define PG8_LDA(dst, b, h) do { _Pragma("unroll") for (int m = 0; m < 4; ++m) _Pragma("unroll") for (int k = 0; k < 2; ++k) dst[m][k] = *(const LAS bf16x8*)(lds + PG8_SA(b, h) + aoff + m * 2048 + k * 1024); } while (0)
; #define PG8_MMA(ai, bj, At, Bt) do { __builtin_amdgcn_s_setprio(1); _Pragma("unroll") for (int m = 0; m < 4; ++m) _Pragma("unroll") for (int n = 0; n < 2; ++n) _Pragma("unroll") for (int k = 0; k < 2; ++k) \
;         acc[ai][bj][m][n] = __builtin_amdgcn_mfma_f32_16x16x32_bf16(Bt[n][k], At[m][k], acc[ai][bj][m][n], 0, 0, 0); __builtin_amdgcn_s_setprio(0); } while (0)
; #define PG8_WAIT_V(n) asm volatile("s_waitcnt vmcnt(" #n ")" ::: "memory")
; #define PG8_WAIT_L(n) asm volatile("s_waitcnt lgkmcnt(" #n ")" ::: "memory")
; #define PG8_BAR __builtin_amdgcn_s_barrier()
; #define PG8_SCHED __builtin_amdgcn_sched_barrier(0)
; template <class Epi>
; __device__ __forceinline__ void gemm_phase(LAS unsigned char* lds, const Gemm g, const TileOrder& S, const Epi& E) {
;     ...
;             PG8_WAIT_V(8); PG8_WAIT_L(0); PG8_BAR; PG8_MMA(0, 0, At, B0); PG8_MMA(0, 1, At, B1); PG8_BAR; PG8_SCHED;
;             PG8_LDA(At, 1, 1); PG8_STAGE(PG8_SB(1, 0), b3, voffB); PG8_STAGE(PG8_SB(1, 1), b3 + hstepB, voffB); PG8_STAGE(PG8_SA(1, 0), a3, voffA);
;             PG8_WAIT_V(8); PG8_WAIT_L(0); PG8_BAR; PG8_MMA(1, 0, At, B0); PG8_MMA(1, 1, At, B1); PG8_BAR; PG8_SCHED;
;         }
;         if (wr == 0) PG8_BAR;
	v_mfma_f32_16x16x32_bf16 v[98:101], v[82:85], v[194:197], v[98:101]
	v_mfma_f32_16x16x32_bf16 v[90:93], v[102:105], v[194:197], v[90:93]
	s_setprio 0
	s_add_i32 s6, s6, s25
	v_lshl_add_u64 v[194:195], v[198:199], 0, s[34:35]
	s_mov_b32 m0, s6
	ds_read_b128 v[114:117], v225 offset:49152
	ds_read_b128 v[126:129], v225 offset:50176
	ds_read_b128 v[138:141], v225 offset:51200
	ds_read_b128 v[150:153], v225 offset:52224
	ds_read_b128 v[162:165], v225 offset:53248
	ds_read_b128 v[174:177], v225 offset:54272
	ds_read_b128 v[186:189], v225 offset:55296
	ds_read_b128 v[190:193], v225 offset:56320
	global_load_lds_dwordx4 v[194:195], off
	s_add_i32 m0, s6, 0x2000
	s_add_u32 s14, s30, 0x30080
	v_lshl_add_u64 v[194:195], v[200:201], 0, s[34:35]
	s_addc_u32 s15, s31, 0
	s_add_i32 s6, s12, s25
	global_load_lds_dwordx4 v[194:195], off
	s_mov_b32 m0, s6
	s_nop 0
	global_load_lds_dwordx4 v0, s[14:15]
	v_lshl_add_u64 v[194:195], s[14:15], 0, v[208:209]
	s_add_i32 m0, s6, 0x2000
	s_nop 0
	global_load_lds_dwordx4 v[194:195], off
	v_lshl_add_u64 v[194:195], v[202:203], 0, s[34:35]
	s_mov_b32 m0, s51
	s_nop 0
	global_load_lds_dwordx4 v[194:195], off
	v_lshl_add_u64 v[194:195], v[204:205], 0, s[34:35]
	s_mov_b32 m0, s52
	s_nop 0
	global_load_lds_dwordx4 v[194:195], off
	s_waitcnt vmcnt(8)
	s_waitcnt lgkmcnt(0)
	s_barrier
	s_setprio 1
	s_waitcnt lgkmcnt(0)
	v_mfma_f32_16x16x32_bf16 v[86:89], v[50:53], v[114:117], v[86:89]
	v_mfma_f32_16x16x32_bf16 v[78:81], v[66:69], v[114:117], v[78:81]
	v_mfma_f32_16x16x32_bf16 v[62:65], v[50:53], v[138:141], v[62:65]
	v_mfma_f32_16x16x32_bf16 v[54:57], v[66:69], v[138:141], v[54:57]
	v_mfma_f32_16x16x32_bf16 v[30:33], v[50:53], v[162:165], v[30:33]
	v_mfma_f32_16x16x32_bf16 v[26:29], v[66:69], v[162:165], v[26:29]
	v_mfma_f32_16x16x32_bf16 v[14:17], v[50:53], v[186:189], v[14:17]
	v_mfma_f32_16x16x32_bf16 v[10:13], v[66:69], v[186:189], v[10:13]
	v_mfma_f32_16x16x32_bf16 v[86:89], v[58:61], v[126:129], v[86:89]
	v_mfma_f32_16x16x32_bf16 v[78:81], v[70:73], v[126:129], v[78:81]
	v_mfma_f32_16x16x32_bf16 v[62:65], v[58:61], v[150:153], v[62:65]
	v_mfma_f32_16x16x32_bf16 v[54:57], v[70:73], v[150:153], v[54:57]
	v_mfma_f32_16x16x32_bf16 v[30:33], v[58:61], v[174:177], v[30:33]
	v_mfma_f32_16x16x32_bf16 v[26:29], v[70:73], v[174:177], v[26:29]
	v_mfma_f32_16x16x32_bf16 v[14:17], v[58:61], v[190:193], v[14:17]
	v_mfma_f32_16x16x32_bf16 v[10:13], v[70:73], v[190:193], v[10:13]
	s_setprio 0
	s_setprio 1
	v_mfma_f32_16x16x32_bf16 v[42:45], v[74:77], v[114:117], v[42:45]
	v_mfma_f32_16x16x32_bf16 v[70:73], v[82:85], v[126:129], v[42:45]
	v_mfma_f32_16x16x32_bf16 v[42:45], v[94:97], v[114:117], v[46:49]
	v_mfma_f32_16x16x32_bf16 v[38:41], v[74:77], v[138:141], v[38:41]
	v_mfma_f32_16x16x32_bf16 v[34:37], v[94:97], v[138:141], v[34:37]
	v_mfma_f32_16x16x32_bf16 v[22:25], v[74:77], v[162:165], v[22:25]
	v_mfma_f32_16x16x32_bf16 v[18:21], v[94:97], v[162:165], v[18:21]
	v_mfma_f32_16x16x32_bf16 v[6:9], v[74:77], v[186:189], v[6:9]
	v_mfma_f32_16x16x32_bf16 v[2:5], v[94:97], v[186:189], v[2:5]
	v_mfma_f32_16x16x32_bf16 v[66:69], v[102:105], v[126:129], v[42:45]
	v_mfma_f32_16x16x32_bf16 v[38:41], v[82:85], v[150:153], v[38:41]
	v_mfma_f32_16x16x32_bf16 v[34:37], v[102:105], v[150:153], v[34:37]
	v_mfma_f32_16x16x32_bf16 v[22:25], v[82:85], v[174:177], v[22:25]
	v_mfma_f32_16x16x32_bf16 v[18:21], v[102:105], v[174:177], v[18:21]
	s_setprio 2
	s_barrier
	v_mfma_f32_16x16x32_bf16 v[6:9], v[82:85], v[190:193], v[6:9]
	v_mfma_f32_16x16x32_bf16 v[2:5], v[102:105], v[190:193], v[2:5]
	s_setprio 0
	s_add_i32 s62, s62, 2
	s_add_u32 s60, s60, 0x100
	s_addc_u32 s61, s61, 0
	s_cmp_gt_u32 s62, 9
	s_mov_b64 s[28:29], s[2:3]
	s_cbranch_scc0 .LBB0_596
	s_and_b64 vcc, exec, s[42:43]
	s_cbranch_vccz .LBB0_599
	s_barrier

; #define PG8_STAGE(bufoff, gbase, voff) do { _Pragma("unroll") for (int _i = 0; _i < 2; ++_i) \
;         __builtin_amdgcn_global_load_lds((const unsigned*)((const char*)(gbase) + (voff)[_i]), (LAS unsigned*)(lds + (bufoff) + ldsw + _i * 8192), 16, 0, 0); } while (0)
; #define PG8_LDA(dst, b, h) do { _Pragma("unroll") for (int m = 0; m < 4; ++m) _Pragma("unroll") for (int k = 0; k < 2; ++k) dst[m][k] = *(const LAS bf16x8*)(lds + PG8_SA(b, h) + aoff + m * 2048 + k * 1024); } while (0)
; #define PG8_LDB(dst, b, h) do { _Pragma("unroll") for (int n = 0; n < 2; ++n) _Pragma("unroll") for (int k = 0; k < 2; ++k) dst[n][k] = *(const LAS bf16x8*)(lds + PG8_SB(b, h) + boff + n * 2048 + k * 1024); } while (0)
; #define PG8_MMA(ai, bj, At, Bt) do { __builtin_amdgcn_s_setprio(1); _Pragma("unroll") for (int m = 0; m < 4; ++m) _Pragma("unroll") for (int n = 0; n < 2; ++n) _Pragma("unroll") for (int k = 0; k < 2; ++k) \
;         acc[ai][bj][m][n] = __builtin_amdgcn_mfma_f32_16x16x32_bf16(Bt[n][k], At[m][k], acc[ai][bj][m][n], 0, 0, 0); __builtin_amdgcn_s_setprio(0); } while (0)
; #define PG8_WAIT_V(n) asm volatile("s_waitcnt vmcnt(" #n ")" ::: "memory")
; #define PG8_WAIT_L(n) asm volatile("s_waitcnt lgkmcnt(" #n ")" ::: "memory")
; #define PG8_BAR __builtin_amdgcn_s_barrier()
; #define PG8_SCHED __builtin_amdgcn_sched_barrier(0)
; template <class Epi>
; __device__ __forceinline__ void gemm_phase(LAS unsigned char* lds, const Gemm g, const TileOrder& S, const Epi& E) {
;     ...
;             const bool last = (t == nt - 2);
;             const char* a1 = cA + (size_t)(t + 1) * kstepA;
;             const char* a2 = last ? nA : cA + (size_t)(t + 2) * kstepA; const char* b2 = last ? nB : cB + (size_t)(t + 2) * kstep;
;             const char* a3 = a2 + kstepA; const char* b3 = b2 + kstep;
;             PG8_LDB(B0, 0, 0); PG8_LDB(B1, 0, 1); PG8_SCHED; PG8_LDA(At, 0, 0); PG8_STAGE(PG8_SA(1, 1), a1 + hstepA, voffA);
;             PG8_WAIT_V(8); PG8_WAIT_L(0); PG8_BAR; PG8_MMA(0, 0, At, B0); PG8_MMA(0, 1, At, B1); PG8_BAR; PG8_SCHED;
;             PG8_LDA(At, 0, 1); PG8_STAGE(PG8_SB(0, 0), b2, voffB); PG8_STAGE(PG8_SB(0, 1), b2 + hstepB, voffB); PG8_STAGE(PG8_SA(0, 0), a2, voffA);
.LBB0_668:
	s_mov_b32 s6, 0x10000
	s_mov_b32 s12, 0x14000
	v_add_u32_e32 v142, s6, v184
	v_add_u32_e32 v168, s12, v184
	ds_read_b128 v[130:133], v142
	ds_read_b128 v[134:137], v142 offset:1024
	ds_read_b128 v[138:141], v142 offset:2048
	ds_read_b128 v[142:145], v142 offset:3072
	ds_read_b128 v[146:149], v168
	ds_read_b128 v[150:153], v168 offset:1024
	ds_read_b128 v[164:167], v168 offset:2048
	ds_read_b128 v[168:171], v168 offset:3072
	ds_read_b128 v[172:175], v185
	ds_read_b128 v[176:179], v185 offset:1024
	ds_read_b128 v[186:189], v185 offset:2048
	ds_read_b128 v[190:193], v185 offset:3072
	ds_read_b128 v[194:197], v185 offset:4096
	ds_read_b128 v[198:201], v185 offset:5120
	ds_read_b128 v[202:205], v185 offset:6144
	ds_read_b128 v[206:209], v185 offset:7168
	s_add_u32 s2, s4, 0xfff80080
	s_addc_u32 s3, s5, -1
	s_cmp_eq_u32 s66, 28
	s_cselect_b32 s29, s45, s3
	s_cselect_b32 s28, s62, s2
	s_cselect_b32 s3, s43, s65
	s_cselect_b32 s2, s63, s64
	s_add_i32 m0, s50, 0xc000
	s_nop 0
	global_load_lds_dwordx4 v160, s[4:5]
	s_add_i32 m0, s50, 0xe000
	s_nop 0
	global_load_lds_dwordx4 v162, s[4:5]
	s_waitcnt vmcnt(8)
	s_waitcnt lgkmcnt(0)
	s_barrier
	s_setprio 1
	s_waitcnt lgkmcnt(0)
	v_mfma_f32_16x16x32_bf16 v[122:125], v[130:133], v[172:175], v[122:125]
	v_mfma_f32_16x16x32_bf16 v[118:121], v[138:141], v[172:175], v[118:121]
	v_mfma_f32_16x16x32_bf16 v[110:113], v[130:133], v[186:189], v[110:113]
	v_mfma_f32_16x16x32_bf16 v[102:105], v[138:141], v[186:189], v[102:105]
	v_mfma_f32_16x16x32_bf16 v[94:97], v[130:133], v[194:197], v[94:97]
	v_mfma_f32_16x16x32_bf16 v[86:89], v[138:141], v[194:197], v[86:89]
	v_mfma_f32_16x16x32_bf16 v[78:81], v[130:133], v[202:205], v[78:81]
	v_mfma_f32_16x16x32_bf16 v[70:73], v[138:141], v[202:205], v[70:73]
	v_mfma_f32_16x16x32_bf16 v[122:125], v[134:137], v[176:179], v[122:125]
	v_mfma_f32_16x16x32_bf16 v[118:121], v[142:145], v[176:179], v[118:121]
	v_mfma_f32_16x16x32_bf16 v[110:113], v[134:137], v[190:193], v[110:113]
	v_mfma_f32_16x16x32_bf16 v[102:105], v[142:145], v[190:193], v[102:105]
	v_mfma_f32_16x16x32_bf16 v[94:97], v[134:137], v[198:201], v[94:97]
	v_mfma_f32_16x16x32_bf16 v[86:89], v[142:145], v[198:201], v[86:89]
	v_mfma_f32_16x16x32_bf16 v[78:81], v[134:137], v[206:209], v[78:81]
	v_mfma_f32_16x16x32_bf16 v[70:73], v[142:145], v[206:209], v[70:73]
	s_setprio 0
	s_setprio 1
	v_mfma_f32_16x16x32_bf16 v[114:117], v[146:149], v[172:175], v[114:117]
	v_mfma_f32_16x16x32_bf16 v[126:129], v[164:167], v[172:175], v[126:129]
	v_mfma_f32_16x16x32_bf16 v[106:109], v[146:149], v[186:189], v[106:109]
	v_mfma_f32_16x16x32_bf16 v[98:101], v[164:167], v[186:189], v[98:101]
	v_mfma_f32_16x16x32_bf16 v[90:93], v[146:149], v[194:197], v[90:93]
	v_mfma_f32_16x16x32_bf16 v[82:85], v[164:167], v[194:197], v[82:85]
	v_mfma_f32_16x16x32_bf16 v[74:77], v[146:149], v[202:205], v[74:77]
	v_mfma_f32_16x16x32_bf16 v[66:69], v[164:167], v[202:205], v[66:69]
	v_mfma_f32_16x16x32_bf16 v[114:117], v[150:153], v[176:179], v[114:117]
	v_mfma_f32_16x16x32_bf16 v[126:129], v[168:171], v[176:179], v[126:129]
	v_mfma_f32_16x16x32_bf16 v[106:109], v[150:153], v[190:193], v[106:109]
	v_mfma_f32_16x16x32_bf16 v[98:101], v[168:171], v[190:193], v[98:101]
	v_mfma_f32_16x16x32_bf16 v[90:93], v[150:153], v[198:201], v[90:93]
	v_mfma_f32_16x16x32_bf16 v[82:85], v[168:171], v[198:201], v[82:85]
	s_setprio 2
	s_barrier
	v_mfma_f32_16x16x32_bf16 v[74:77], v[150:153], v[206:209], v[74:77]
	v_mfma_f32_16x16x32_bf16 v[66:69], v[168:171], v[206:209], v[66:69]
	s_setprio 0
	s_add_i32 s6, s6, s31
	v_lshl_add_u64 v[180:181], s[2:3], 0, v[0:1]
	s_mov_b32 m0, s6
	ds_read_b128 v[172:175], v185 offset:16384
	ds_read_b128 v[176:179], v185 offset:17408
	ds_read_b128 v[186:189], v185 offset:18432
	ds_read_b128 v[190:193], v185 offset:19456
	ds_read_b128 v[194:197], v185 offset:20480
	ds_read_b128 v[198:201], v185 offset:21504
	ds_read_b128 v[202:205], v185 offset:22528
	ds_read_b128 v[206:209], v185 offset:23552
	global_load_lds_dwordx4 v[180:181], off
	s_add_i32 m0, s6, 0x2000
	s_add_u32 s14, s2, 0x80000
	v_lshl_add_u64 v[210:211], s[2:3], 0, v[154:155]
	s_addc_u32 s15, s3, 0
	s_add_i32 s6, s12, s31
	global_load_lds_dwordx4 v[210:211], off
	s_mov_b32 m0, s6
	v_lshl_add_u64 v[214:215], s[28:29], 0, v[156:157]
	global_load_lds_dwordx4 v0, s[14:15]
	s_add_i32 m0, s6, 0x2000
	s_nop 0
	global_load_lds_dwordx4 v154, s[14:15]
	v_lshl_add_u64 v[212:213], s[28:29], 0, v[158:159]
	s_mov_b32 m0, s50
	s_nop 0
	global_load_lds_dwordx4 v[212:213], off
	s_mov_b32 m0, s51
	s_nop 0
	global_load_lds_dwordx4 v[214:215], off
	s_waitcnt vmcnt(8)
	s_waitcnt lgkmcnt(0)
	s_barrier
; #define PG8_STAGE(bufoff, gbase, voff) do { _Pragma("unroll") for (int _i = 0; _i < 2; ++_i) \
;         __builtin_amdgcn_global_load_lds((const unsigned*)((const char*)(gbase) + (voff)[_i]), (LAS unsigned*)(lds + (bufoff) + ldsw + _i * 8192), 16, 0, 0); } while (0)
; #define PG8_LDA(dst, b, h) do { _Pragma("unroll") for (int m = 0; m < 4; ++m) _Pragma("unroll") for (int k = 0; k < 2; ++k) dst[m][k] = *(const LAS bf16x8*)(lds + PG8_SA(b, h) + aoff + m * 2048 + k * 1024); } while (0)
; #define PG8_LDB(dst, b, h) do { _Pragma("unroll") for (int n = 0; n < 2; ++n) _Pragma("unroll") for (int k = 0; k < 2; ++k) dst[n][k] = *(const LAS bf16x8*)(lds + PG8_SB(b, h) + boff + n * 2048 + k * 1024); } while (0)
; #define PG8_MMA(ai, bj, At, Bt) do { __builtin_amdgcn_s_setprio(1); _Pragma("unroll") for (int m = 0; m < 4; ++m) _Pragma("unroll") for (int n = 0; n < 2; ++n) _Pragma("unroll") for (int k = 0; k < 2; ++k) \
;         acc[ai][bj][m][n] = __builtin_amdgcn_mfma_f32_16x16x32_bf16(Bt[n][k], At[m][k], acc[ai][bj][m][n], 0, 0, 0); __builtin_amdgcn_s_setprio(0); } while (0)
; #define PG8_WAIT_V(n) asm volatile("s_waitcnt vmcnt(" #n ")" ::: "memory")
; #define PG8_WAIT_L(n) asm volatile("s_waitcnt lgkmcnt(" #n ")" ::: "memory")
; #define PG8_BAR __builtin_amdgcn_s_barrier()
; #define PG8_SCHED __builtin_amdgcn_sched_barrier(0)
; template <class Epi>
; __device__ __forceinline__ void gemm_phase(LAS unsigned char* lds, const Gemm g, const TileOrder& S, const Epi& E) {
;     ...
;             PG8_WAIT_V(8); PG8_WAIT_L(0); PG8_BAR; PG8_MMA(1, 0, At, B0); PG8_MMA(1, 1, At, B1); PG8_BAR; PG8_SCHED;
;             PG8_LDB(B0, 1, 0); PG8_LDB(B1, 1, 1); PG8_SCHED; PG8_LDA(At, 1, 0); PG8_STAGE(PG8_SA(0, 1), a2 + hstepA, voffA);
;             PG8_WAIT_V(8); PG8_WAIT_L(0); PG8_BAR; PG8_MMA(0, 0, At, B0); PG8_MMA(0, 1, At, B1); PG8_BAR; PG8_SCHED;
	s_setprio 1
	s_waitcnt lgkmcnt(0)
	v_mfma_f32_16x16x32_bf16 v[62:65], v[130:133], v[172:175], v[62:65]
	v_mfma_f32_16x16x32_bf16 v[54:57], v[138:141], v[172:175], v[54:57]
	v_mfma_f32_16x16x32_bf16 v[46:49], v[130:133], v[186:189], v[46:49]
	v_mfma_f32_16x16x32_bf16 v[38:41], v[138:141], v[186:189], v[38:41]
	v_mfma_f32_16x16x32_bf16 v[30:33], v[130:133], v[194:197], v[30:33]
	v_mfma_f32_16x16x32_bf16 v[22:25], v[138:141], v[194:197], v[22:25]
	v_mfma_f32_16x16x32_bf16 v[14:17], v[130:133], v[202:205], v[14:17]
	v_mfma_f32_16x16x32_bf16 v[6:9], v[138:141], v[202:205], v[6:9]
	v_mfma_f32_16x16x32_bf16 v[62:65], v[134:137], v[176:179], v[62:65]
	v_mfma_f32_16x16x32_bf16 v[54:57], v[142:145], v[176:179], v[54:57]
	v_mfma_f32_16x16x32_bf16 v[46:49], v[134:137], v[190:193], v[46:49]
	v_mfma_f32_16x16x32_bf16 v[38:41], v[142:145], v[190:193], v[38:41]
	v_mfma_f32_16x16x32_bf16 v[30:33], v[134:137], v[198:201], v[30:33]
	v_mfma_f32_16x16x32_bf16 v[22:25], v[142:145], v[198:201], v[22:25]
	v_mfma_f32_16x16x32_bf16 v[14:17], v[134:137], v[206:209], v[14:17]
	v_mfma_f32_16x16x32_bf16 v[6:9], v[142:145], v[206:209], v[6:9]
	s_setprio 0
	s_setprio 1
	v_mfma_f32_16x16x32_bf16 v[58:61], v[146:149], v[172:175], v[58:61]
	v_mfma_f32_16x16x32_bf16 v[50:53], v[164:167], v[172:175], v[50:53]
	v_mfma_f32_16x16x32_bf16 v[42:45], v[146:149], v[186:189], v[42:45]
	v_mfma_f32_16x16x32_bf16 v[34:37], v[164:167], v[186:189], v[34:37]
	v_mfma_f32_16x16x32_bf16 v[26:29], v[146:149], v[194:197], v[26:29]
	v_mfma_f32_16x16x32_bf16 v[18:21], v[164:167], v[194:197], v[18:21]
	v_mfma_f32_16x16x32_bf16 v[10:13], v[146:149], v[202:205], v[10:13]
	v_mfma_f32_16x16x32_bf16 v[2:5], v[164:167], v[202:205], v[2:5]
	v_mfma_f32_16x16x32_bf16 v[58:61], v[150:153], v[176:179], v[58:61]
	v_mfma_f32_16x16x32_bf16 v[50:53], v[168:171], v[176:179], v[50:53]
	v_mfma_f32_16x16x32_bf16 v[42:45], v[150:153], v[190:193], v[42:45]
	v_mfma_f32_16x16x32_bf16 v[34:37], v[168:171], v[190:193], v[34:37]
	v_mfma_f32_16x16x32_bf16 v[26:29], v[150:153], v[198:201], v[26:29]
	v_mfma_f32_16x16x32_bf16 v[18:21], v[168:171], v[198:201], v[18:21]
	s_setprio 2
	s_barrier
	v_mfma_f32_16x16x32_bf16 v[10:13], v[150:153], v[206:209], v[10:13]
	v_mfma_f32_16x16x32_bf16 v[2:5], v[168:171], v[206:209], v[2:5]
	s_setprio 0
	s_add_i32 s6, 0, 0x18000
	s_add_i32 s12, 0, 0x1c000
	v_add_u32_e32 v142, s6, v184
	v_add_u32_e32 v168, s12, v184
	ds_read_b128 v[130:133], v142
	ds_read_b128 v[134:137], v142 offset:1024
	ds_read_b128 v[138:141], v142 offset:2048
	ds_read_b128 v[142:145], v142 offset:3072
	ds_read_b128 v[146:149], v168
	ds_read_b128 v[150:153], v168 offset:1024
	ds_read_b128 v[164:167], v168 offset:2048
	ds_read_b128 v[168:171], v168 offset:3072
	s_add_u32 s14, s28, 0x80000
	s_addc_u32 s15, s29, 0
	s_mov_b32 m0, s52
	ds_read_b128 v[172:175], v185 offset:32768
	ds_read_b128 v[176:179], v185 offset:33792
	ds_read_b128 v[186:189], v185 offset:34816
	ds_read_b128 v[190:193], v185 offset:35840
	ds_read_b128 v[194:197], v185 offset:36864
	ds_read_b128 v[198:201], v185 offset:37888
	ds_read_b128 v[202:205], v185 offset:38912
	ds_read_b128 v[206:209], v185 offset:39936
	global_load_lds_dwordx4 v158, s[14:15]
	s_mov_b32 m0, s53
	s_nop 0
	global_load_lds_dwordx4 v156, s[14:15]
	s_waitcnt vmcnt(8)
	s_waitcnt lgkmcnt(0)
	s_barrier
	s_setprio 1
	s_waitcnt lgkmcnt(0)
	v_mfma_f32_16x16x32_bf16 v[122:125], v[130:133], v[172:175], v[122:125]
	v_mfma_f32_16x16x32_bf16 v[118:121], v[138:141], v[172:175], v[118:121]
	v_mfma_f32_16x16x32_bf16 v[110:113], v[130:133], v[186:189], v[110:113]
	v_mfma_f32_16x16x32_bf16 v[102:105], v[138:141], v[186:189], v[102:105]
	v_mfma_f32_16x16x32_bf16 v[94:97], v[130:133], v[194:197], v[94:97]
	v_mfma_f32_16x16x32_bf16 v[86:89], v[138:141], v[194:197], v[86:89]
	v_mfma_f32_16x16x32_bf16 v[78:81], v[130:133], v[202:205], v[78:81]
	v_mfma_f32_16x16x32_bf16 v[70:73], v[138:141], v[202:205], v[70:73]
	v_mfma_f32_16x16x32_bf16 v[122:125], v[134:137], v[176:179], v[122:125]
	v_mfma_f32_16x16x32_bf16 v[118:121], v[142:145], v[176:179], v[118:121]
	v_mfma_f32_16x16x32_bf16 v[110:113], v[134:137], v[190:193], v[110:113]
	v_mfma_f32_16x16x32_bf16 v[102:105], v[142:145], v[190:193], v[102:105]
	v_mfma_f32_16x16x32_bf16 v[94:97], v[134:137], v[198:201], v[94:97]
	v_mfma_f32_16x16x32_bf16 v[86:89], v[142:145], v[198:201], v[86:89]
	v_mfma_f32_16x16x32_bf16 v[78:81], v[134:137], v[206:209], v[78:81]
	v_mfma_f32_16x16x32_bf16 v[70:73], v[142:145], v[206:209], v[70:73]
	s_setprio 0
	s_setprio 1
	v_mfma_f32_16x16x32_bf16 v[114:117], v[146:149], v[172:175], v[114:117]
	v_mfma_f32_16x16x32_bf16 v[126:129], v[164:167], v[172:175], v[126:129]
	v_mfma_f32_16x16x32_bf16 v[106:109], v[146:149], v[186:189], v[106:109]
	v_mfma_f32_16x16x32_bf16 v[98:101], v[164:167], v[186:189], v[98:101]
	v_mfma_f32_16x16x32_bf16 v[90:93], v[146:149], v[194:197], v[90:93]
	v_mfma_f32_16x16x32_bf16 v[82:85], v[164:167], v[194:197], v[82:85]
	v_mfma_f32_16x16x32_bf16 v[74:77], v[146:149], v[202:205], v[74:77]
	v_mfma_f32_16x16x32_bf16 v[66:69], v[164:167], v[202:205], v[66:69]
	v_mfma_f32_16x16x32_bf16 v[114:117], v[150:153], v[176:179], v[114:117]
	v_mfma_f32_16x16x32_bf16 v[126:129], v[168:171], v[176:179], v[126:129]
	v_mfma_f32_16x16x32_bf16 v[106:109], v[150:153], v[190:193], v[106:109]
	v_mfma_f32_16x16x32_bf16 v[98:101], v[168:171], v[190:193], v[98:101]
	v_mfma_f32_16x16x32_bf16 v[90:93], v[150:153], v[198:201], v[90:93]
	v_mfma_f32_16x16x32_bf16 v[82:85], v[168:171], v[198:201], v[82:85]
	s_setprio 2
	s_barrier
; #define PG8_STAGE(bufoff, gbase, voff) do { _Pragma("unroll") for (int _i = 0; _i < 2; ++_i) \
;         __builtin_amdgcn_global_load_lds((const unsigned*)((const char*)(gbase) + (voff)[_i]), (LAS unsigned*)(lds + (bufoff) + ldsw + _i * 8192), 16, 0, 0); } while (0)
; #define PG8_LDA(dst, b, h) do { _Pragma("unroll") for (int m = 0; m < 4; ++m) _Pragma("unroll") for (int k = 0; k < 2; ++k) dst[m][k] = *(const LAS bf16x8*)(lds + PG8_SA(b, h) + aoff + m * 2048 + k * 1024); } while (0)
; #define PG8_MMA(ai, bj, At, Bt) do { __builtin_amdgcn_s_setprio(1); _Pragma("unroll") for (int m = 0; m < 4; ++m) _Pragma("unroll") for (int n = 0; n < 2; ++n) _Pragma("unroll") for (int k = 0; k < 2; ++k) \
;         acc[ai][bj][m][n] = __builtin_amdgcn_mfma_f32_16x16x32_bf16(Bt[n][k], At[m][k], acc[ai][bj][m][n], 0, 0, 0); __builtin_amdgcn_s_setprio(0); } while (0)
; #define PG8_WAIT_V(n) asm volatile("s_waitcnt vmcnt(" #n ")" ::: "memory")
; #define PG8_WAIT_L(n) asm volatile("s_waitcnt lgkmcnt(" #n ")" ::: "memory")
; #define PG8_BAR __builtin_amdgcn_s_barrier()
; #define PG8_SCHED __builtin_amdgcn_sched_barrier(0)
; template <class Epi>
; __device__ __forceinline__ void gemm_phase(LAS unsigned char* lds, const Gemm g, const TileOrder& S, const Epi& E) {
;     ...
;             PG8_WAIT_V(8); PG8_WAIT_L(0); PG8_BAR; PG8_MMA(0, 0, At, B0); PG8_MMA(0, 1, At, B1); PG8_BAR; PG8_SCHED;
;             PG8_LDA(At, 1, 1); PG8_STAGE(PG8_SB(1, 0), b3, voffB); PG8_STAGE(PG8_SB(1, 1), b3 + hstepB, voffB); PG8_STAGE(PG8_SA(1, 0), a3, voffA);
;             PG8_WAIT_V(8); PG8_WAIT_L(0); PG8_BAR; PG8_MMA(1, 0, At, B0); PG8_MMA(1, 1, At, B1); PG8_BAR; PG8_SCHED;
;         }
;         if (wr == 0) PG8_BAR;
	v_mfma_f32_16x16x32_bf16 v[74:77], v[150:153], v[206:209], v[74:77]
	v_mfma_f32_16x16x32_bf16 v[66:69], v[168:171], v[206:209], v[66:69]
	s_setprio 0
	s_add_i32 s6, s6, s31
	v_lshl_add_u64 v[180:181], v[180:181], 0, s[34:35]
	s_mov_b32 m0, s6
	ds_read_b128 v[172:175], v185 offset:49152
	ds_read_b128 v[176:179], v185 offset:50176
	ds_read_b128 v[186:189], v185 offset:51200
	ds_read_b128 v[190:193], v185 offset:52224
	ds_read_b128 v[194:197], v185 offset:53248
	ds_read_b128 v[198:201], v185 offset:54272
	ds_read_b128 v[202:205], v185 offset:55296
	ds_read_b128 v[206:209], v185 offset:56320
	global_load_lds_dwordx4 v[180:181], off
	s_add_i32 m0, s6, 0x2000
	s_add_u32 s2, s2, 0x80080
	v_lshl_add_u64 v[180:181], v[210:211], 0, s[34:35]
	s_addc_u32 s3, s3, 0
	s_add_i32 s6, s12, s31
	global_load_lds_dwordx4 v[180:181], off
	s_mov_b32 m0, s6
	s_nop 0
	global_load_lds_dwordx4 v0, s[2:3]
	v_lshl_add_u64 v[180:181], s[2:3], 0, v[154:155]
	s_add_i32 m0, s6, 0x2000
	s_nop 0
	global_load_lds_dwordx4 v[180:181], off
	v_lshl_add_u64 v[180:181], v[212:213], 0, s[34:35]
	s_mov_b32 m0, s58
	s_nop 0
	global_load_lds_dwordx4 v[180:181], off
	v_lshl_add_u64 v[180:181], v[214:215], 0, s[34:35]
	s_mov_b32 m0, s59
	s_nop 0
	global_load_lds_dwordx4 v[180:181], off
	s_waitcnt vmcnt(8)
	s_waitcnt lgkmcnt(0)
	s_barrier
	s_setprio 1
	s_waitcnt lgkmcnt(0)
	v_mfma_f32_16x16x32_bf16 v[62:65], v[130:133], v[172:175], v[62:65]
	v_mfma_f32_16x16x32_bf16 v[54:57], v[138:141], v[172:175], v[54:57]
	v_mfma_f32_16x16x32_bf16 v[46:49], v[130:133], v[186:189], v[46:49]
	v_mfma_f32_16x16x32_bf16 v[38:41], v[138:141], v[186:189], v[38:41]
	v_mfma_f32_16x16x32_bf16 v[30:33], v[130:133], v[194:197], v[30:33]
	v_mfma_f32_16x16x32_bf16 v[22:25], v[138:141], v[194:197], v[22:25]
	v_mfma_f32_16x16x32_bf16 v[14:17], v[130:133], v[202:205], v[14:17]
	v_mfma_f32_16x16x32_bf16 v[6:9], v[138:141], v[202:205], v[6:9]
	v_mfma_f32_16x16x32_bf16 v[62:65], v[134:137], v[176:179], v[62:65]
	v_mfma_f32_16x16x32_bf16 v[54:57], v[142:145], v[176:179], v[54:57]
	v_mfma_f32_16x16x32_bf16 v[46:49], v[134:137], v[190:193], v[46:49]
	v_mfma_f32_16x16x32_bf16 v[38:41], v[142:145], v[190:193], v[38:41]
	v_mfma_f32_16x16x32_bf16 v[30:33], v[134:137], v[198:201], v[30:33]
	v_mfma_f32_16x16x32_bf16 v[22:25], v[142:145], v[198:201], v[22:25]
	v_mfma_f32_16x16x32_bf16 v[14:17], v[134:137], v[206:209], v[14:17]
	v_mfma_f32_16x16x32_bf16 v[6:9], v[142:145], v[206:209], v[6:9]
	s_setprio 0
	s_setprio 1
	v_mfma_f32_16x16x32_bf16 v[58:61], v[146:149], v[172:175], v[58:61]
	v_mfma_f32_16x16x32_bf16 v[50:53], v[164:167], v[172:175], v[50:53]
	v_mfma_f32_16x16x32_bf16 v[42:45], v[146:149], v[186:189], v[42:45]
	v_mfma_f32_16x16x32_bf16 v[34:37], v[164:167], v[186:189], v[34:37]
	v_mfma_f32_16x16x32_bf16 v[26:29], v[146:149], v[194:197], v[26:29]
	v_mfma_f32_16x16x32_bf16 v[18:21], v[164:167], v[194:197], v[18:21]
	v_mfma_f32_16x16x32_bf16 v[10:13], v[146:149], v[202:205], v[10:13]
	v_mfma_f32_16x16x32_bf16 v[2:5], v[164:167], v[202:205], v[2:5]
	v_mfma_f32_16x16x32_bf16 v[58:61], v[150:153], v[176:179], v[58:61]
	v_mfma_f32_16x16x32_bf16 v[50:53], v[168:171], v[176:179], v[50:53]
	v_mfma_f32_16x16x32_bf16 v[42:45], v[150:153], v[190:193], v[42:45]
	v_mfma_f32_16x16x32_bf16 v[34:37], v[168:171], v[190:193], v[34:37]
	v_mfma_f32_16x16x32_bf16 v[26:29], v[150:153], v[198:201], v[26:29]
	v_mfma_f32_16x16x32_bf16 v[18:21], v[168:171], v[198:201], v[18:21]
	s_setprio 2
	s_barrier
	v_mfma_f32_16x16x32_bf16 v[10:13], v[150:153], v[206:209], v[10:13]
	v_mfma_f32_16x16x32_bf16 v[2:5], v[168:171], v[206:209], v[2:5]
	s_setprio 0
	s_add_i32 s66, s66, 2
	s_add_u32 s4, s4, 0x100
	s_addc_u32 s5, s5, 0
	s_add_u32 s64, s64, 0x100
	s_addc_u32 s65, s65, 0
	s_cmp_gt_u32 s66, 29
	s_cbranch_scc0 .LBB0_668
	s_and_b64 vcc, exec, s[38:39]
	s_cbranch_vccz .LBB0_671
	s_barrier

; #define PG8_STAGE(bufoff, gbase, voff) do { _Pragma("unroll") for (int _i = 0; _i < 2; ++_i) \
;         __builtin_amdgcn_global_load_lds((const unsigned*)((const char*)(gbase) + (voff)[_i]), (LAS unsigned*)(lds + (bufoff) + ldsw + _i * 8192), 16, 0, 0); } while (0)
; #define PG8_LDA(dst, b, h) do { _Pragma("unroll") for (int m = 0; m < 4; ++m) _Pragma("unroll") for (int k = 0; k < 2; ++k) dst[m][k] = *(const LAS bf16x8*)(lds + PG8_SA(b, h) + aoff + m * 2048 + k * 1024); } while (0)
; #define PG8_LDB(dst, b, h) do { _Pragma("unroll") for (int n = 0; n < 2; ++n) _Pragma("unroll") for (int k = 0; k < 2; ++k) dst[n][k] = *(const LAS bf16x8*)(lds + PG8_SB(b, h) + boff + n * 2048 + k * 1024); } while (0)
; #define PG8_MMA(ai, bj, At, Bt) do { __builtin_amdgcn_s_setprio(1); _Pragma("unroll") for (int m = 0; m < 4; ++m) _Pragma("unroll") for (int n = 0; n < 2; ++n) _Pragma("unroll") for (int k = 0; k < 2; ++k) \
;         acc[ai][bj][m][n] = __builtin_amdgcn_mfma_f32_16x16x32_bf16(Bt[n][k], At[m][k], acc[ai][bj][m][n], 0, 0, 0); __builtin_amdgcn_s_setprio(0); } while (0)
; #define PG8_WAIT_V(n) asm volatile("s_waitcnt vmcnt(" #n ")" ::: "memory")
; #define PG8_WAIT_L(n) asm volatile("s_waitcnt lgkmcnt(" #n ")" ::: "memory")
; #define PG8_BAR __builtin_amdgcn_s_barrier()
; #define PG8_SCHED __builtin_amdgcn_sched_barrier(0)
; template <class Epi>
; __device__ __forceinline__ void gemm_phase(LAS unsigned char* lds, const Gemm g, const TileOrder& S, const Epi& E) {
;     ...
;             const bool last = (t == nt - 2);
;             const char* a1 = cA + (size_t)(t + 1) * kstepA;
;             const char* a2 = last ? nA : cA + (size_t)(t + 2) * kstepA; const char* b2 = last ? nB : cB + (size_t)(t + 2) * kstep;
;             const char* a3 = a2 + kstepA; const char* b3 = b2 + kstep;
;             PG8_LDB(B0, 0, 0); PG8_LDB(B1, 0, 1); PG8_SCHED; PG8_LDA(At, 0, 0); PG8_STAGE(PG8_SA(1, 1), a1 + hstepA, voffA);
;             PG8_WAIT_V(8); PG8_WAIT_L(0); PG8_BAR; PG8_MMA(0, 0, At, B0); PG8_MMA(0, 1, At, B1); PG8_BAR; PG8_SCHED;
;             PG8_LDA(At, 0, 1); PG8_STAGE(PG8_SB(0, 0), b2, voffB); PG8_STAGE(PG8_SB(0, 1), b2 + hstepB, voffB); PG8_STAGE(PG8_SA(0, 0), a2, voffA);
.LBB0_757:
	s_mov_b32 s6, 0x10000
	v_add_u32_e32 v0, s6, v154
	s_mov_b32 s14, 0x14000
	ds_read_b128 v[142:145], v0
	ds_read_b128 v[146:149], v0 offset:1024
	ds_read_b128 v[156:159], v0 offset:2048
	ds_read_b128 v[160:163], v0 offset:3072
	v_add_u32_e32 v0, s14, v154
	ds_read_b128 v[164:167], v0
	ds_read_b128 v[168:171], v0 offset:1024
	ds_read_b128 v[172:175], v0 offset:2048
	ds_read_b128 v[176:179], v0 offset:3072
	ds_read_b128 v[180:183], v155
	ds_read_b128 v[184:187], v155 offset:1024
	ds_read_b128 v[188:191], v155 offset:2048
	ds_read_b128 v[192:195], v155 offset:3072
	ds_read_b128 v[196:199], v155 offset:4096
	ds_read_b128 v[200:203], v155 offset:5120
	ds_read_b128 v[204:207], v155 offset:6144
	ds_read_b128 v[208:211], v155 offset:7168
	s_add_u32 s2, s28, 0xfff80080
	s_addc_u32 s3, s29, -1
	s_cmp_eq_u32 s72, 28
	s_cselect_b32 s31, s47, s3
	s_cselect_b32 s30, s51, s2
	s_cselect_b32 s3, s49, s71
	s_cselect_b32 s2, s69, s70
	s_add_i32 m0, s59, 0xc000
	s_nop 0
	global_load_lds_dwordx4 v138, s[28:29]
	s_add_i32 m0, s59, 0xe000
	s_nop 0
	global_load_lds_dwordx4 v140, s[28:29]
	s_waitcnt vmcnt(8)
	s_waitcnt lgkmcnt(0)
	s_barrier
	s_setprio 1
	s_waitcnt lgkmcnt(0)
	v_mfma_f32_16x16x32_bf16 v[126:129], v[142:145], v[180:183], v[126:129]
	v_mfma_f32_16x16x32_bf16 v[122:125], v[156:159], v[180:183], v[122:125]
	v_mfma_f32_16x16x32_bf16 v[110:113], v[142:145], v[188:191], v[110:113]
	v_mfma_f32_16x16x32_bf16 v[106:109], v[156:159], v[188:191], v[106:109]
	v_mfma_f32_16x16x32_bf16 v[94:97], v[142:145], v[196:199], v[94:97]
	v_mfma_f32_16x16x32_bf16 v[90:93], v[156:159], v[196:199], v[90:93]
	v_mfma_f32_16x16x32_bf16 v[78:81], v[142:145], v[204:207], v[78:81]
	v_mfma_f32_16x16x32_bf16 v[74:77], v[156:159], v[204:207], v[74:77]
	v_mfma_f32_16x16x32_bf16 v[126:129], v[146:149], v[184:187], v[126:129]
	v_mfma_f32_16x16x32_bf16 v[122:125], v[160:163], v[184:187], v[122:125]
	v_mfma_f32_16x16x32_bf16 v[110:113], v[146:149], v[192:195], v[110:113]
	v_mfma_f32_16x16x32_bf16 v[106:109], v[160:163], v[192:195], v[106:109]
	v_mfma_f32_16x16x32_bf16 v[94:97], v[146:149], v[200:203], v[94:97]
	v_mfma_f32_16x16x32_bf16 v[90:93], v[160:163], v[200:203], v[90:93]
	v_mfma_f32_16x16x32_bf16 v[78:81], v[146:149], v[208:211], v[78:81]
	v_mfma_f32_16x16x32_bf16 v[74:77], v[160:163], v[208:211], v[74:77]
	s_setprio 0
	s_setprio 1
	v_mfma_f32_16x16x32_bf16 v[118:121], v[164:167], v[180:183], v[118:121]
	v_mfma_f32_16x16x32_bf16 v[114:117], v[172:175], v[180:183], v[114:117]
	v_mfma_f32_16x16x32_bf16 v[102:105], v[164:167], v[188:191], v[102:105]
	v_mfma_f32_16x16x32_bf16 v[98:101], v[172:175], v[188:191], v[98:101]
	v_mfma_f32_16x16x32_bf16 v[86:89], v[164:167], v[196:199], v[86:89]
	v_mfma_f32_16x16x32_bf16 v[82:85], v[172:175], v[196:199], v[82:85]
	v_mfma_f32_16x16x32_bf16 v[70:73], v[164:167], v[204:207], v[70:73]
	v_mfma_f32_16x16x32_bf16 v[66:69], v[172:175], v[204:207], v[66:69]
	v_mfma_f32_16x16x32_bf16 v[118:121], v[168:171], v[184:187], v[118:121]
	v_mfma_f32_16x16x32_bf16 v[114:117], v[176:179], v[184:187], v[114:117]
	v_mfma_f32_16x16x32_bf16 v[102:105], v[168:171], v[192:195], v[102:105]
	v_mfma_f32_16x16x32_bf16 v[98:101], v[176:179], v[192:195], v[98:101]
	v_mfma_f32_16x16x32_bf16 v[86:89], v[168:171], v[200:203], v[86:89]
	v_mfma_f32_16x16x32_bf16 v[82:85], v[176:179], v[200:203], v[82:85]
	s_setprio 2
	s_barrier
	v_mfma_f32_16x16x32_bf16 v[70:73], v[168:171], v[208:211], v[70:73]
	v_mfma_f32_16x16x32_bf16 v[66:69], v[176:179], v[208:211], v[66:69]
	s_setprio 0
	s_add_i32 s6, s6, s58
	v_lshl_add_u64 v[150:151], s[2:3], 0, v[134:135]
	s_mov_b32 m0, s6
	ds_read_b128 v[180:183], v155 offset:16384
	ds_read_b128 v[184:187], v155 offset:17408
	ds_read_b128 v[188:191], v155 offset:18432
	ds_read_b128 v[192:195], v155 offset:19456
	ds_read_b128 v[196:199], v155 offset:20480
	ds_read_b128 v[200:203], v155 offset:21504
	ds_read_b128 v[204:207], v155 offset:22528
	ds_read_b128 v[208:211], v155 offset:23552
	global_load_lds_dwordx4 v[150:151], off
	s_add_i32 m0, s6, 0x2000
	s_add_u32 s12, s2, 0x80000
	v_lshl_add_u64 v[212:213], s[2:3], 0, v[130:131]
	s_addc_u32 s13, s3, 0
	s_add_i32 s6, s14, s58
	global_load_lds_dwordx4 v[212:213], off
	s_mov_b32 m0, s6
	v_lshl_add_u64 v[216:217], s[30:31], 0, v[132:133]
	global_load_lds_dwordx4 v134, s[12:13]
	s_add_i32 m0, s6, 0x2000
	s_nop 0
	global_load_lds_dwordx4 v130, s[12:13]
	v_lshl_add_u64 v[214:215], s[30:31], 0, v[136:137]
	s_mov_b32 m0, s59
	s_nop 0
	global_load_lds_dwordx4 v[214:215], off
	s_mov_b32 m0, s60
	s_nop 0
	global_load_lds_dwordx4 v[216:217], off
	s_waitcnt vmcnt(8)
	s_waitcnt lgkmcnt(0)
	s_barrier
; #define PG8_STAGE(bufoff, gbase, voff) do { _Pragma("unroll") for (int _i = 0; _i < 2; ++_i) \
;         __builtin_amdgcn_global_load_lds((const unsigned*)((const char*)(gbase) + (voff)[_i]), (LAS unsigned*)(lds + (bufoff) + ldsw + _i * 8192), 16, 0, 0); } while (0)
; #define PG8_LDA(dst, b, h) do { _Pragma("unroll") for (int m = 0; m < 4; ++m) _Pragma("unroll") for (int k = 0; k < 2; ++k) dst[m][k] = *(const LAS bf16x8*)(lds + PG8_SA(b, h) + aoff + m * 2048 + k * 1024); } while (0)
; #define PG8_LDB(dst, b, h) do { _Pragma("unroll") for (int n = 0; n < 2; ++n) _Pragma("unroll") for (int k = 0; k < 2; ++k) dst[n][k] = *(const LAS bf16x8*)(lds + PG8_SB(b, h) + boff + n * 2048 + k * 1024); } while (0)
; #define PG8_MMA(ai, bj, At, Bt) do { __builtin_amdgcn_s_setprio(1); _Pragma("unroll") for (int m = 0; m < 4; ++m) _Pragma("unroll") for (int n = 0; n < 2; ++n) _Pragma("unroll") for (int k = 0; k < 2; ++k) \
;         acc[ai][bj][m][n] = __builtin_amdgcn_mfma_f32_16x16x32_bf16(Bt[n][k], At[m][k], acc[ai][bj][m][n], 0, 0, 0); __builtin_amdgcn_s_setprio(0); } while (0)
; #define PG8_WAIT_V(n) asm volatile("s_waitcnt vmcnt(" #n ")" ::: "memory")
; #define PG8_WAIT_L(n) asm volatile("s_waitcnt lgkmcnt(" #n ")" ::: "memory")
; #define PG8_BAR __builtin_amdgcn_s_barrier()
; #define PG8_SCHED __builtin_amdgcn_sched_barrier(0)
; template <class Epi>
; __device__ __forceinline__ void gemm_phase(LAS unsigned char* lds, const Gemm g, const TileOrder& S, const Epi& E) {
;     ...
;             PG8_WAIT_V(8); PG8_WAIT_L(0); PG8_BAR; PG8_MMA(1, 0, At, B0); PG8_MMA(1, 1, At, B1); PG8_BAR; PG8_SCHED;
;             PG8_LDB(B0, 1, 0); PG8_LDB(B1, 1, 1); PG8_SCHED; PG8_LDA(At, 1, 0); PG8_STAGE(PG8_SA(0, 1), a2 + hstepA, voffA);
;             PG8_WAIT_V(8); PG8_WAIT_L(0); PG8_BAR; PG8_MMA(0, 0, At, B0); PG8_MMA(0, 1, At, B1); PG8_BAR; PG8_SCHED;
	s_setprio 1
	s_waitcnt lgkmcnt(0)
	v_mfma_f32_16x16x32_bf16 v[62:65], v[142:145], v[180:183], v[62:65]
	v_mfma_f32_16x16x32_bf16 v[58:61], v[156:159], v[180:183], v[58:61]
	v_mfma_f32_16x16x32_bf16 v[46:49], v[142:145], v[188:191], v[46:49]
	v_mfma_f32_16x16x32_bf16 v[42:45], v[156:159], v[188:191], v[42:45]
	v_mfma_f32_16x16x32_bf16 v[30:33], v[142:145], v[196:199], v[30:33]
	v_mfma_f32_16x16x32_bf16 v[26:29], v[156:159], v[196:199], v[26:29]
	v_mfma_f32_16x16x32_bf16 v[14:17], v[142:145], v[204:207], v[14:17]
	v_mfma_f32_16x16x32_bf16 v[10:13], v[156:159], v[204:207], v[10:13]
	v_mfma_f32_16x16x32_bf16 v[62:65], v[146:149], v[184:187], v[62:65]
	v_mfma_f32_16x16x32_bf16 v[58:61], v[160:163], v[184:187], v[58:61]
	v_mfma_f32_16x16x32_bf16 v[46:49], v[146:149], v[192:195], v[46:49]
	v_mfma_f32_16x16x32_bf16 v[42:45], v[160:163], v[192:195], v[42:45]
	v_mfma_f32_16x16x32_bf16 v[30:33], v[146:149], v[200:203], v[30:33]
	v_mfma_f32_16x16x32_bf16 v[26:29], v[160:163], v[200:203], v[26:29]
	v_mfma_f32_16x16x32_bf16 v[14:17], v[146:149], v[208:211], v[14:17]
	v_mfma_f32_16x16x32_bf16 v[10:13], v[160:163], v[208:211], v[10:13]
	s_setprio 0
	s_setprio 1
	v_mfma_f32_16x16x32_bf16 v[54:57], v[164:167], v[180:183], v[54:57]
	v_mfma_f32_16x16x32_bf16 v[50:53], v[172:175], v[180:183], v[50:53]
	v_mfma_f32_16x16x32_bf16 v[38:41], v[164:167], v[188:191], v[38:41]
	v_mfma_f32_16x16x32_bf16 v[34:37], v[172:175], v[188:191], v[34:37]
	v_mfma_f32_16x16x32_bf16 v[22:25], v[164:167], v[196:199], v[22:25]
	v_mfma_f32_16x16x32_bf16 v[18:21], v[172:175], v[196:199], v[18:21]
	v_mfma_f32_16x16x32_bf16 v[6:9], v[164:167], v[204:207], v[6:9]
	v_mfma_f32_16x16x32_bf16 v[2:5], v[172:175], v[204:207], v[2:5]
	v_mfma_f32_16x16x32_bf16 v[54:57], v[168:171], v[184:187], v[54:57]
	v_mfma_f32_16x16x32_bf16 v[50:53], v[176:179], v[184:187], v[50:53]
	v_mfma_f32_16x16x32_bf16 v[38:41], v[168:171], v[192:195], v[38:41]
	v_mfma_f32_16x16x32_bf16 v[34:37], v[176:179], v[192:195], v[34:37]
	v_mfma_f32_16x16x32_bf16 v[22:25], v[168:171], v[200:203], v[22:25]
	v_mfma_f32_16x16x32_bf16 v[18:21], v[176:179], v[200:203], v[18:21]
	s_setprio 2
	s_barrier
	v_mfma_f32_16x16x32_bf16 v[6:9], v[168:171], v[208:211], v[6:9]
	v_mfma_f32_16x16x32_bf16 v[2:5], v[176:179], v[208:211], v[2:5]
	s_setprio 0
	s_add_i32 s6, 0, 0x18000
	v_add_u32_e32 v0, s6, v154
	s_add_i32 s14, 0, 0x1c000
	ds_read_b128 v[142:145], v0
	ds_read_b128 v[146:149], v0 offset:1024
	ds_read_b128 v[156:159], v0 offset:2048
	ds_read_b128 v[160:163], v0 offset:3072
	v_add_u32_e32 v0, s14, v154
	ds_read_b128 v[164:167], v0
	ds_read_b128 v[168:171], v0 offset:1024
	ds_read_b128 v[172:175], v0 offset:2048
	ds_read_b128 v[176:179], v0 offset:3072
	s_add_u32 s12, s30, 0x80000
	s_addc_u32 s13, s31, 0
	s_mov_b32 m0, s61
	ds_read_b128 v[180:183], v155 offset:32768
	ds_read_b128 v[184:187], v155 offset:33792
	ds_read_b128 v[188:191], v155 offset:34816
	ds_read_b128 v[192:195], v155 offset:35840
	ds_read_b128 v[196:199], v155 offset:36864
	ds_read_b128 v[200:203], v155 offset:37888
	ds_read_b128 v[204:207], v155 offset:38912
	ds_read_b128 v[208:211], v155 offset:39936
	global_load_lds_dwordx4 v136, s[12:13]
	s_mov_b32 m0, s62
	s_nop 0
	global_load_lds_dwordx4 v132, s[12:13]
	s_waitcnt vmcnt(8)
	s_waitcnt lgkmcnt(0)
	s_barrier
	s_setprio 1
	s_waitcnt lgkmcnt(0)
	v_mfma_f32_16x16x32_bf16 v[126:129], v[142:145], v[180:183], v[126:129]
	v_mfma_f32_16x16x32_bf16 v[122:125], v[156:159], v[180:183], v[122:125]
	v_mfma_f32_16x16x32_bf16 v[110:113], v[142:145], v[188:191], v[110:113]
	v_mfma_f32_16x16x32_bf16 v[106:109], v[156:159], v[188:191], v[106:109]
	v_mfma_f32_16x16x32_bf16 v[94:97], v[142:145], v[196:199], v[94:97]
	v_mfma_f32_16x16x32_bf16 v[90:93], v[156:159], v[196:199], v[90:93]
	v_mfma_f32_16x16x32_bf16 v[78:81], v[142:145], v[204:207], v[78:81]
	v_mfma_f32_16x16x32_bf16 v[74:77], v[156:159], v[204:207], v[74:77]
	v_mfma_f32_16x16x32_bf16 v[126:129], v[146:149], v[184:187], v[126:129]
	v_mfma_f32_16x16x32_bf16 v[122:125], v[160:163], v[184:187], v[122:125]
	v_mfma_f32_16x16x32_bf16 v[110:113], v[146:149], v[192:195], v[110:113]
	v_mfma_f32_16x16x32_bf16 v[106:109], v[160:163], v[192:195], v[106:109]
	v_mfma_f32_16x16x32_bf16 v[94:97], v[146:149], v[200:203], v[94:97]
	v_mfma_f32_16x16x32_bf16 v[90:93], v[160:163], v[200:203], v[90:93]
	v_mfma_f32_16x16x32_bf16 v[78:81], v[146:149], v[208:211], v[78:81]
	v_mfma_f32_16x16x32_bf16 v[74:77], v[160:163], v[208:211], v[74:77]
	s_setprio 0
	s_setprio 1
	v_mfma_f32_16x16x32_bf16 v[118:121], v[164:167], v[180:183], v[118:121]
	v_mfma_f32_16x16x32_bf16 v[114:117], v[172:175], v[180:183], v[114:117]
	v_mfma_f32_16x16x32_bf16 v[102:105], v[164:167], v[188:191], v[102:105]
	v_mfma_f32_16x16x32_bf16 v[98:101], v[172:175], v[188:191], v[98:101]
	v_mfma_f32_16x16x32_bf16 v[86:89], v[164:167], v[196:199], v[86:89]
	v_mfma_f32_16x16x32_bf16 v[82:85], v[172:175], v[196:199], v[82:85]
	v_mfma_f32_16x16x32_bf16 v[70:73], v[164:167], v[204:207], v[70:73]
	v_mfma_f32_16x16x32_bf16 v[66:69], v[172:175], v[204:207], v[66:69]
	v_mfma_f32_16x16x32_bf16 v[118:121], v[168:171], v[184:187], v[118:121]
	v_mfma_f32_16x16x32_bf16 v[114:117], v[176:179], v[184:187], v[114:117]
	v_mfma_f32_16x16x32_bf16 v[102:105], v[168:171], v[192:195], v[102:105]
	v_mfma_f32_16x16x32_bf16 v[98:101], v[176:179], v[192:195], v[98:101]
	v_mfma_f32_16x16x32_bf16 v[86:89], v[168:171], v[200:203], v[86:89]
	v_mfma_f32_16x16x32_bf16 v[82:85], v[176:179], v[200:203], v[82:85]
	s_setprio 2
	s_barrier
; #define PG8_STAGE(bufoff, gbase, voff) do { _Pragma("unroll") for (int _i = 0; _i < 2; ++_i) \
;         __builtin_amdgcn_global_load_lds((const unsigned*)((const char*)(gbase) + (voff)[_i]), (LAS unsigned*)(lds + (bufoff) + ldsw + _i * 8192), 16, 0, 0); } while (0)
; #define PG8_LDA(dst, b, h) do { _Pragma("unroll") for (int m = 0; m < 4; ++m) _Pragma("unroll") for (int k = 0; k < 2; ++k) dst[m][k] = *(const LAS bf16x8*)(lds + PG8_SA(b, h) + aoff + m * 2048 + k * 1024); } while (0)
; #define PG8_MMA(ai, bj, At, Bt) do { __builtin_amdgcn_s_setprio(1); _Pragma("unroll") for (int m = 0; m < 4; ++m) _Pragma("unroll") for (int n = 0; n < 2; ++n) _Pragma("unroll") for (int k = 0; k < 2; ++k) \
;         acc[ai][bj][m][n] = __builtin_amdgcn_mfma_f32_16x16x32_bf16(Bt[n][k], At[m][k], acc[ai][bj][m][n], 0, 0, 0); __builtin_amdgcn_s_setprio(0); } while (0)
; #define PG8_WAIT_V(n) asm volatile("s_waitcnt vmcnt(" #n ")" ::: "memory")
; #define PG8_WAIT_L(n) asm volatile("s_waitcnt lgkmcnt(" #n ")" ::: "memory")
; #define PG8_BAR __builtin_amdgcn_s_barrier()
; #define PG8_SCHED __builtin_amdgcn_sched_barrier(0)
; template <class Epi>
; __device__ __forceinline__ void gemm_phase(LAS unsigned char* lds, const Gemm g, const TileOrder& S, const Epi& E) {
;     ...
;             PG8_WAIT_V(8); PG8_WAIT_L(0); PG8_BAR; PG8_MMA(0, 0, At, B0); PG8_MMA(0, 1, At, B1); PG8_BAR; PG8_SCHED;
;             PG8_LDA(At, 1, 1); PG8_STAGE(PG8_SB(1, 0), b3, voffB); PG8_STAGE(PG8_SB(1, 1), b3 + hstepB, voffB); PG8_STAGE(PG8_SA(1, 0), a3, voffA);
;             PG8_WAIT_V(8); PG8_WAIT_L(0); PG8_BAR; PG8_MMA(1, 0, At, B0); PG8_MMA(1, 1, At, B1); PG8_BAR; PG8_SCHED;
;         }
;         if (wr == 0) PG8_BAR;
	v_mfma_f32_16x16x32_bf16 v[70:73], v[168:171], v[208:211], v[70:73]
	v_mfma_f32_16x16x32_bf16 v[66:69], v[176:179], v[208:211], v[66:69]
	s_setprio 0
	s_add_i32 s6, s6, s58
	v_lshl_add_u64 v[150:151], v[150:151], 0, s[34:35]
	s_mov_b32 m0, s6
	ds_read_b128 v[180:183], v155 offset:49152
	ds_read_b128 v[184:187], v155 offset:50176
	ds_read_b128 v[188:191], v155 offset:51200
	ds_read_b128 v[192:195], v155 offset:52224
	ds_read_b128 v[196:199], v155 offset:53248
	ds_read_b128 v[200:203], v155 offset:54272
	ds_read_b128 v[204:207], v155 offset:55296
	ds_read_b128 v[208:211], v155 offset:56320
	global_load_lds_dwordx4 v[150:151], off
	s_add_i32 m0, s6, 0x2000
	s_add_u32 s2, s2, 0x80080
	v_lshl_add_u64 v[150:151], v[212:213], 0, s[34:35]
	s_addc_u32 s3, s3, 0
	s_add_i32 s6, s14, s58
	global_load_lds_dwordx4 v[150:151], off
	s_mov_b32 m0, s6
	s_nop 0
	global_load_lds_dwordx4 v134, s[2:3]
	v_lshl_add_u64 v[150:151], s[2:3], 0, v[130:131]
	s_add_i32 m0, s6, 0x2000
	s_nop 0
	global_load_lds_dwordx4 v[150:151], off
	v_lshl_add_u64 v[150:151], v[214:215], 0, s[34:35]
	s_mov_b32 m0, s63
	s_nop 0
	global_load_lds_dwordx4 v[150:151], off
	v_lshl_add_u64 v[150:151], v[216:217], 0, s[34:35]
	s_mov_b32 m0, s64
	s_nop 0
	global_load_lds_dwordx4 v[150:151], off
	s_waitcnt vmcnt(8)
	s_waitcnt lgkmcnt(0)
	s_barrier
	s_setprio 1
	s_waitcnt lgkmcnt(0)
	v_mfma_f32_16x16x32_bf16 v[62:65], v[142:145], v[180:183], v[62:65]
	v_mfma_f32_16x16x32_bf16 v[58:61], v[156:159], v[180:183], v[58:61]
	v_mfma_f32_16x16x32_bf16 v[46:49], v[142:145], v[188:191], v[46:49]
	v_mfma_f32_16x16x32_bf16 v[42:45], v[156:159], v[188:191], v[42:45]
	v_mfma_f32_16x16x32_bf16 v[30:33], v[142:145], v[196:199], v[30:33]
	v_mfma_f32_16x16x32_bf16 v[26:29], v[156:159], v[196:199], v[26:29]
	v_mfma_f32_16x16x32_bf16 v[14:17], v[142:145], v[204:207], v[14:17]
	v_mfma_f32_16x16x32_bf16 v[10:13], v[156:159], v[204:207], v[10:13]
	v_mfma_f32_16x16x32_bf16 v[62:65], v[146:149], v[184:187], v[62:65]
	v_mfma_f32_16x16x32_bf16 v[58:61], v[160:163], v[184:187], v[58:61]
	v_mfma_f32_16x16x32_bf16 v[46:49], v[146:149], v[192:195], v[46:49]
	v_mfma_f32_16x16x32_bf16 v[42:45], v[160:163], v[192:195], v[42:45]
	v_mfma_f32_16x16x32_bf16 v[30:33], v[146:149], v[200:203], v[30:33]
	v_mfma_f32_16x16x32_bf16 v[26:29], v[160:163], v[200:203], v[26:29]
	v_mfma_f32_16x16x32_bf16 v[14:17], v[146:149], v[208:211], v[14:17]
	v_mfma_f32_16x16x32_bf16 v[10:13], v[160:163], v[208:211], v[10:13]
	s_setprio 0
	s_setprio 1
	v_mfma_f32_16x16x32_bf16 v[54:57], v[164:167], v[180:183], v[54:57]
	v_mfma_f32_16x16x32_bf16 v[50:53], v[172:175], v[180:183], v[50:53]
	v_mfma_f32_16x16x32_bf16 v[38:41], v[164:167], v[188:191], v[38:41]
	v_mfma_f32_16x16x32_bf16 v[34:37], v[172:175], v[188:191], v[34:37]
	v_mfma_f32_16x16x32_bf16 v[22:25], v[164:167], v[196:199], v[22:25]
	v_mfma_f32_16x16x32_bf16 v[18:21], v[172:175], v[196:199], v[18:21]
	v_mfma_f32_16x16x32_bf16 v[6:9], v[164:167], v[204:207], v[6:9]
	v_mfma_f32_16x16x32_bf16 v[2:5], v[172:175], v[204:207], v[2:5]
	v_mfma_f32_16x16x32_bf16 v[54:57], v[168:171], v[184:187], v[54:57]
	v_mfma_f32_16x16x32_bf16 v[50:53], v[176:179], v[184:187], v[50:53]
	v_mfma_f32_16x16x32_bf16 v[38:41], v[168:171], v[192:195], v[38:41]
	v_mfma_f32_16x16x32_bf16 v[34:37], v[176:179], v[192:195], v[34:37]
	v_mfma_f32_16x16x32_bf16 v[22:25], v[168:171], v[200:203], v[22:25]
	v_mfma_f32_16x16x32_bf16 v[18:21], v[176:179], v[200:203], v[18:21]
	s_setprio 2
	s_barrier
	v_mfma_f32_16x16x32_bf16 v[6:9], v[168:171], v[208:211], v[6:9]
	v_mfma_f32_16x16x32_bf16 v[2:5], v[176:179], v[208:211], v[2:5]
	s_setprio 0
	s_add_i32 s72, s72, 2
	s_add_u32 s28, s28, 0x100
	s_addc_u32 s29, s29, 0
	s_add_u32 s70, s70, 0x100
	s_addc_u32 s71, s71, 0
	s_cmp_gt_u32 s72, 29
	s_cbranch_scc0 .LBB0_757
	s_and_b64 vcc, exec, s[42:43]
	s_cbranch_vccz .LBB0_760
	s_barrier

; #define PG8_STAGE(bufoff, gbase, voff) do { _Pragma("unroll") for (int _i = 0; _i < 2; ++_i) \
;         __builtin_amdgcn_global_load_lds((const unsigned*)((const char*)(gbase) + (voff)[_i]), (LAS unsigned*)(lds + (bufoff) + ldsw + _i * 8192), 16, 0, 0); } while (0)
; #define PG8_LDA(dst, b, h) do { _Pragma("unroll") for (int m = 0; m < 4; ++m) _Pragma("unroll") for (int k = 0; k < 2; ++k) dst[m][k] = *(const LAS bf16x8*)(lds + PG8_SA(b, h) + aoff + m * 2048 + k * 1024); } while (0)
; #define PG8_LDB(dst, b, h) do { _Pragma("unroll") for (int n = 0; n < 2; ++n) _Pragma("unroll") for (int k = 0; k < 2; ++k) dst[n][k] = *(const LAS bf16x8*)(lds + PG8_SB(b, h) + boff + n * 2048 + k * 1024); } while (0)
; #define PG8_MMA(ai, bj, At, Bt) do { __builtin_amdgcn_s_setprio(1); _Pragma("unroll") for (int m = 0; m < 4; ++m) _Pragma("unroll") for (int n = 0; n < 2; ++n) _Pragma("unroll") for (int k = 0; k < 2; ++k) \
;         acc[ai][bj][m][n] = __builtin_amdgcn_mfma_f32_16x16x32_bf16(Bt[n][k], At[m][k], acc[ai][bj][m][n], 0, 0, 0); __builtin_amdgcn_s_setprio(0); } while (0)
; #define PG8_WAIT_V(n) asm volatile("s_waitcnt vmcnt(" #n ")" ::: "memory")
; #define PG8_WAIT_L(n) asm volatile("s_waitcnt lgkmcnt(" #n ")" ::: "memory")
; #define PG8_BAR __builtin_amdgcn_s_barrier()
; #define PG8_SCHED __builtin_amdgcn_sched_barrier(0)
; template <class Epi>
; __device__ __forceinline__ void gemm_phase(LAS unsigned char* lds, const Gemm g, const TileOrder& S, const Epi& E) {
;     ...
;             const bool last = (t == nt - 2);
;             const char* a1 = cA + (size_t)(t + 1) * kstepA;
;             const char* a2 = last ? nA : cA + (size_t)(t + 2) * kstepA; const char* b2 = last ? nB : cB + (size_t)(t + 2) * kstep;
;             const char* a3 = a2 + kstepA; const char* b3 = b2 + kstep;
;             PG8_LDB(B0, 0, 0); PG8_LDB(B1, 0, 1); PG8_SCHED; PG8_LDA(At, 0, 0); PG8_STAGE(PG8_SA(1, 1), a1 + hstepA, voffA);
;             PG8_WAIT_V(8); PG8_WAIT_L(0); PG8_BAR; PG8_MMA(0, 0, At, B0); PG8_MMA(0, 1, At, B1); PG8_BAR; PG8_SCHED;
;             PG8_LDA(At, 0, 1); PG8_STAGE(PG8_SB(0, 0), b2, voffB); PG8_STAGE(PG8_SB(0, 1), b2 + hstepB, voffB); PG8_STAGE(PG8_SA(0, 0), a2, voffA);
.LBB0_835:
	s_mov_b32 s6, 0x10000
	s_mov_b32 s14, 0x14000
	v_add_u32_e32 v106, s6, v240
	v_add_u32_e32 v150, s14, v240
	ds_read_b128 v[74:77], v106
	ds_read_b128 v[86:89], v106 offset:1024
	ds_read_b128 v[98:101], v106 offset:2048
	ds_read_b128 v[106:109], v106 offset:3072
	ds_read_b128 v[122:125], v150
	ds_read_b128 v[126:129], v150 offset:1024
	ds_read_b128 v[142:145], v150 offset:2048
	ds_read_b128 v[150:153], v150 offset:3072
	ds_read_b128 v[154:157], v241
	ds_read_b128 v[166:169], v241 offset:1024
	ds_read_b128 v[170:173], v241 offset:2048
	ds_read_b128 v[174:177], v241 offset:3072
	ds_read_b128 v[178:181], v241 offset:4096
	ds_read_b128 v[182:185], v241 offset:5120
	ds_read_b128 v[186:189], v241 offset:6144
	ds_read_b128 v[200:203], v241 offset:7168
	s_add_u32 s2, s28, 0x4000
	s_addc_u32 s3, s29, 0
	s_cmpk_eq_i32 s72, 0x7c
	s_cselect_b32 s38, s43, s2
	s_cselect_b32 s39, s42, s3
	s_cselect_b32 s30, s51, s53
	s_cselect_b32 s31, s45, s71
	s_add_u32 s2, s38, 0x8000
	s_addc_u32 s3, s39, 0
	s_add_i32 m0, s60, 0xc000
	s_nop 0
	global_load_lds_dwordx4 v196, s[28:29]
	s_add_i32 m0, s60, 0xe000
	s_nop 0
	global_load_lds_dwordx4 v198, s[28:29]
	s_waitcnt vmcnt(8)
	s_waitcnt lgkmcnt(0)
	s_barrier
	s_setprio 1
	s_waitcnt lgkmcnt(0)
	v_mfma_f32_16x16x32_bf16 v[162:165], v[74:77], v[154:157], v[162:165]
	v_mfma_f32_16x16x32_bf16 v[158:161], v[98:101], v[154:157], v[158:161]
	v_mfma_f32_16x16x32_bf16 v[134:137], v[74:77], v[170:173], v[134:137]
	v_mfma_f32_16x16x32_bf16 v[130:133], v[98:101], v[170:173], v[130:133]
	v_mfma_f32_16x16x32_bf16 v[110:113], v[74:77], v[178:181], v[110:113]
	v_mfma_f32_16x16x32_bf16 v[102:105], v[98:101], v[178:181], v[102:105]
	v_mfma_f32_16x16x32_bf16 v[82:85], v[74:77], v[186:189], v[82:85]
	v_mfma_f32_16x16x32_bf16 v[78:81], v[98:101], v[186:189], v[78:81]
	v_mfma_f32_16x16x32_bf16 v[162:165], v[86:89], v[166:169], v[162:165]
	v_mfma_f32_16x16x32_bf16 v[158:161], v[106:109], v[166:169], v[158:161]
	v_mfma_f32_16x16x32_bf16 v[134:137], v[86:89], v[174:177], v[134:137]
	v_mfma_f32_16x16x32_bf16 v[130:133], v[106:109], v[174:177], v[130:133]
	v_mfma_f32_16x16x32_bf16 v[110:113], v[86:89], v[182:185], v[110:113]
	v_mfma_f32_16x16x32_bf16 v[102:105], v[106:109], v[182:185], v[102:105]
	v_mfma_f32_16x16x32_bf16 v[82:85], v[86:89], v[200:203], v[82:85]
	v_mfma_f32_16x16x32_bf16 v[78:81], v[106:109], v[200:203], v[78:81]
	s_setprio 0
	s_setprio 1
	v_mfma_f32_16x16x32_bf16 v[146:149], v[122:125], v[154:157], v[146:149]
	v_mfma_f32_16x16x32_bf16 v[138:141], v[142:145], v[154:157], v[138:141]
	v_mfma_f32_16x16x32_bf16 v[118:121], v[122:125], v[170:173], v[118:121]
	v_mfma_f32_16x16x32_bf16 v[114:117], v[142:145], v[170:173], v[114:117]
	v_mfma_f32_16x16x32_bf16 v[94:97], v[122:125], v[178:181], v[94:97]
	v_mfma_f32_16x16x32_bf16 v[90:93], v[142:145], v[178:181], v[90:93]
	v_mfma_f32_16x16x32_bf16 v[70:73], v[122:125], v[186:189], v[70:73]
	v_mfma_f32_16x16x32_bf16 v[66:69], v[142:145], v[186:189], v[66:69]
	v_mfma_f32_16x16x32_bf16 v[146:149], v[126:129], v[166:169], v[146:149]
	v_mfma_f32_16x16x32_bf16 v[138:141], v[150:153], v[166:169], v[138:141]
	v_mfma_f32_16x16x32_bf16 v[118:121], v[126:129], v[174:177], v[118:121]
	v_mfma_f32_16x16x32_bf16 v[114:117], v[150:153], v[174:177], v[114:117]
	v_mfma_f32_16x16x32_bf16 v[94:97], v[126:129], v[182:185], v[94:97]
	v_mfma_f32_16x16x32_bf16 v[90:93], v[150:153], v[182:185], v[90:93]
	s_setprio 2
	s_barrier
	v_mfma_f32_16x16x32_bf16 v[70:73], v[126:129], v[200:203], v[70:73]
	v_mfma_f32_16x16x32_bf16 v[66:69], v[150:153], v[200:203], v[66:69]
	s_setprio 0
	s_add_i32 s6, s6, s59
	v_lshl_add_u64 v[204:205], s[30:31], 0, v[0:1]
	s_mov_b32 m0, s6
	ds_read_b128 v[154:157], v241 offset:16384
	ds_read_b128 v[166:169], v241 offset:17408
	ds_read_b128 v[170:173], v241 offset:18432
	ds_read_b128 v[174:177], v241 offset:19456
	ds_read_b128 v[178:181], v241 offset:20480
	ds_read_b128 v[182:185], v241 offset:21504
	ds_read_b128 v[186:189], v241 offset:22528
	ds_read_b128 v[200:203], v241 offset:23552
	global_load_lds_dwordx4 v[204:205], off
	s_add_i32 m0, s6, 0x2000
	s_add_u32 s12, s30, 0x200000
	v_lshl_add_u64 v[206:207], s[30:31], 0, v[190:191]
	s_addc_u32 s13, s31, 0
	s_add_i32 s6, s14, s59
	global_load_lds_dwordx4 v[206:207], off
	s_mov_b32 m0, s6
	s_nop 0
	global_load_lds_dwordx4 v0, s[12:13]
	s_add_i32 m0, s6, 0x2000
	s_nop 0
	global_load_lds_dwordx4 v190, s[12:13]
	s_mov_b32 m0, s60
	s_nop 0
	global_load_lds_dwordx4 v194, s[38:39]
	s_mov_b32 m0, s61
	s_nop 0
	global_load_lds_dwordx4 v192, s[38:39]
	s_waitcnt vmcnt(8)
	s_waitcnt lgkmcnt(0)
	s_barrier
; #define PG8_STAGE(bufoff, gbase, voff) do { _Pragma("unroll") for (int _i = 0; _i < 2; ++_i) \
;         __builtin_amdgcn_global_load_lds((const unsigned*)((const char*)(gbase) + (voff)[_i]), (LAS unsigned*)(lds + (bufoff) + ldsw + _i * 8192), 16, 0, 0); } while (0)
; #define PG8_LDA(dst, b, h) do { _Pragma("unroll") for (int m = 0; m < 4; ++m) _Pragma("unroll") for (int k = 0; k < 2; ++k) dst[m][k] = *(const LAS bf16x8*)(lds + PG8_SA(b, h) + aoff + m * 2048 + k * 1024); } while (0)
; #define PG8_LDB(dst, b, h) do { _Pragma("unroll") for (int n = 0; n < 2; ++n) _Pragma("unroll") for (int k = 0; k < 2; ++k) dst[n][k] = *(const LAS bf16x8*)(lds + PG8_SB(b, h) + boff + n * 2048 + k * 1024); } while (0)
; #define PG8_MMA(ai, bj, At, Bt) do { __builtin_amdgcn_s_setprio(1); _Pragma("unroll") for (int m = 0; m < 4; ++m) _Pragma("unroll") for (int n = 0; n < 2; ++n) _Pragma("unroll") for (int k = 0; k < 2; ++k) \
;         acc[ai][bj][m][n] = __builtin_amdgcn_mfma_f32_16x16x32_bf16(Bt[n][k], At[m][k], acc[ai][bj][m][n], 0, 0, 0); __builtin_amdgcn_s_setprio(0); } while (0)
; #define PG8_WAIT_V(n) asm volatile("s_waitcnt vmcnt(" #n ")" ::: "memory")
; #define PG8_WAIT_L(n) asm volatile("s_waitcnt lgkmcnt(" #n ")" ::: "memory")
; #define PG8_BAR __builtin_amdgcn_s_barrier()
; #define PG8_SCHED __builtin_amdgcn_sched_barrier(0)
; template <class Epi>
; __device__ __forceinline__ void gemm_phase(LAS unsigned char* lds, const Gemm g, const TileOrder& S, const Epi& E) {
;     ...
;             PG8_WAIT_V(8); PG8_WAIT_L(0); PG8_BAR; PG8_MMA(1, 0, At, B0); PG8_MMA(1, 1, At, B1); PG8_BAR; PG8_SCHED;
;             PG8_LDB(B0, 1, 0); PG8_LDB(B1, 1, 1); PG8_SCHED; PG8_LDA(At, 1, 0); PG8_STAGE(PG8_SA(0, 1), a2 + hstepA, voffA);
;             PG8_WAIT_V(8); PG8_WAIT_L(0); PG8_BAR; PG8_MMA(0, 0, At, B0); PG8_MMA(0, 1, At, B1); PG8_BAR; PG8_SCHED;
	s_setprio 1
	s_waitcnt lgkmcnt(0)
	v_mfma_f32_16x16x32_bf16 v[62:65], v[74:77], v[154:157], v[62:65]
	v_mfma_f32_16x16x32_bf16 v[58:61], v[98:101], v[154:157], v[58:61]
	v_mfma_f32_16x16x32_bf16 v[46:49], v[74:77], v[170:173], v[46:49]
	v_mfma_f32_16x16x32_bf16 v[42:45], v[98:101], v[170:173], v[42:45]
	v_mfma_f32_16x16x32_bf16 v[30:33], v[74:77], v[178:181], v[30:33]
	v_mfma_f32_16x16x32_bf16 v[26:29], v[98:101], v[178:181], v[26:29]
	v_mfma_f32_16x16x32_bf16 v[14:17], v[74:77], v[186:189], v[14:17]
	v_mfma_f32_16x16x32_bf16 v[10:13], v[98:101], v[186:189], v[10:13]
	v_mfma_f32_16x16x32_bf16 v[62:65], v[86:89], v[166:169], v[62:65]
	v_mfma_f32_16x16x32_bf16 v[58:61], v[106:109], v[166:169], v[58:61]
	v_mfma_f32_16x16x32_bf16 v[46:49], v[86:89], v[174:177], v[46:49]
	v_mfma_f32_16x16x32_bf16 v[42:45], v[106:109], v[174:177], v[42:45]
	v_mfma_f32_16x16x32_bf16 v[30:33], v[86:89], v[182:185], v[30:33]
	v_mfma_f32_16x16x32_bf16 v[26:29], v[106:109], v[182:185], v[26:29]
	v_mfma_f32_16x16x32_bf16 v[14:17], v[86:89], v[200:203], v[14:17]
	v_mfma_f32_16x16x32_bf16 v[10:13], v[106:109], v[200:203], v[10:13]
	s_setprio 0
	s_setprio 1
	v_mfma_f32_16x16x32_bf16 v[54:57], v[122:125], v[154:157], v[54:57]
	v_mfma_f32_16x16x32_bf16 v[50:53], v[142:145], v[154:157], v[50:53]
	v_mfma_f32_16x16x32_bf16 v[38:41], v[122:125], v[170:173], v[38:41]
	v_mfma_f32_16x16x32_bf16 v[34:37], v[142:145], v[170:173], v[34:37]
	v_mfma_f32_16x16x32_bf16 v[22:25], v[122:125], v[178:181], v[22:25]
	v_mfma_f32_16x16x32_bf16 v[18:21], v[142:145], v[178:181], v[18:21]
	v_mfma_f32_16x16x32_bf16 v[6:9], v[122:125], v[186:189], v[6:9]
	v_mfma_f32_16x16x32_bf16 v[2:5], v[142:145], v[186:189], v[2:5]
	v_mfma_f32_16x16x32_bf16 v[54:57], v[126:129], v[166:169], v[54:57]
	v_mfma_f32_16x16x32_bf16 v[50:53], v[150:153], v[166:169], v[50:53]
	v_mfma_f32_16x16x32_bf16 v[38:41], v[126:129], v[174:177], v[38:41]
	v_mfma_f32_16x16x32_bf16 v[34:37], v[150:153], v[174:177], v[34:37]
	v_mfma_f32_16x16x32_bf16 v[22:25], v[126:129], v[182:185], v[22:25]
	v_mfma_f32_16x16x32_bf16 v[18:21], v[150:153], v[182:185], v[18:21]
	s_setprio 2
	s_barrier
	v_mfma_f32_16x16x32_bf16 v[6:9], v[126:129], v[200:203], v[6:9]
	v_mfma_f32_16x16x32_bf16 v[2:5], v[150:153], v[200:203], v[2:5]
	s_setprio 0
	s_add_i32 s6, 0, 0x18000
	s_add_i32 s14, 0, 0x1c000
	v_add_u32_e32 v106, s6, v240
	v_add_u32_e32 v150, s14, v240
	ds_read_b128 v[74:77], v106
	ds_read_b128 v[86:89], v106 offset:1024
	ds_read_b128 v[98:101], v106 offset:2048
	ds_read_b128 v[106:109], v106 offset:3072
	ds_read_b128 v[122:125], v150
	ds_read_b128 v[126:129], v150 offset:1024
	ds_read_b128 v[142:145], v150 offset:2048
	ds_read_b128 v[150:153], v150 offset:3072
	s_add_u32 s12, s38, 0x4000
	s_addc_u32 s13, s39, 0
	s_mov_b32 m0, s62
	ds_read_b128 v[154:157], v241 offset:32768
	ds_read_b128 v[166:169], v241 offset:33792
	ds_read_b128 v[170:173], v241 offset:34816
	ds_read_b128 v[174:177], v241 offset:35840
	ds_read_b128 v[178:181], v241 offset:36864
	ds_read_b128 v[182:185], v241 offset:37888
	ds_read_b128 v[186:189], v241 offset:38912
	ds_read_b128 v[200:203], v241 offset:39936
	global_load_lds_dwordx4 v194, s[12:13]
	s_mov_b32 m0, s63
	s_nop 0
	global_load_lds_dwordx4 v192, s[12:13]
	s_waitcnt vmcnt(8)
	s_waitcnt lgkmcnt(0)
	s_barrier
	s_setprio 1
	s_waitcnt lgkmcnt(0)
	v_mfma_f32_16x16x32_bf16 v[162:165], v[74:77], v[154:157], v[162:165]
	v_mfma_f32_16x16x32_bf16 v[158:161], v[98:101], v[154:157], v[158:161]
	v_mfma_f32_16x16x32_bf16 v[134:137], v[74:77], v[170:173], v[134:137]
	v_mfma_f32_16x16x32_bf16 v[130:133], v[98:101], v[170:173], v[130:133]
	v_mfma_f32_16x16x32_bf16 v[110:113], v[74:77], v[178:181], v[110:113]
	v_mfma_f32_16x16x32_bf16 v[102:105], v[98:101], v[178:181], v[102:105]
	v_mfma_f32_16x16x32_bf16 v[82:85], v[74:77], v[186:189], v[82:85]
	v_mfma_f32_16x16x32_bf16 v[78:81], v[98:101], v[186:189], v[78:81]
	v_mfma_f32_16x16x32_bf16 v[162:165], v[86:89], v[166:169], v[162:165]
	v_mfma_f32_16x16x32_bf16 v[158:161], v[106:109], v[166:169], v[158:161]
	v_mfma_f32_16x16x32_bf16 v[134:137], v[86:89], v[174:177], v[134:137]
	v_mfma_f32_16x16x32_bf16 v[130:133], v[106:109], v[174:177], v[130:133]
	v_mfma_f32_16x16x32_bf16 v[110:113], v[86:89], v[182:185], v[110:113]
	v_mfma_f32_16x16x32_bf16 v[102:105], v[106:109], v[182:185], v[102:105]
	v_mfma_f32_16x16x32_bf16 v[82:85], v[86:89], v[200:203], v[82:85]
	v_mfma_f32_16x16x32_bf16 v[78:81], v[106:109], v[200:203], v[78:81]
	s_setprio 0
	s_setprio 1
	v_mfma_f32_16x16x32_bf16 v[146:149], v[122:125], v[154:157], v[146:149]
	v_mfma_f32_16x16x32_bf16 v[138:141], v[142:145], v[154:157], v[138:141]
	v_mfma_f32_16x16x32_bf16 v[118:121], v[122:125], v[170:173], v[118:121]
	v_mfma_f32_16x16x32_bf16 v[114:117], v[142:145], v[170:173], v[114:117]
	v_mfma_f32_16x16x32_bf16 v[94:97], v[122:125], v[178:181], v[94:97]
	v_mfma_f32_16x16x32_bf16 v[90:93], v[142:145], v[178:181], v[90:93]
	v_mfma_f32_16x16x32_bf16 v[70:73], v[122:125], v[186:189], v[70:73]
	v_mfma_f32_16x16x32_bf16 v[66:69], v[142:145], v[186:189], v[66:69]
	v_mfma_f32_16x16x32_bf16 v[146:149], v[126:129], v[166:169], v[146:149]
	v_mfma_f32_16x16x32_bf16 v[138:141], v[150:153], v[166:169], v[138:141]
	v_mfma_f32_16x16x32_bf16 v[118:121], v[126:129], v[174:177], v[118:121]
	v_mfma_f32_16x16x32_bf16 v[114:117], v[150:153], v[174:177], v[114:117]
	v_mfma_f32_16x16x32_bf16 v[94:97], v[126:129], v[182:185], v[94:97]
	v_mfma_f32_16x16x32_bf16 v[90:93], v[150:153], v[182:185], v[90:93]
	s_setprio 2
	s_barrier
; #define PG8_STAGE(bufoff, gbase, voff) do { _Pragma("unroll") for (int _i = 0; _i < 2; ++_i) \
;         __builtin_amdgcn_global_load_lds((const unsigned*)((const char*)(gbase) + (voff)[_i]), (LAS unsigned*)(lds + (bufoff) + ldsw + _i * 8192), 16, 0, 0); } while (0)
; #define PG8_LDA(dst, b, h) do { _Pragma("unroll") for (int m = 0; m < 4; ++m) _Pragma("unroll") for (int k = 0; k < 2; ++k) dst[m][k] = *(const LAS bf16x8*)(lds + PG8_SA(b, h) + aoff + m * 2048 + k * 1024); } while (0)
; #define PG8_MMA(ai, bj, At, Bt) do { __builtin_amdgcn_s_setprio(1); _Pragma("unroll") for (int m = 0; m < 4; ++m) _Pragma("unroll") for (int n = 0; n < 2; ++n) _Pragma("unroll") for (int k = 0; k < 2; ++k) \
;         acc[ai][bj][m][n] = __builtin_amdgcn_mfma_f32_16x16x32_bf16(Bt[n][k], At[m][k], acc[ai][bj][m][n], 0, 0, 0); __builtin_amdgcn_s_setprio(0); } while (0)
; #define PG8_WAIT_V(n) asm volatile("s_waitcnt vmcnt(" #n ")" ::: "memory")
; #define PG8_WAIT_L(n) asm volatile("s_waitcnt lgkmcnt(" #n ")" ::: "memory")
; #define PG8_BAR __builtin_amdgcn_s_barrier()
; #define PG8_SCHED __builtin_amdgcn_sched_barrier(0)
; template <class Epi>
; __device__ __forceinline__ void gemm_phase(LAS unsigned char* lds, const Gemm g, const TileOrder& S, const Epi& E) {
;     ...
;             PG8_WAIT_V(8); PG8_WAIT_L(0); PG8_BAR; PG8_MMA(0, 0, At, B0); PG8_MMA(0, 1, At, B1); PG8_BAR; PG8_SCHED;
;             PG8_LDA(At, 1, 1); PG8_STAGE(PG8_SB(1, 0), b3, voffB); PG8_STAGE(PG8_SB(1, 1), b3 + hstepB, voffB); PG8_STAGE(PG8_SA(1, 0), a3, voffA);
;             PG8_WAIT_V(8); PG8_WAIT_L(0); PG8_BAR; PG8_MMA(1, 0, At, B0); PG8_MMA(1, 1, At, B1); PG8_BAR; PG8_SCHED;
;         }
;         if (wr == 0) PG8_BAR;
	v_mfma_f32_16x16x32_bf16 v[70:73], v[126:129], v[200:203], v[70:73]
	v_mfma_f32_16x16x32_bf16 v[66:69], v[150:153], v[200:203], v[66:69]
	s_setprio 0
	s_add_i32 s6, s6, s59
	v_lshl_add_u64 v[204:205], v[204:205], 0, s[34:35]
	s_mov_b32 m0, s6
	ds_read_b128 v[154:157], v241 offset:49152
	ds_read_b128 v[166:169], v241 offset:50176
	ds_read_b128 v[170:173], v241 offset:51200
	ds_read_b128 v[174:177], v241 offset:52224
	ds_read_b128 v[178:181], v241 offset:53248
	ds_read_b128 v[182:185], v241 offset:54272
	ds_read_b128 v[186:189], v241 offset:55296
	ds_read_b128 v[200:203], v241 offset:56320
	global_load_lds_dwordx4 v[204:205], off
	s_add_i32 m0, s6, 0x2000
	s_add_u32 s12, s30, 0x200080
	v_lshl_add_u64 v[204:205], v[206:207], 0, s[34:35]
	s_addc_u32 s13, s31, 0
	s_add_i32 s6, s14, s59
	global_load_lds_dwordx4 v[204:205], off
	s_mov_b32 m0, s6
	s_nop 0
	global_load_lds_dwordx4 v0, s[12:13]
	s_add_i32 m0, s6, 0x2000
	s_nop 0
	global_load_lds_dwordx4 v190, s[12:13]
	s_mov_b32 m0, s69
	s_nop 0
	global_load_lds_dwordx4 v194, s[2:3]
	s_mov_b32 m0, s70
	s_nop 0
	global_load_lds_dwordx4 v192, s[2:3]
	s_waitcnt vmcnt(8)
	s_waitcnt lgkmcnt(0)
	s_barrier
	s_setprio 1
	s_waitcnt lgkmcnt(0)
	v_mfma_f32_16x16x32_bf16 v[62:65], v[74:77], v[154:157], v[62:65]
	v_mfma_f32_16x16x32_bf16 v[58:61], v[98:101], v[154:157], v[58:61]
	v_mfma_f32_16x16x32_bf16 v[46:49], v[74:77], v[170:173], v[46:49]
	v_mfma_f32_16x16x32_bf16 v[42:45], v[98:101], v[170:173], v[42:45]
	v_mfma_f32_16x16x32_bf16 v[30:33], v[74:77], v[178:181], v[30:33]
	v_mfma_f32_16x16x32_bf16 v[26:29], v[98:101], v[178:181], v[26:29]
	v_mfma_f32_16x16x32_bf16 v[14:17], v[74:77], v[186:189], v[14:17]
	v_mfma_f32_16x16x32_bf16 v[10:13], v[98:101], v[186:189], v[10:13]
	v_mfma_f32_16x16x32_bf16 v[62:65], v[86:89], v[166:169], v[62:65]
	v_mfma_f32_16x16x32_bf16 v[58:61], v[106:109], v[166:169], v[58:61]
	v_mfma_f32_16x16x32_bf16 v[46:49], v[86:89], v[174:177], v[46:49]
	v_mfma_f32_16x16x32_bf16 v[42:45], v[106:109], v[174:177], v[42:45]
	v_mfma_f32_16x16x32_bf16 v[30:33], v[86:89], v[182:185], v[30:33]
	v_mfma_f32_16x16x32_bf16 v[26:29], v[106:109], v[182:185], v[26:29]
	v_mfma_f32_16x16x32_bf16 v[14:17], v[86:89], v[200:203], v[14:17]
	v_mfma_f32_16x16x32_bf16 v[10:13], v[106:109], v[200:203], v[10:13]
	s_setprio 0
	s_setprio 1
	v_mfma_f32_16x16x32_bf16 v[54:57], v[122:125], v[154:157], v[54:57]
	v_mfma_f32_16x16x32_bf16 v[50:53], v[142:145], v[154:157], v[50:53]
	v_mfma_f32_16x16x32_bf16 v[38:41], v[122:125], v[170:173], v[38:41]
	v_mfma_f32_16x16x32_bf16 v[34:37], v[142:145], v[170:173], v[34:37]
	v_mfma_f32_16x16x32_bf16 v[22:25], v[122:125], v[178:181], v[22:25]
	v_mfma_f32_16x16x32_bf16 v[18:21], v[142:145], v[178:181], v[18:21]
	v_mfma_f32_16x16x32_bf16 v[6:9], v[122:125], v[186:189], v[6:9]
	v_mfma_f32_16x16x32_bf16 v[2:5], v[142:145], v[186:189], v[2:5]
	v_mfma_f32_16x16x32_bf16 v[54:57], v[126:129], v[166:169], v[54:57]
	v_mfma_f32_16x16x32_bf16 v[50:53], v[150:153], v[166:169], v[50:53]
	v_mfma_f32_16x16x32_bf16 v[38:41], v[126:129], v[174:177], v[38:41]
	v_mfma_f32_16x16x32_bf16 v[34:37], v[150:153], v[174:177], v[34:37]
	v_mfma_f32_16x16x32_bf16 v[22:25], v[126:129], v[182:185], v[22:25]
	v_mfma_f32_16x16x32_bf16 v[18:21], v[150:153], v[182:185], v[18:21]
	s_setprio 2
	s_barrier
	v_mfma_f32_16x16x32_bf16 v[6:9], v[126:129], v[200:203], v[6:9]
	v_mfma_f32_16x16x32_bf16 v[2:5], v[150:153], v[200:203], v[2:5]
	s_setprio 0
	s_add_i32 s72, s72, 2
	s_add_u32 s53, s53, 0x100
	s_addc_u32 s71, s71, 0
	s_add_u32 s28, s28, 0x10000
	s_addc_u32 s29, s29, 0
	s_cmpk_gt_u32 s72, 0x7d
	s_cbranch_scc0 .LBB0_835
	s_and_b64 vcc, exec, s[46:47]
	s_cbranch_vccz .LBB0_838
	s_barrier
